# group barriers drop the L1 invalidate: loads of data produced inside the group (GEMM A operand, row-op XB/F, prep Z rows) bypass L1 with sc1
# speedup vs baseline: 1.0556x; 1.0091x over previous
.Lxb20_done:
	global_load_dword v4, v1, s[24:25] sc1
	s_waitcnt vmcnt(0)
	v_readfirstlane_b32 s21, v4
	s_bcnt1_i32_b32 s21, s21
	s_cmp_eq_u32 s21, 1
	s_cselect_b32 s21, 1, 0
	s_cmp_eq_u32 s46, 0x200
	s_cselect_b32 s21, s21, 0
	s_nop 0
	v_writelane_b32 v162, s21, 62
	v_mov_b32_e32 v4, s21
	ds_write_b32 v1, v4 offset:53260
.LBB0_128:
	s_or_b64 exec, exec, s[0:1]
	s_waitcnt vmcnt(0) lgkmcnt(0)
	s_barrier
	v_mov_b32_e32 v0, 0
	ds_read_b32 v0, v0 offset:53260
	s_waitcnt lgkmcnt(0)
	v_readfirstlane_b32 s0, v0
	s_nop 3
	v_writelane_b32 v162, s0, 62

.LBB0_135:
	s_or_b64 exec, exec, s[0:1]
	s_cmp_lt_u32 s45, 3
	s_cbranch_scc1 .LBB0_185
	s_waitcnt vmcnt(0)
	s_barrier
	v_readlane_b32 s21, v162, 62
	s_nop 1
	s_cmp_eq_u32 s21, 1
	s_cbranch_scc1 .Lxb21_noinv
	v_lshrrev_b32_e32 v0, 6, v128
	v_readfirstlane_b32 s20, v0
	s_cmp_lg_u32 s20, 1
	s_cbranch_scc1 .Lxb21_ninv
	buffer_inv sc1

.Lxb21_noinv:
	s_mov_b64 s[0:1], exec
	v_readlane_b32 s2, v163, 17
	v_readlane_b32 s3, v163, 18
	s_and_b64 s[2:3], s[0:1], s[2:3]
	s_mov_b64 exec, s[2:3]
	s_cbranch_execz .LBB0_184
	v_mov_b32_e32 v16, 0
	s_waitcnt vmcnt(0) expcnt(0) lgkmcnt(0)
	ds_read_b32 v2, v16 offset:53248
	ds_read_b32 v0, v16 offset:53252
	s_waitcnt lgkmcnt(1)
	v_cmp_ne_u32_e32 vcc, 0, v2
	s_cbranch_vccnz .LBB0_152
	s_add_u32 s2, s84, 0x1000
	s_addc_u32 s3, s85, 0
	s_add_u32 s20, s84, 0x1100
	s_addc_u32 s21, s85, 0
	s_add_u32 s22, s84, 0x1200
	s_addc_u32 s23, s85, 0
	s_mov_b32 s4, s34
	s_mul_i32 s34, s47, s33
	s_add_u32 s24, s84, 0x1300
	s_mul_i32 s34, s34, s46
	s_addc_u32 s25, s85, 0
	s_mov_b32 s35, 1
	s_branch .LBB0_140

.Lggu0_noprio:
	s_and_b32 s4, s10, 7
	s_lshl_b32 s4, s4, 3
	s_bfe_u32 s32, s10, 0x30003
	s_or_b32 s4, s4, s32
	s_mul_i32 s4, s4, 0x50000
	s_add_u32 s2, s16, s4
	s_addc_u32 s3, s17, 0
	s_lshr_b32 s4, s10, 6
	s_mul_i32 s4, s4, 0x40000
	s_add_u32 s6, s18, s4
	s_addc_u32 s7, s19, 0
	s_add_u32 m0, s13, 0x0
	s_nop 0
	global_load_lds_dwordx4 v161, s[2:3] sc1
	s_add_u32 m0, s13, 0x1000
	v_add_u32_e32 v166, 0x10000, v161
	global_load_lds_dwordx4 v166, s[2:3] sc1
	s_add_u32 m0, s13, 0x2000
	v_add_u32_e32 v166, 0x20000, v161
	global_load_lds_dwordx4 v166, s[2:3] sc1
	s_add_u32 m0, s13, 0x3000
	v_add_u32_e32 v166, 0x30000, v161
	global_load_lds_dwordx4 v166, s[2:3] sc1
	s_add_u32 m0, s13, 0x4000
	v_add_u32_e32 v166, 0x40000, v161
	global_load_lds_dwordx4 v166, s[2:3] sc1
	s_add_u32 m0, s13, 0x5000
	s_nop 0
	global_load_lds_dwordx4 v165, s[6:7]
	s_add_u32 m0, s13, 0x6000
	v_add_u32_e32 v166, 0x2000, v165
	global_load_lds_dwordx4 v166, s[6:7]
	s_add_u32 m0, s13, 0x7000
	v_add_u32_e32 v166, 0x10000, v165
	global_load_lds_dwordx4 v166, s[6:7]
	s_add_u32 m0, s13, 0x8000
	v_add_u32_e32 v166, 0x12000, v165
	global_load_lds_dwordx4 v166, s[6:7]
	s_add_u32 s24, s6, 0x20000
	s_addc_u32 s25, s7, 0
	s_add_u32 s2, s2, 0x80
	s_addc_u32 s3, s3, 0
	s_add_u32 s6, s6, 0x80
	s_addc_u32 s7, s7, 0
	s_mov_b32 s48, 0

.Lggu0_wd:
	s_barrier
	ds_read_b128 v[184:187], v116 offset:0
	ds_read_b128 v[204:207], v119 offset:20480
	ds_read_b128 v[208:211], v119 offset:22528
	ds_read_b128 v[212:215], v119 offset:24576
	ds_read_b128 v[216:219], v119 offset:26624
	ds_read_b128 v[188:191], v116 offset:2048
	ds_read_b128 v[192:195], v116 offset:4096
	ds_read_b128 v[196:199], v116 offset:6144
	ds_read_b128 v[200:203], v116 offset:8192
	s_waitcnt lgkmcnt(7)
	v_mfma_f32_16x16x32_bf16 v[0:3], v[204:207], v[184:187], v[0:3]
	s_add_u32 m0, s13, 0x9000
	s_nop 0
	global_load_lds_dwordx4 v165, s[24:25]
	s_waitcnt lgkmcnt(6)
	v_mfma_f32_16x16x32_bf16 v[4:7], v[208:211], v[184:187], v[4:7]
	s_add_u32 m0, s13, 0xa000
	v_add_u32_e32 v166, 0x2000, v165
	global_load_lds_dwordx4 v166, s[24:25]
	s_waitcnt lgkmcnt(5)
	v_mfma_f32_16x16x32_bf16 v[8:11], v[212:215], v[184:187], v[8:11]
	s_add_u32 m0, s13, 0xb000
	v_add_u32_e32 v166, 0x10000, v165
	global_load_lds_dwordx4 v166, s[24:25]
	s_waitcnt lgkmcnt(4)
	v_mfma_f32_16x16x32_bf16 v[12:15], v[216:219], v[184:187], v[12:15]
	s_add_u32 m0, s13, 0xc000
	v_add_u32_e32 v166, 0x12000, v165
	global_load_lds_dwordx4 v166, s[24:25]
	ds_read_b128 v[220:223], v118 offset:0
	ds_read_b128 v[240:243], v160 offset:20480
	ds_read_b128 v[244:247], v160 offset:22528
	ds_read_b128 v[248:251], v160 offset:24576
	ds_read_b128 v[252:255], v160 offset:26624
	s_waitcnt lgkmcnt(8)
	v_mfma_f32_16x16x32_bf16 v[16:19], v[204:207], v[188:191], v[16:19]
	v_mfma_f32_16x16x32_bf16 v[20:23], v[208:211], v[188:191], v[20:23]
	v_mfma_f32_16x16x32_bf16 v[24:27], v[212:215], v[188:191], v[24:27]
	v_mfma_f32_16x16x32_bf16 v[28:31], v[216:219], v[188:191], v[28:31]
	ds_read_b128 v[224:227], v118 offset:2048
	ds_read_b128 v[228:231], v118 offset:4096
	ds_read_b128 v[232:235], v118 offset:6144
	ds_read_b128 v[236:239], v118 offset:8192
	s_waitcnt lgkmcnt(11)
	v_mfma_f32_16x16x32_bf16 v[32:35], v[204:207], v[192:195], v[32:35]
	v_mfma_f32_16x16x32_bf16 v[36:39], v[208:211], v[192:195], v[36:39]
	v_mfma_f32_16x16x32_bf16 v[40:43], v[212:215], v[192:195], v[40:43]
	v_mfma_f32_16x16x32_bf16 v[44:47], v[216:219], v[192:195], v[44:47]
	s_waitcnt lgkmcnt(10)
	v_mfma_f32_16x16x32_bf16 v[48:51], v[204:207], v[196:199], v[48:51]
	v_mfma_f32_16x16x32_bf16 v[52:55], v[208:211], v[196:199], v[52:55]
	v_mfma_f32_16x16x32_bf16 v[56:59], v[212:215], v[196:199], v[56:59]
	v_mfma_f32_16x16x32_bf16 v[60:63], v[216:219], v[196:199], v[60:63]
	s_waitcnt lgkmcnt(9)
	v_mfma_f32_16x16x32_bf16 v[64:67], v[204:207], v[200:203], v[64:67]
	v_mfma_f32_16x16x32_bf16 v[68:71], v[208:211], v[200:203], v[68:71]
	v_mfma_f32_16x16x32_bf16 v[72:75], v[212:215], v[200:203], v[72:75]
	v_mfma_f32_16x16x32_bf16 v[76:79], v[216:219], v[200:203], v[76:79]
	s_waitcnt lgkmcnt(7)
	v_mfma_f32_16x16x32_bf16 v[0:3], v[240:243], v[220:223], v[0:3]
	s_waitcnt lgkmcnt(6)
	v_mfma_f32_16x16x32_bf16 v[4:7], v[244:247], v[220:223], v[4:7]
	s_waitcnt lgkmcnt(5)
	v_mfma_f32_16x16x32_bf16 v[8:11], v[248:251], v[220:223], v[8:11]
	s_waitcnt lgkmcnt(4)
	v_mfma_f32_16x16x32_bf16 v[12:15], v[252:255], v[220:223], v[12:15]
	s_waitcnt lgkmcnt(3)
	v_mfma_f32_16x16x32_bf16 v[16:19], v[240:243], v[224:227], v[16:19]
	v_mfma_f32_16x16x32_bf16 v[20:23], v[244:247], v[224:227], v[20:23]
	v_mfma_f32_16x16x32_bf16 v[24:27], v[248:251], v[224:227], v[24:27]
	v_mfma_f32_16x16x32_bf16 v[28:31], v[252:255], v[224:227], v[28:31]
	s_waitcnt lgkmcnt(2)
	v_mfma_f32_16x16x32_bf16 v[32:35], v[240:243], v[228:231], v[32:35]
	v_mfma_f32_16x16x32_bf16 v[36:39], v[244:247], v[228:231], v[36:39]
	v_mfma_f32_16x16x32_bf16 v[40:43], v[248:251], v[228:231], v[40:43]
	v_mfma_f32_16x16x32_bf16 v[44:47], v[252:255], v[228:231], v[44:47]
	s_waitcnt lgkmcnt(1)
	v_mfma_f32_16x16x32_bf16 v[48:51], v[240:243], v[232:235], v[48:51]
	v_mfma_f32_16x16x32_bf16 v[52:55], v[244:247], v[232:235], v[52:55]
	v_mfma_f32_16x16x32_bf16 v[56:59], v[248:251], v[232:235], v[56:59]
	v_mfma_f32_16x16x32_bf16 v[60:63], v[252:255], v[232:235], v[60:63]
	s_add_u32 s24, s24, 0x80
	s_addc_u32 s25, s25, 0
	s_waitcnt lgkmcnt(0)
	v_mfma_f32_16x16x32_bf16 v[64:67], v[240:243], v[236:239], v[64:67]
	v_mfma_f32_16x16x32_bf16 v[68:71], v[244:247], v[236:239], v[68:71]
	v_mfma_f32_16x16x32_bf16 v[72:75], v[248:251], v[236:239], v[72:75]
	v_mfma_f32_16x16x32_bf16 v[76:79], v[252:255], v[236:239], v[76:79]
	s_waitcnt vmcnt(0)
	s_barrier
	ds_read_b128 v[184:187], v116 offset:0
	ds_read_b128 v[204:207], v119 offset:36864
	ds_read_b128 v[208:211], v119 offset:38912
	ds_read_b128 v[212:215], v119 offset:40960
	ds_read_b128 v[216:219], v119 offset:43008
	ds_read_b128 v[188:191], v116 offset:2048
	ds_read_b128 v[192:195], v116 offset:4096
	ds_read_b128 v[196:199], v116 offset:6144
	ds_read_b128 v[200:203], v116 offset:8192
	s_waitcnt lgkmcnt(7)
	v_mfma_f32_16x16x32_bf16 v[80:83], v[204:207], v[184:187], v[80:83]
	s_add_u32 m0, s13, 0xd100
	s_nop 0
	global_load_lds_dwordx4 v161, s[2:3] sc1
	s_waitcnt lgkmcnt(6)
	v_mfma_f32_16x16x32_bf16 v[84:87], v[208:211], v[184:187], v[84:87]
	s_add_u32 m0, s13, 0xe100
	v_add_u32_e32 v166, 0x10000, v161
	global_load_lds_dwordx4 v166, s[2:3] sc1
	s_waitcnt lgkmcnt(5)
	v_mfma_f32_16x16x32_bf16 v[88:91], v[212:215], v[184:187], v[88:91]
	s_add_u32 m0, s13, 0xf100
	v_add_u32_e32 v166, 0x20000, v161
	global_load_lds_dwordx4 v166, s[2:3] sc1
	s_waitcnt lgkmcnt(4)
	v_mfma_f32_16x16x32_bf16 v[92:95], v[216:219], v[184:187], v[92:95]
	s_add_u32 m0, s13, 0x10100
	v_add_u32_e32 v166, 0x30000, v161
	global_load_lds_dwordx4 v166, s[2:3] sc1
	ds_read_b128 v[220:223], v118 offset:0
	ds_read_b128 v[240:243], v160 offset:36864
	ds_read_b128 v[244:247], v160 offset:38912
	ds_read_b128 v[248:251], v160 offset:40960
	ds_read_b128 v[252:255], v160 offset:43008
	s_waitcnt lgkmcnt(8)
	v_mfma_f32_16x16x32_bf16 v[96:99], v[204:207], v[188:191], v[96:99]
	s_add_u32 m0, s13, 0x11100
	v_add_u32_e32 v166, 0x40000, v161
	global_load_lds_dwordx4 v166, s[2:3] sc1
	v_mfma_f32_16x16x32_bf16 v[100:103], v[208:211], v[188:191], v[100:103]
	s_add_u32 m0, s13, 0x5000
	s_nop 0
	global_load_lds_dwordx4 v165, s[6:7]
	v_mfma_f32_16x16x32_bf16 v[104:107], v[212:215], v[188:191], v[104:107]
	s_add_u32 m0, s13, 0x6000
	v_add_u32_e32 v166, 0x2000, v165
	global_load_lds_dwordx4 v166, s[6:7]
	v_mfma_f32_16x16x32_bf16 v[108:111], v[216:219], v[188:191], v[108:111]
	s_add_u32 m0, s13, 0x7000
	v_add_u32_e32 v166, 0x10000, v165
	global_load_lds_dwordx4 v166, s[6:7]
	ds_read_b128 v[224:227], v118 offset:2048
	ds_read_b128 v[228:231], v118 offset:4096
	ds_read_b128 v[232:235], v118 offset:6144
	ds_read_b128 v[236:239], v118 offset:8192
	s_waitcnt lgkmcnt(11)
	v_mfma_f32_16x16x32_bf16 v[112:115], v[204:207], v[192:195], v[112:115]
	s_add_u32 m0, s13, 0x8000
	v_add_u32_e32 v166, 0x12000, v165
	global_load_lds_dwordx4 v166, s[6:7]
	v_mfma_f32_16x16x32_bf16 v[120:123], v[208:211], v[192:195], v[120:123]
	v_mfma_f32_16x16x32_bf16 v[124:127], v[212:215], v[192:195], v[124:127]
	v_mfma_f32_16x16x32_bf16 v[140:143], v[216:219], v[192:195], v[140:143]
	s_waitcnt lgkmcnt(10)
	v_mfma_f32_16x16x32_bf16 v[144:147], v[204:207], v[196:199], v[144:147]
	v_mfma_f32_16x16x32_bf16 v[148:151], v[208:211], v[196:199], v[148:151]
	v_mfma_f32_16x16x32_bf16 v[152:155], v[212:215], v[196:199], v[152:155]
	v_mfma_f32_16x16x32_bf16 v[156:159], v[216:219], v[196:199], v[156:159]
	s_waitcnt lgkmcnt(9)
	v_mfma_f32_16x16x32_bf16 v[168:171], v[204:207], v[200:203], v[168:171]
	v_mfma_f32_16x16x32_bf16 v[172:175], v[208:211], v[200:203], v[172:175]
	v_mfma_f32_16x16x32_bf16 v[176:179], v[212:215], v[200:203], v[176:179]
	v_mfma_f32_16x16x32_bf16 v[180:183], v[216:219], v[200:203], v[180:183]
	s_waitcnt lgkmcnt(7)
	v_mfma_f32_16x16x32_bf16 v[80:83], v[240:243], v[220:223], v[80:83]
	s_waitcnt lgkmcnt(6)
	v_mfma_f32_16x16x32_bf16 v[84:87], v[244:247], v[220:223], v[84:87]
	s_waitcnt lgkmcnt(5)
	v_mfma_f32_16x16x32_bf16 v[88:91], v[248:251], v[220:223], v[88:91]
	s_waitcnt lgkmcnt(4)
	v_mfma_f32_16x16x32_bf16 v[92:95], v[252:255], v[220:223], v[92:95]
	s_waitcnt lgkmcnt(3)
	v_mfma_f32_16x16x32_bf16 v[96:99], v[240:243], v[224:227], v[96:99]
	v_mfma_f32_16x16x32_bf16 v[100:103], v[244:247], v[224:227], v[100:103]
	v_mfma_f32_16x16x32_bf16 v[104:107], v[248:251], v[224:227], v[104:107]
	v_mfma_f32_16x16x32_bf16 v[108:111], v[252:255], v[224:227], v[108:111]
	s_waitcnt lgkmcnt(2)
	v_mfma_f32_16x16x32_bf16 v[112:115], v[240:243], v[228:231], v[112:115]
	v_mfma_f32_16x16x32_bf16 v[120:123], v[244:247], v[228:231], v[120:123]
	v_mfma_f32_16x16x32_bf16 v[124:127], v[248:251], v[228:231], v[124:127]
	v_mfma_f32_16x16x32_bf16 v[140:143], v[252:255], v[228:231], v[140:143]
	s_waitcnt lgkmcnt(1)
	v_mfma_f32_16x16x32_bf16 v[144:147], v[240:243], v[232:235], v[144:147]
	v_mfma_f32_16x16x32_bf16 v[148:151], v[244:247], v[232:235], v[148:151]
	v_mfma_f32_16x16x32_bf16 v[152:155], v[248:251], v[232:235], v[152:155]
	v_mfma_f32_16x16x32_bf16 v[156:159], v[252:255], v[232:235], v[156:159]
	s_add_u32 s2, s2, 0x80
	s_addc_u32 s3, s3, 0
	s_add_u32 s6, s6, 0x80
	s_addc_u32 s7, s7, 0
	s_waitcnt lgkmcnt(0)
	v_mfma_f32_16x16x32_bf16 v[168:171], v[240:243], v[236:239], v[168:171]
	v_mfma_f32_16x16x32_bf16 v[172:175], v[244:247], v[236:239], v[172:175]
	v_mfma_f32_16x16x32_bf16 v[176:179], v[248:251], v[236:239], v[176:179]
	v_mfma_f32_16x16x32_bf16 v[180:183], v[252:255], v[236:239], v[180:183]
	s_waitcnt vmcnt(0)
	s_barrier
	ds_read_b128 v[184:187], v116 offset:53504
	ds_read_b128 v[204:207], v119 offset:20480
	ds_read_b128 v[208:211], v119 offset:22528
	ds_read_b128 v[212:215], v119 offset:24576
	ds_read_b128 v[216:219], v119 offset:26624
	ds_read_b128 v[188:191], v116 offset:55552
	ds_read_b128 v[192:195], v116 offset:57600
	ds_read_b128 v[196:199], v116 offset:59648
	ds_read_b128 v[200:203], v116 offset:61696
	s_waitcnt lgkmcnt(7)
	v_mfma_f32_16x16x32_bf16 v[0:3], v[204:207], v[184:187], v[0:3]
	s_add_u32 m0, s13, 0x9000
	s_nop 0
	global_load_lds_dwordx4 v165, s[24:25]
	s_waitcnt lgkmcnt(6)
	v_mfma_f32_16x16x32_bf16 v[4:7], v[208:211], v[184:187], v[4:7]
	s_add_u32 m0, s13, 0xa000
	v_add_u32_e32 v166, 0x2000, v165
	global_load_lds_dwordx4 v166, s[24:25]
	s_waitcnt lgkmcnt(5)
	v_mfma_f32_16x16x32_bf16 v[8:11], v[212:215], v[184:187], v[8:11]
	s_add_u32 m0, s13, 0xb000
	v_add_u32_e32 v166, 0x10000, v165
	global_load_lds_dwordx4 v166, s[24:25]
	s_waitcnt lgkmcnt(4)
	v_mfma_f32_16x16x32_bf16 v[12:15], v[216:219], v[184:187], v[12:15]
	s_add_u32 m0, s13, 0xc000
	v_add_u32_e32 v166, 0x12000, v165
	global_load_lds_dwordx4 v166, s[24:25]
	ds_read_b128 v[220:223], v118 offset:53504
	ds_read_b128 v[240:243], v160 offset:20480
	ds_read_b128 v[244:247], v160 offset:22528
	ds_read_b128 v[248:251], v160 offset:24576
	ds_read_b128 v[252:255], v160 offset:26624
	s_waitcnt lgkmcnt(8)
	v_mfma_f32_16x16x32_bf16 v[16:19], v[204:207], v[188:191], v[16:19]
	v_mfma_f32_16x16x32_bf16 v[20:23], v[208:211], v[188:191], v[20:23]
	v_mfma_f32_16x16x32_bf16 v[24:27], v[212:215], v[188:191], v[24:27]
	v_mfma_f32_16x16x32_bf16 v[28:31], v[216:219], v[188:191], v[28:31]
	ds_read_b128 v[224:227], v118 offset:55552
	ds_read_b128 v[228:231], v118 offset:57600
	ds_read_b128 v[232:235], v118 offset:59648
	ds_read_b128 v[236:239], v118 offset:61696
	s_waitcnt lgkmcnt(11)
	v_mfma_f32_16x16x32_bf16 v[32:35], v[204:207], v[192:195], v[32:35]
	v_mfma_f32_16x16x32_bf16 v[36:39], v[208:211], v[192:195], v[36:39]
	v_mfma_f32_16x16x32_bf16 v[40:43], v[212:215], v[192:195], v[40:43]
	v_mfma_f32_16x16x32_bf16 v[44:47], v[216:219], v[192:195], v[44:47]
	s_waitcnt lgkmcnt(10)
	v_mfma_f32_16x16x32_bf16 v[48:51], v[204:207], v[196:199], v[48:51]
	v_mfma_f32_16x16x32_bf16 v[52:55], v[208:211], v[196:199], v[52:55]
	v_mfma_f32_16x16x32_bf16 v[56:59], v[212:215], v[196:199], v[56:59]
	v_mfma_f32_16x16x32_bf16 v[60:63], v[216:219], v[196:199], v[60:63]
	s_waitcnt lgkmcnt(9)
	v_mfma_f32_16x16x32_bf16 v[64:67], v[204:207], v[200:203], v[64:67]
	v_mfma_f32_16x16x32_bf16 v[68:71], v[208:211], v[200:203], v[68:71]
	v_mfma_f32_16x16x32_bf16 v[72:75], v[212:215], v[200:203], v[72:75]
	v_mfma_f32_16x16x32_bf16 v[76:79], v[216:219], v[200:203], v[76:79]
	s_waitcnt lgkmcnt(7)
	v_mfma_f32_16x16x32_bf16 v[0:3], v[240:243], v[220:223], v[0:3]
	s_waitcnt lgkmcnt(6)
	v_mfma_f32_16x16x32_bf16 v[4:7], v[244:247], v[220:223], v[4:7]
	s_waitcnt lgkmcnt(5)
	v_mfma_f32_16x16x32_bf16 v[8:11], v[248:251], v[220:223], v[8:11]
	s_waitcnt lgkmcnt(4)
	v_mfma_f32_16x16x32_bf16 v[12:15], v[252:255], v[220:223], v[12:15]
	s_waitcnt lgkmcnt(3)
	v_mfma_f32_16x16x32_bf16 v[16:19], v[240:243], v[224:227], v[16:19]
	v_mfma_f32_16x16x32_bf16 v[20:23], v[244:247], v[224:227], v[20:23]
	v_mfma_f32_16x16x32_bf16 v[24:27], v[248:251], v[224:227], v[24:27]
	v_mfma_f32_16x16x32_bf16 v[28:31], v[252:255], v[224:227], v[28:31]
	s_waitcnt lgkmcnt(2)
	v_mfma_f32_16x16x32_bf16 v[32:35], v[240:243], v[228:231], v[32:35]
	v_mfma_f32_16x16x32_bf16 v[36:39], v[244:247], v[228:231], v[36:39]
	v_mfma_f32_16x16x32_bf16 v[40:43], v[248:251], v[228:231], v[40:43]
	v_mfma_f32_16x16x32_bf16 v[44:47], v[252:255], v[228:231], v[44:47]
	s_waitcnt lgkmcnt(1)
	v_mfma_f32_16x16x32_bf16 v[48:51], v[240:243], v[232:235], v[48:51]
	v_mfma_f32_16x16x32_bf16 v[52:55], v[244:247], v[232:235], v[52:55]
	v_mfma_f32_16x16x32_bf16 v[56:59], v[248:251], v[232:235], v[56:59]
	v_mfma_f32_16x16x32_bf16 v[60:63], v[252:255], v[232:235], v[60:63]
	s_add_u32 s24, s24, 0x80
	s_addc_u32 s25, s25, 0
	s_waitcnt lgkmcnt(0)
	v_mfma_f32_16x16x32_bf16 v[64:67], v[240:243], v[236:239], v[64:67]
	v_mfma_f32_16x16x32_bf16 v[68:71], v[244:247], v[236:239], v[68:71]
	v_mfma_f32_16x16x32_bf16 v[72:75], v[248:251], v[236:239], v[72:75]
	v_mfma_f32_16x16x32_bf16 v[76:79], v[252:255], v[236:239], v[76:79]
	s_cmp_eq_u32 s12, 1
	s_cselect_b32 s2, s20, s2
	s_cselect_b32 s3, s21, s3
	s_cselect_b32 s6, s22, s6
	s_cselect_b32 s7, s23, s7
	s_add_u32 s4, s22, 0x20000
	s_addc_u32 s32, s23, 0
	s_cmp_eq_u32 s12, 1
	s_cselect_b32 s24, s4, s24
	s_cselect_b32 s25, s32, s25
	s_waitcnt vmcnt(0)
	s_barrier
	ds_read_b128 v[184:187], v116 offset:53504
	ds_read_b128 v[204:207], v119 offset:36864
	ds_read_b128 v[208:211], v119 offset:38912
	ds_read_b128 v[212:215], v119 offset:40960
	ds_read_b128 v[216:219], v119 offset:43008
	ds_read_b128 v[188:191], v116 offset:55552
	ds_read_b128 v[192:195], v116 offset:57600
	ds_read_b128 v[196:199], v116 offset:59648
	ds_read_b128 v[200:203], v116 offset:61696
	s_waitcnt lgkmcnt(7)
	v_mfma_f32_16x16x32_bf16 v[80:83], v[204:207], v[184:187], v[80:83]
	s_add_u32 m0, s13, 0x0
	s_nop 0
	global_load_lds_dwordx4 v161, s[2:3] sc1
	s_waitcnt lgkmcnt(6)
	v_mfma_f32_16x16x32_bf16 v[84:87], v[208:211], v[184:187], v[84:87]
	s_add_u32 m0, s13, 0x1000
	v_add_u32_e32 v166, 0x10000, v161
	global_load_lds_dwordx4 v166, s[2:3] sc1
	s_waitcnt lgkmcnt(5)
	v_mfma_f32_16x16x32_bf16 v[88:91], v[212:215], v[184:187], v[88:91]
	s_add_u32 m0, s13, 0x2000
	v_add_u32_e32 v166, 0x20000, v161
	global_load_lds_dwordx4 v166, s[2:3] sc1
	s_waitcnt lgkmcnt(4)
	v_mfma_f32_16x16x32_bf16 v[92:95], v[216:219], v[184:187], v[92:95]
	s_add_u32 m0, s13, 0x3000
	v_add_u32_e32 v166, 0x30000, v161
	global_load_lds_dwordx4 v166, s[2:3] sc1
	ds_read_b128 v[220:223], v118 offset:53504
	ds_read_b128 v[240:243], v160 offset:36864
	ds_read_b128 v[244:247], v160 offset:38912
	ds_read_b128 v[248:251], v160 offset:40960
	ds_read_b128 v[252:255], v160 offset:43008
	s_waitcnt lgkmcnt(8)
	v_mfma_f32_16x16x32_bf16 v[96:99], v[204:207], v[188:191], v[96:99]
	s_add_u32 m0, s13, 0x4000
	v_add_u32_e32 v166, 0x40000, v161
	global_load_lds_dwordx4 v166, s[2:3] sc1
	v_mfma_f32_16x16x32_bf16 v[100:103], v[208:211], v[188:191], v[100:103]
	s_add_u32 m0, s13, 0x5000
	s_nop 0
	global_load_lds_dwordx4 v165, s[6:7]
	v_mfma_f32_16x16x32_bf16 v[104:107], v[212:215], v[188:191], v[104:107]
	s_add_u32 m0, s13, 0x6000
	v_add_u32_e32 v166, 0x2000, v165
	global_load_lds_dwordx4 v166, s[6:7]
	v_mfma_f32_16x16x32_bf16 v[108:111], v[216:219], v[188:191], v[108:111]
	s_add_u32 m0, s13, 0x7000
	v_add_u32_e32 v166, 0x10000, v165
	global_load_lds_dwordx4 v166, s[6:7]
	ds_read_b128 v[224:227], v118 offset:55552
	ds_read_b128 v[228:231], v118 offset:57600
	ds_read_b128 v[232:235], v118 offset:59648
	ds_read_b128 v[236:239], v118 offset:61696
	s_waitcnt lgkmcnt(11)
	v_mfma_f32_16x16x32_bf16 v[112:115], v[204:207], v[192:195], v[112:115]
	s_add_u32 m0, s13, 0x8000
	v_add_u32_e32 v166, 0x12000, v165
	global_load_lds_dwordx4 v166, s[6:7]
	v_mfma_f32_16x16x32_bf16 v[120:123], v[208:211], v[192:195], v[120:123]
	v_mfma_f32_16x16x32_bf16 v[124:127], v[212:215], v[192:195], v[124:127]
	v_mfma_f32_16x16x32_bf16 v[140:143], v[216:219], v[192:195], v[140:143]
	s_waitcnt lgkmcnt(10)
	v_mfma_f32_16x16x32_bf16 v[144:147], v[204:207], v[196:199], v[144:147]
	v_mfma_f32_16x16x32_bf16 v[148:151], v[208:211], v[196:199], v[148:151]
	v_mfma_f32_16x16x32_bf16 v[152:155], v[212:215], v[196:199], v[152:155]
	v_mfma_f32_16x16x32_bf16 v[156:159], v[216:219], v[196:199], v[156:159]
	s_waitcnt lgkmcnt(9)
	v_mfma_f32_16x16x32_bf16 v[168:171], v[204:207], v[200:203], v[168:171]
	v_mfma_f32_16x16x32_bf16 v[172:175], v[208:211], v[200:203], v[172:175]
	v_mfma_f32_16x16x32_bf16 v[176:179], v[212:215], v[200:203], v[176:179]
	v_mfma_f32_16x16x32_bf16 v[180:183], v[216:219], v[200:203], v[180:183]
	s_waitcnt lgkmcnt(7)
	v_mfma_f32_16x16x32_bf16 v[80:83], v[240:243], v[220:223], v[80:83]
	s_waitcnt lgkmcnt(6)
	v_mfma_f32_16x16x32_bf16 v[84:87], v[244:247], v[220:223], v[84:87]
	s_waitcnt lgkmcnt(5)
	v_mfma_f32_16x16x32_bf16 v[88:91], v[248:251], v[220:223], v[88:91]
	s_waitcnt lgkmcnt(4)
	v_mfma_f32_16x16x32_bf16 v[92:95], v[252:255], v[220:223], v[92:95]
	s_waitcnt lgkmcnt(3)
	v_mfma_f32_16x16x32_bf16 v[96:99], v[240:243], v[224:227], v[96:99]
	v_mfma_f32_16x16x32_bf16 v[100:103], v[244:247], v[224:227], v[100:103]
	v_mfma_f32_16x16x32_bf16 v[104:107], v[248:251], v[224:227], v[104:107]
	v_mfma_f32_16x16x32_bf16 v[108:111], v[252:255], v[224:227], v[108:111]
	s_waitcnt lgkmcnt(2)
	v_mfma_f32_16x16x32_bf16 v[112:115], v[240:243], v[228:231], v[112:115]
	v_mfma_f32_16x16x32_bf16 v[120:123], v[244:247], v[228:231], v[120:123]
	v_mfma_f32_16x16x32_bf16 v[124:127], v[248:251], v[228:231], v[124:127]
	v_mfma_f32_16x16x32_bf16 v[140:143], v[252:255], v[228:231], v[140:143]
	s_waitcnt lgkmcnt(1)
	v_mfma_f32_16x16x32_bf16 v[144:147], v[240:243], v[232:235], v[144:147]
	v_mfma_f32_16x16x32_bf16 v[148:151], v[244:247], v[232:235], v[148:151]
	v_mfma_f32_16x16x32_bf16 v[152:155], v[248:251], v[232:235], v[152:155]
	v_mfma_f32_16x16x32_bf16 v[156:159], v[252:255], v[232:235], v[156:159]
	s_add_u32 s2, s2, 0x80
	s_addc_u32 s3, s3, 0
	s_add_u32 s6, s6, 0x80
	s_addc_u32 s7, s7, 0
	s_waitcnt lgkmcnt(0)
	v_mfma_f32_16x16x32_bf16 v[168:171], v[240:243], v[236:239], v[168:171]
	v_mfma_f32_16x16x32_bf16 v[172:175], v[244:247], v[236:239], v[172:175]
	v_mfma_f32_16x16x32_bf16 v[176:179], v[248:251], v[236:239], v[176:179]
	v_mfma_f32_16x16x32_bf16 v[180:183], v[252:255], v[236:239], v[180:183]
	s_sub_u32 s12, s12, 1
	s_cmp_lg_u32 s12, 0
	s_cbranch_scc1 .Lggu0_pair
	s_and_b32 s4, s10, 7
	s_lshl_b32 s4, s4, 3
	s_bfe_u32 s14, s10, 0x30003
	s_or_b32 s14, s14, s4
	s_lshr_b32 s15, s10, 6
	s_mul_i32 s4, s14, 0xdc000
	s_lshl_b32 s32, s15, 8
	s_add_u32 s4, s4, s32
	s_add_u32 s8, s76, s4
	s_addc_u32 s9, s77, 0
	s_mov_b32 s44, s8
	s_mov_b32 s46, s9
	s_nop 7
	v_mul_f32_e32 v184, 0xbfb8aa3b, v0
	v_mul_f32_e32 v185, 0xbfb8aa3b, v1
	v_mul_f32_e32 v186, 0xbfb8aa3b, v2
	v_mul_f32_e32 v187, 0xbfb8aa3b, v3
	v_exp_f32_e32 v184, v184
	v_exp_f32_e32 v185, v185
	v_exp_f32_e32 v186, v186
	v_exp_f32_e32 v187, v187
	s_nop 0
	v_add_f32_e32 v184, 1.0, v184
	v_add_f32_e32 v185, 1.0, v185
	v_add_f32_e32 v186, 1.0, v186
	v_add_f32_e32 v187, 1.0, v187
	v_rcp_f32_e32 v184, v184
	v_rcp_f32_e32 v185, v185
	v_rcp_f32_e32 v186, v186
	v_rcp_f32_e32 v187, v187
	s_nop 0
	v_mul_f32_e32 v184, v0, v184
	v_mul_f32_e32 v185, v1, v185
	v_mul_f32_e32 v186, v2, v186
	v_mul_f32_e32 v187, v3, v187
	v_mul_f32_e32 v184, v4, v184
	v_mul_f32_e32 v185, v5, v185
	v_mul_f32_e32 v186, v6, v186
	v_mul_f32_e32 v187, v7, v187
	v_mul_f32_e32 v192, 0xbfb8aa3b, v8
	v_mul_f32_e32 v193, 0xbfb8aa3b, v9
	v_mul_f32_e32 v194, 0xbfb8aa3b, v10
	v_mul_f32_e32 v195, 0xbfb8aa3b, v11
	v_exp_f32_e32 v192, v192
	v_exp_f32_e32 v193, v193
	v_exp_f32_e32 v194, v194
	v_exp_f32_e32 v195, v195
	s_nop 0
	v_add_f32_e32 v192, 1.0, v192
	v_add_f32_e32 v193, 1.0, v193
	v_add_f32_e32 v194, 1.0, v194
	v_add_f32_e32 v195, 1.0, v195
	v_rcp_f32_e32 v192, v192
	v_rcp_f32_e32 v193, v193
	v_rcp_f32_e32 v194, v194
	v_rcp_f32_e32 v195, v195
	s_nop 0
	v_mul_f32_e32 v192, v8, v192
	v_mul_f32_e32 v193, v9, v193
	v_mul_f32_e32 v194, v10, v194
	v_mul_f32_e32 v195, v11, v195
	v_mul_f32_e32 v192, v12, v192
	v_mul_f32_e32 v193, v13, v193
	v_mul_f32_e32 v194, v14, v194
	v_mul_f32_e32 v195, v15, v195
	v_cvt_pk_bf16_f32 v200, v184, v185
	v_cvt_pk_bf16_f32 v201, v186, v187
	v_cvt_pk_bf16_f32 v202, v192, v193
	v_cvt_pk_bf16_f32 v203, v194, v195
	global_store_dwordx4 v167, v[200:203], s[8:9]
	s_add_u32 s8, s8, 0x16000
	s_addc_u32 s9, s9, 0
	v_mul_f32_e32 v184, 0xbfb8aa3b, v16
	v_mul_f32_e32 v185, 0xbfb8aa3b, v17
	v_mul_f32_e32 v186, 0xbfb8aa3b, v18
	v_mul_f32_e32 v187, 0xbfb8aa3b, v19
	v_exp_f32_e32 v184, v184
	v_exp_f32_e32 v185, v185
	v_exp_f32_e32 v186, v186
	v_exp_f32_e32 v187, v187
	s_nop 0
	v_add_f32_e32 v184, 1.0, v184
	v_add_f32_e32 v185, 1.0, v185
	v_add_f32_e32 v186, 1.0, v186
	v_add_f32_e32 v187, 1.0, v187
	v_rcp_f32_e32 v184, v184
	v_rcp_f32_e32 v185, v185
	v_rcp_f32_e32 v186, v186
	v_rcp_f32_e32 v187, v187
	s_nop 0
	v_mul_f32_e32 v184, v16, v184
	v_mul_f32_e32 v185, v17, v185
	v_mul_f32_e32 v186, v18, v186
	v_mul_f32_e32 v187, v19, v187
	v_mul_f32_e32 v184, v20, v184
	v_mul_f32_e32 v185, v21, v185
	v_mul_f32_e32 v186, v22, v186
	v_mul_f32_e32 v187, v23, v187
	v_mul_f32_e32 v192, 0xbfb8aa3b, v24
	v_mul_f32_e32 v193, 0xbfb8aa3b, v25
	v_mul_f32_e32 v194, 0xbfb8aa3b, v26
	v_mul_f32_e32 v195, 0xbfb8aa3b, v27
	v_exp_f32_e32 v192, v192
	v_exp_f32_e32 v193, v193
	v_exp_f32_e32 v194, v194
	v_exp_f32_e32 v195, v195
	s_nop 0
	v_add_f32_e32 v192, 1.0, v192
	v_add_f32_e32 v193, 1.0, v193
	v_add_f32_e32 v194, 1.0, v194
	v_add_f32_e32 v195, 1.0, v195
	v_rcp_f32_e32 v192, v192
	v_rcp_f32_e32 v193, v193
	v_rcp_f32_e32 v194, v194
	v_rcp_f32_e32 v195, v195
	s_nop 0
	v_mul_f32_e32 v192, v24, v192
	v_mul_f32_e32 v193, v25, v193
	v_mul_f32_e32 v194, v26, v194
	v_mul_f32_e32 v195, v27, v195
	v_mul_f32_e32 v192, v28, v192
	v_mul_f32_e32 v193, v29, v193
	v_mul_f32_e32 v194, v30, v194
	v_mul_f32_e32 v195, v31, v195
	v_cvt_pk_bf16_f32 v204, v184, v185
	v_cvt_pk_bf16_f32 v205, v186, v187
	v_cvt_pk_bf16_f32 v206, v192, v193
	v_cvt_pk_bf16_f32 v207, v194, v195
	global_store_dwordx4 v167, v[204:207], s[8:9]
	s_add_u32 s8, s8, 0x16000
	s_addc_u32 s9, s9, 0
	v_mul_f32_e32 v184, 0xbfb8aa3b, v32
	v_mul_f32_e32 v185, 0xbfb8aa3b, v33
	v_mul_f32_e32 v186, 0xbfb8aa3b, v34
	v_mul_f32_e32 v187, 0xbfb8aa3b, v35
	v_exp_f32_e32 v184, v184
	v_exp_f32_e32 v185, v185
	v_exp_f32_e32 v186, v186
	v_exp_f32_e32 v187, v187
	s_nop 0
	v_add_f32_e32 v184, 1.0, v184
	v_add_f32_e32 v185, 1.0, v185
	v_add_f32_e32 v186, 1.0, v186
	v_add_f32_e32 v187, 1.0, v187
	v_rcp_f32_e32 v184, v184
	v_rcp_f32_e32 v185, v185
	v_rcp_f32_e32 v186, v186
	v_rcp_f32_e32 v187, v187
	s_nop 0
	v_mul_f32_e32 v184, v32, v184
	v_mul_f32_e32 v185, v33, v185
	v_mul_f32_e32 v186, v34, v186
	v_mul_f32_e32 v187, v35, v187
	v_mul_f32_e32 v184, v36, v184
	v_mul_f32_e32 v185, v37, v185
	v_mul_f32_e32 v186, v38, v186
	v_mul_f32_e32 v187, v39, v187
	v_mul_f32_e32 v192, 0xbfb8aa3b, v40
	v_mul_f32_e32 v193, 0xbfb8aa3b, v41
	v_mul_f32_e32 v194, 0xbfb8aa3b, v42
	v_mul_f32_e32 v195, 0xbfb8aa3b, v43
	v_exp_f32_e32 v192, v192
	v_exp_f32_e32 v193, v193
	v_exp_f32_e32 v194, v194
	v_exp_f32_e32 v195, v195
	s_nop 0
	v_add_f32_e32 v192, 1.0, v192
	v_add_f32_e32 v193, 1.0, v193
	v_add_f32_e32 v194, 1.0, v194
	v_add_f32_e32 v195, 1.0, v195
	v_rcp_f32_e32 v192, v192
	v_rcp_f32_e32 v193, v193
	v_rcp_f32_e32 v194, v194
	v_rcp_f32_e32 v195, v195
	s_nop 0
	v_mul_f32_e32 v192, v40, v192
	v_mul_f32_e32 v193, v41, v193
	v_mul_f32_e32 v194, v42, v194
	v_mul_f32_e32 v195, v43, v195
	v_mul_f32_e32 v192, v44, v192
	v_mul_f32_e32 v193, v45, v193
	v_mul_f32_e32 v194, v46, v194
	v_mul_f32_e32 v195, v47, v195
	v_cvt_pk_bf16_f32 v208, v184, v185
	v_cvt_pk_bf16_f32 v209, v186, v187
	v_cvt_pk_bf16_f32 v210, v192, v193
	v_cvt_pk_bf16_f32 v211, v194, v195
	global_store_dwordx4 v167, v[208:211], s[8:9]
	s_add_u32 s8, s8, 0x16000
	s_addc_u32 s9, s9, 0
	v_mul_f32_e32 v184, 0xbfb8aa3b, v48
	v_mul_f32_e32 v185, 0xbfb8aa3b, v49
	v_mul_f32_e32 v186, 0xbfb8aa3b, v50
	v_mul_f32_e32 v187, 0xbfb8aa3b, v51
	v_exp_f32_e32 v184, v184
	v_exp_f32_e32 v185, v185
	v_exp_f32_e32 v186, v186
	v_exp_f32_e32 v187, v187
	s_nop 0
	v_add_f32_e32 v184, 1.0, v184
	v_add_f32_e32 v185, 1.0, v185
	v_add_f32_e32 v186, 1.0, v186
	v_add_f32_e32 v187, 1.0, v187
	v_rcp_f32_e32 v184, v184
	v_rcp_f32_e32 v185, v185
	v_rcp_f32_e32 v186, v186
	v_rcp_f32_e32 v187, v187
	s_nop 0
	v_mul_f32_e32 v184, v48, v184
	v_mul_f32_e32 v185, v49, v185
	v_mul_f32_e32 v186, v50, v186
	v_mul_f32_e32 v187, v51, v187
	v_mul_f32_e32 v184, v52, v184
	v_mul_f32_e32 v185, v53, v185
	v_mul_f32_e32 v186, v54, v186
	v_mul_f32_e32 v187, v55, v187
	v_mul_f32_e32 v192, 0xbfb8aa3b, v56
	v_mul_f32_e32 v193, 0xbfb8aa3b, v57
	v_mul_f32_e32 v194, 0xbfb8aa3b, v58
	v_mul_f32_e32 v195, 0xbfb8aa3b, v59
	v_exp_f32_e32 v192, v192
	v_exp_f32_e32 v193, v193
	v_exp_f32_e32 v194, v194
	v_exp_f32_e32 v195, v195
	s_nop 0
	v_add_f32_e32 v192, 1.0, v192
	v_add_f32_e32 v193, 1.0, v193
	v_add_f32_e32 v194, 1.0, v194
	v_add_f32_e32 v195, 1.0, v195
	v_rcp_f32_e32 v192, v192
	v_rcp_f32_e32 v193, v193
	v_rcp_f32_e32 v194, v194
	v_rcp_f32_e32 v195, v195
	s_nop 0
	v_mul_f32_e32 v192, v56, v192
	v_mul_f32_e32 v193, v57, v193
	v_mul_f32_e32 v194, v58, v194
	v_mul_f32_e32 v195, v59, v195
	v_mul_f32_e32 v192, v60, v192
	v_mul_f32_e32 v193, v61, v193
	v_mul_f32_e32 v194, v62, v194
	v_mul_f32_e32 v195, v63, v195
	v_cvt_pk_bf16_f32 v212, v184, v185
	v_cvt_pk_bf16_f32 v213, v186, v187
	v_cvt_pk_bf16_f32 v214, v192, v193
	v_cvt_pk_bf16_f32 v215, v194, v195
	global_store_dwordx4 v167, v[212:215], s[8:9]
	s_add_u32 s8, s8, 0x16000
	s_addc_u32 s9, s9, 0
	v_mul_f32_e32 v184, 0xbfb8aa3b, v64
	v_mul_f32_e32 v185, 0xbfb8aa3b, v65
	v_mul_f32_e32 v186, 0xbfb8aa3b, v66
	v_mul_f32_e32 v187, 0xbfb8aa3b, v67
	v_exp_f32_e32 v184, v184
	v_exp_f32_e32 v185, v185
	v_exp_f32_e32 v186, v186
	v_exp_f32_e32 v187, v187
	s_nop 0
	v_add_f32_e32 v184, 1.0, v184
	v_add_f32_e32 v185, 1.0, v185
	v_add_f32_e32 v186, 1.0, v186
	v_add_f32_e32 v187, 1.0, v187
	v_rcp_f32_e32 v184, v184
	v_rcp_f32_e32 v185, v185
	v_rcp_f32_e32 v186, v186
	v_rcp_f32_e32 v187, v187
	s_nop 0
	v_mul_f32_e32 v184, v64, v184
	v_mul_f32_e32 v185, v65, v185
	v_mul_f32_e32 v186, v66, v186
	v_mul_f32_e32 v187, v67, v187
	v_mul_f32_e32 v184, v68, v184
	v_mul_f32_e32 v185, v69, v185
	v_mul_f32_e32 v186, v70, v186
	v_mul_f32_e32 v187, v71, v187
	v_mul_f32_e32 v192, 0xbfb8aa3b, v72
	v_mul_f32_e32 v193, 0xbfb8aa3b, v73
	v_mul_f32_e32 v194, 0xbfb8aa3b, v74
	v_mul_f32_e32 v195, 0xbfb8aa3b, v75
	v_exp_f32_e32 v192, v192
	v_exp_f32_e32 v193, v193
	v_exp_f32_e32 v194, v194
	v_exp_f32_e32 v195, v195
	s_nop 0
	v_add_f32_e32 v192, 1.0, v192
	v_add_f32_e32 v193, 1.0, v193
	v_add_f32_e32 v194, 1.0, v194
	v_add_f32_e32 v195, 1.0, v195
	v_rcp_f32_e32 v192, v192
	v_rcp_f32_e32 v193, v193
	v_rcp_f32_e32 v194, v194
	v_rcp_f32_e32 v195, v195
	s_nop 0
	v_mul_f32_e32 v192, v72, v192
	v_mul_f32_e32 v193, v73, v193
	v_mul_f32_e32 v194, v74, v194
	v_mul_f32_e32 v195, v75, v195
	v_mul_f32_e32 v192, v76, v192
	v_mul_f32_e32 v193, v77, v193
	v_mul_f32_e32 v194, v78, v194
	v_mul_f32_e32 v195, v79, v195
	v_cvt_pk_bf16_f32 v216, v184, v185
	v_cvt_pk_bf16_f32 v217, v186, v187
	v_cvt_pk_bf16_f32 v218, v192, v193
	v_cvt_pk_bf16_f32 v219, v194, v195
	global_store_dwordx4 v167, v[216:219], s[8:9]
	s_add_u32 s8, s44, 0x80
	s_addc_u32 s9, s46, 0
	v_mul_f32_e32 v184, 0xbfb8aa3b, v80
	v_mul_f32_e32 v185, 0xbfb8aa3b, v81
	v_mul_f32_e32 v186, 0xbfb8aa3b, v82
	v_mul_f32_e32 v187, 0xbfb8aa3b, v83
	v_exp_f32_e32 v184, v184
	v_exp_f32_e32 v185, v185
	v_exp_f32_e32 v186, v186
	v_exp_f32_e32 v187, v187
	s_nop 0
	v_add_f32_e32 v184, 1.0, v184
	v_add_f32_e32 v185, 1.0, v185
	v_add_f32_e32 v186, 1.0, v186
	v_add_f32_e32 v187, 1.0, v187
	v_rcp_f32_e32 v184, v184
	v_rcp_f32_e32 v185, v185
	v_rcp_f32_e32 v186, v186
	v_rcp_f32_e32 v187, v187
	s_nop 0
	v_mul_f32_e32 v184, v80, v184
	v_mul_f32_e32 v185, v81, v185
	v_mul_f32_e32 v186, v82, v186
	v_mul_f32_e32 v187, v83, v187
	v_mul_f32_e32 v184, v84, v184
	v_mul_f32_e32 v185, v85, v185
	v_mul_f32_e32 v186, v86, v186
	v_mul_f32_e32 v187, v87, v187
	v_mul_f32_e32 v192, 0xbfb8aa3b, v88
	v_mul_f32_e32 v193, 0xbfb8aa3b, v89
	v_mul_f32_e32 v194, 0xbfb8aa3b, v90
	v_mul_f32_e32 v195, 0xbfb8aa3b, v91
	v_exp_f32_e32 v192, v192
	v_exp_f32_e32 v193, v193
	v_exp_f32_e32 v194, v194
	v_exp_f32_e32 v195, v195
	s_nop 0
	v_add_f32_e32 v192, 1.0, v192
	v_add_f32_e32 v193, 1.0, v193
	v_add_f32_e32 v194, 1.0, v194
	v_add_f32_e32 v195, 1.0, v195
	v_rcp_f32_e32 v192, v192
	v_rcp_f32_e32 v193, v193
	v_rcp_f32_e32 v194, v194
	v_rcp_f32_e32 v195, v195
	s_nop 0
	v_mul_f32_e32 v192, v88, v192
	v_mul_f32_e32 v193, v89, v193
	v_mul_f32_e32 v194, v90, v194
	v_mul_f32_e32 v195, v91, v195
	v_mul_f32_e32 v192, v92, v192
	v_mul_f32_e32 v193, v93, v193
	v_mul_f32_e32 v194, v94, v194
	v_mul_f32_e32 v195, v95, v195
	v_cvt_pk_bf16_f32 v200, v184, v185
	v_cvt_pk_bf16_f32 v201, v186, v187
	v_cvt_pk_bf16_f32 v202, v192, v193
	v_cvt_pk_bf16_f32 v203, v194, v195
	global_store_dwordx4 v167, v[200:203], s[8:9]
	s_add_u32 s8, s8, 0x16000
	s_addc_u32 s9, s9, 0
	v_mul_f32_e32 v184, 0xbfb8aa3b, v96
	v_mul_f32_e32 v185, 0xbfb8aa3b, v97
	v_mul_f32_e32 v186, 0xbfb8aa3b, v98
	v_mul_f32_e32 v187, 0xbfb8aa3b, v99
	v_exp_f32_e32 v184, v184
	v_exp_f32_e32 v185, v185
	v_exp_f32_e32 v186, v186
	v_exp_f32_e32 v187, v187
	s_nop 0
	v_add_f32_e32 v184, 1.0, v184
	v_add_f32_e32 v185, 1.0, v185
	v_add_f32_e32 v186, 1.0, v186
	v_add_f32_e32 v187, 1.0, v187
	v_rcp_f32_e32 v184, v184
	v_rcp_f32_e32 v185, v185
	v_rcp_f32_e32 v186, v186
	v_rcp_f32_e32 v187, v187
	s_nop 0
	v_mul_f32_e32 v184, v96, v184
	v_mul_f32_e32 v185, v97, v185
	v_mul_f32_e32 v186, v98, v186
	v_mul_f32_e32 v187, v99, v187
	v_mul_f32_e32 v184, v100, v184
	v_mul_f32_e32 v185, v101, v185
	v_mul_f32_e32 v186, v102, v186
	v_mul_f32_e32 v187, v103, v187
	v_mul_f32_e32 v192, 0xbfb8aa3b, v104
	v_mul_f32_e32 v193, 0xbfb8aa3b, v105
	v_mul_f32_e32 v194, 0xbfb8aa3b, v106
	v_mul_f32_e32 v195, 0xbfb8aa3b, v107
	v_exp_f32_e32 v192, v192
	v_exp_f32_e32 v193, v193
	v_exp_f32_e32 v194, v194
	v_exp_f32_e32 v195, v195
	s_nop 0
	v_add_f32_e32 v192, 1.0, v192
	v_add_f32_e32 v193, 1.0, v193
	v_add_f32_e32 v194, 1.0, v194
	v_add_f32_e32 v195, 1.0, v195
	v_rcp_f32_e32 v192, v192
	v_rcp_f32_e32 v193, v193
	v_rcp_f32_e32 v194, v194
	v_rcp_f32_e32 v195, v195
	s_nop 0
	v_mul_f32_e32 v192, v104, v192
	v_mul_f32_e32 v193, v105, v193
	v_mul_f32_e32 v194, v106, v194
	v_mul_f32_e32 v195, v107, v195
	v_mul_f32_e32 v192, v108, v192
	v_mul_f32_e32 v193, v109, v193
	v_mul_f32_e32 v194, v110, v194
	v_mul_f32_e32 v195, v111, v195
	v_cvt_pk_bf16_f32 v204, v184, v185
	v_cvt_pk_bf16_f32 v205, v186, v187
	v_cvt_pk_bf16_f32 v206, v192, v193
	v_cvt_pk_bf16_f32 v207, v194, v195
	global_store_dwordx4 v167, v[204:207], s[8:9]
	s_add_u32 s8, s8, 0x16000
	s_addc_u32 s9, s9, 0
	v_mul_f32_e32 v184, 0xbfb8aa3b, v112
	v_mul_f32_e32 v185, 0xbfb8aa3b, v113
	v_mul_f32_e32 v186, 0xbfb8aa3b, v114
	v_mul_f32_e32 v187, 0xbfb8aa3b, v115
	v_exp_f32_e32 v184, v184
	v_exp_f32_e32 v185, v185
	v_exp_f32_e32 v186, v186
	v_exp_f32_e32 v187, v187
	s_nop 0
	v_add_f32_e32 v184, 1.0, v184
	v_add_f32_e32 v185, 1.0, v185
	v_add_f32_e32 v186, 1.0, v186
	v_add_f32_e32 v187, 1.0, v187
	v_rcp_f32_e32 v184, v184
	v_rcp_f32_e32 v185, v185
	v_rcp_f32_e32 v186, v186
	v_rcp_f32_e32 v187, v187
	s_nop 0
	v_mul_f32_e32 v184, v112, v184
	v_mul_f32_e32 v185, v113, v185
	v_mul_f32_e32 v186, v114, v186
	v_mul_f32_e32 v187, v115, v187
	v_mul_f32_e32 v184, v120, v184
	v_mul_f32_e32 v185, v121, v185
	v_mul_f32_e32 v186, v122, v186
	v_mul_f32_e32 v187, v123, v187
	v_mul_f32_e32 v192, 0xbfb8aa3b, v124
	v_mul_f32_e32 v193, 0xbfb8aa3b, v125
	v_mul_f32_e32 v194, 0xbfb8aa3b, v126
	v_mul_f32_e32 v195, 0xbfb8aa3b, v127
	v_exp_f32_e32 v192, v192
	v_exp_f32_e32 v193, v193
	v_exp_f32_e32 v194, v194
	v_exp_f32_e32 v195, v195
	s_nop 0
	v_add_f32_e32 v192, 1.0, v192
	v_add_f32_e32 v193, 1.0, v193
	v_add_f32_e32 v194, 1.0, v194
	v_add_f32_e32 v195, 1.0, v195
	v_rcp_f32_e32 v192, v192
	v_rcp_f32_e32 v193, v193
	v_rcp_f32_e32 v194, v194
	v_rcp_f32_e32 v195, v195
	s_nop 0
	v_mul_f32_e32 v192, v124, v192
	v_mul_f32_e32 v193, v125, v193
	v_mul_f32_e32 v194, v126, v194
	v_mul_f32_e32 v195, v127, v195
	v_mul_f32_e32 v192, v140, v192
	v_mul_f32_e32 v193, v141, v193
	v_mul_f32_e32 v194, v142, v194
	v_mul_f32_e32 v195, v143, v195
	v_cvt_pk_bf16_f32 v208, v184, v185
	v_cvt_pk_bf16_f32 v209, v186, v187
	v_cvt_pk_bf16_f32 v210, v192, v193
	v_cvt_pk_bf16_f32 v211, v194, v195
	global_store_dwordx4 v167, v[208:211], s[8:9]
	s_add_u32 s8, s8, 0x16000
	s_addc_u32 s9, s9, 0
	v_mul_f32_e32 v184, 0xbfb8aa3b, v144
	v_mul_f32_e32 v185, 0xbfb8aa3b, v145
	v_mul_f32_e32 v186, 0xbfb8aa3b, v146
	v_mul_f32_e32 v187, 0xbfb8aa3b, v147
	v_exp_f32_e32 v184, v184
	v_exp_f32_e32 v185, v185
	v_exp_f32_e32 v186, v186
	v_exp_f32_e32 v187, v187
	s_nop 0
	v_add_f32_e32 v184, 1.0, v184
	v_add_f32_e32 v185, 1.0, v185
	v_add_f32_e32 v186, 1.0, v186
	v_add_f32_e32 v187, 1.0, v187
	v_rcp_f32_e32 v184, v184
	v_rcp_f32_e32 v185, v185
	v_rcp_f32_e32 v186, v186
	v_rcp_f32_e32 v187, v187
	s_nop 0
	v_mul_f32_e32 v184, v144, v184
	v_mul_f32_e32 v185, v145, v185
	v_mul_f32_e32 v186, v146, v186
	v_mul_f32_e32 v187, v147, v187
	v_mul_f32_e32 v184, v148, v184
	v_mul_f32_e32 v185, v149, v185
	v_mul_f32_e32 v186, v150, v186
	v_mul_f32_e32 v187, v151, v187
	v_mul_f32_e32 v192, 0xbfb8aa3b, v152
	v_mul_f32_e32 v193, 0xbfb8aa3b, v153
	v_mul_f32_e32 v194, 0xbfb8aa3b, v154
	v_mul_f32_e32 v195, 0xbfb8aa3b, v155
	v_exp_f32_e32 v192, v192
	v_exp_f32_e32 v193, v193
	v_exp_f32_e32 v194, v194
	v_exp_f32_e32 v195, v195
	s_nop 0
	v_add_f32_e32 v192, 1.0, v192
	v_add_f32_e32 v193, 1.0, v193
	v_add_f32_e32 v194, 1.0, v194
	v_add_f32_e32 v195, 1.0, v195
	v_rcp_f32_e32 v192, v192
	v_rcp_f32_e32 v193, v193
	v_rcp_f32_e32 v194, v194
	v_rcp_f32_e32 v195, v195
	s_nop 0
	v_mul_f32_e32 v192, v152, v192
	v_mul_f32_e32 v193, v153, v193
	v_mul_f32_e32 v194, v154, v194
	v_mul_f32_e32 v195, v155, v195
	v_mul_f32_e32 v192, v156, v192
	v_mul_f32_e32 v193, v157, v193
	v_mul_f32_e32 v194, v158, v194
	v_mul_f32_e32 v195, v159, v195
	v_cvt_pk_bf16_f32 v212, v184, v185
	v_cvt_pk_bf16_f32 v213, v186, v187
	v_cvt_pk_bf16_f32 v214, v192, v193
	v_cvt_pk_bf16_f32 v215, v194, v195
	global_store_dwordx4 v167, v[212:215], s[8:9]
	s_add_u32 s8, s8, 0x16000
	s_addc_u32 s9, s9, 0
	v_mul_f32_e32 v184, 0xbfb8aa3b, v168
	v_mul_f32_e32 v185, 0xbfb8aa3b, v169
	v_mul_f32_e32 v186, 0xbfb8aa3b, v170
	v_mul_f32_e32 v187, 0xbfb8aa3b, v171
	v_exp_f32_e32 v184, v184
	v_exp_f32_e32 v185, v185
	v_exp_f32_e32 v186, v186
	v_exp_f32_e32 v187, v187
	s_nop 0
	v_add_f32_e32 v184, 1.0, v184
	v_add_f32_e32 v185, 1.0, v185
	v_add_f32_e32 v186, 1.0, v186
	v_add_f32_e32 v187, 1.0, v187
	v_rcp_f32_e32 v184, v184
	v_rcp_f32_e32 v185, v185
	v_rcp_f32_e32 v186, v186
	v_rcp_f32_e32 v187, v187
	s_nop 0
	v_mul_f32_e32 v184, v168, v184
	v_mul_f32_e32 v185, v169, v185
	v_mul_f32_e32 v186, v170, v186
	v_mul_f32_e32 v187, v171, v187
	v_mul_f32_e32 v184, v172, v184
	v_mul_f32_e32 v185, v173, v185
	v_mul_f32_e32 v186, v174, v186
	v_mul_f32_e32 v187, v175, v187
	v_mul_f32_e32 v192, 0xbfb8aa3b, v176
	v_mul_f32_e32 v193, 0xbfb8aa3b, v177
	v_mul_f32_e32 v194, 0xbfb8aa3b, v178
	v_mul_f32_e32 v195, 0xbfb8aa3b, v179
	v_exp_f32_e32 v192, v192
	v_exp_f32_e32 v193, v193
	v_exp_f32_e32 v194, v194
	v_exp_f32_e32 v195, v195
	s_nop 0
	v_add_f32_e32 v192, 1.0, v192
	v_add_f32_e32 v193, 1.0, v193
	v_add_f32_e32 v194, 1.0, v194
	v_add_f32_e32 v195, 1.0, v195
	v_rcp_f32_e32 v192, v192
	v_rcp_f32_e32 v193, v193
	v_rcp_f32_e32 v194, v194
	v_rcp_f32_e32 v195, v195
	s_nop 0
	v_mul_f32_e32 v192, v176, v192
	v_mul_f32_e32 v193, v177, v193
	v_mul_f32_e32 v194, v178, v194
	v_mul_f32_e32 v195, v179, v195
	v_mul_f32_e32 v192, v180, v192
	v_mul_f32_e32 v193, v181, v193
	v_mul_f32_e32 v194, v182, v194
	v_mul_f32_e32 v195, v183, v195
	v_cvt_pk_bf16_f32 v216, v184, v185
	v_cvt_pk_bf16_f32 v217, v186, v187
	v_cvt_pk_bf16_f32 v218, v192, v193
	v_cvt_pk_bf16_f32 v219, v194, v195
	global_store_dwordx4 v167, v[216:219], s[8:9]
	s_mov_b32 s48, 1
	s_add_u32 s10, s10, s11
	s_cmp_lt_u32 s10, s50
	s_cbranch_scc1 .Lggu0_tile

.LBB0_197:
	s_mul_i32 s2, s34, 12
	v_readlane_b32 s20, v162, 12
	s_or_b32 s35, s2, 3
	v_readlane_b32 s21, v162, 13
	s_cmp_ge_u32 s35, s21
	v_readlane_b32 s22, v162, 14
	v_readlane_b32 s23, v162, 15
	s_cbranch_scc1 .LBB0_247
	s_waitcnt vmcnt(0)
	v_readlane_b32 s4, v163, 17
	v_readlane_b32 s5, v163, 18
	s_barrier
	v_readlane_b32 s21, v162, 62
	s_nop 1
	s_cmp_eq_u32 s21, 1
	s_cbranch_scc1 .Lxb0_noinv
	v_lshrrev_b32_e32 v0, 6, v128
	v_readfirstlane_b32 s20, v0
	s_cmp_lg_u32 s20, 1
	s_cbranch_scc1 .Lxb0_ninv
	buffer_inv sc1

.Lxb0_noinv:
	s_and_saveexec_b64 s[2:3], s[4:5]
	s_cbranch_execz .LBB0_246
	s_waitcnt vmcnt(0) lgkmcnt(0)
	v_readlane_b32 s20, v162, 62
	v_readlane_b32 s21, v164, 0
	v_readlane_b32 s22, v162, 63
	s_cmp_eq_u32 s20, 1
	s_cbranch_scc0 .Lxb0_glob
	s_and_b32 s4, s21, 15
	s_lshl_b32 s4, s4, 8
	s_bfe_u32 s5, s21, 0x20004
	s_lshl_b32 s5, s5, 5
	s_add_u32 s4, s4, s5
	s_add_u32 s4, s4, 0x480
	s_add_u32 s4, s84, s4
	s_addc_u32 s5, s85, 0
	s_add_u32 s22, s22, 1
	s_nop 1
	v_writelane_b32 v162, s22, 63
	s_lshr_b32 s21, s21, 6
	s_lshl_b32 s21, s21, 2
	v_mov_b32_e32 v5, s21
	v_mov_b32_e32 v6, s22
	global_store_dword v5, v6, s[4:5]
	s_waitcnt vmcnt(0)
	s_mov_b32 s20, 0

.Lgdn0_noprio:
	s_and_b32 s4, s10, 7
	s_lshl_b32 s4, s4, 3
	s_bfe_u32 s32, s10, 0x30003
	s_or_b32 s4, s4, s32
	s_mul_i32 s4, s4, 0xdc000
	s_add_u32 s2, s16, s4
	s_addc_u32 s3, s17, 0
	s_lshr_b32 s4, s10, 6
	s_mul_i32 s4, s4, 0xb0000
	s_add_u32 s6, s18, s4
	s_addc_u32 s7, s19, 0
	s_add_u32 m0, s13, 0x0
	s_nop 0
	global_load_lds_dwordx4 v208, s[2:3] sc1
	s_add_u32 m0, s13, 0x1000
	s_nop 0
	global_load_lds_dwordx4 v209, s[2:3] sc1
	s_add_u32 m0, s13, 0x2000
	s_nop 0
	global_load_lds_dwordx4 v210, s[2:3] sc1
	s_add_u32 m0, s13, 0x3000
	s_nop 0
	global_load_lds_dwordx4 v211, s[2:3] sc1
	s_add_u32 m0, s13, 0x4000
	s_nop 0
	global_load_lds_dwordx4 v212, s[2:3] sc1
	s_add_u32 m0, s13, 0x5000
	s_nop 0
	global_load_lds_dwordx4 v213, s[6:7]
	s_add_u32 m0, s13, 0x6000
	s_nop 0
	global_load_lds_dwordx4 v214, s[6:7]
	s_add_u32 m0, s13, 0x7000
	s_nop 0
	global_load_lds_dwordx4 v215, s[6:7]
	s_add_u32 m0, s13, 0x8000
	s_nop 0
	global_load_lds_dwordx4 v216, s[6:7]
	s_add_u32 s2, s2, 0x80
	s_addc_u32 s3, s3, 0
	s_add_u32 s6, s6, 0x80
	s_addc_u32 s7, s7, 0

.Lgdn0_pair:
	s_waitcnt vmcnt(0)
	s_barrier
	ds_read_b128 v[80:83], v204 offset:0
	ds_read_b128 v[100:103], v206 offset:20480
	ds_read_b128 v[104:107], v206 offset:22528
	ds_read_b128 v[108:111], v206 offset:24576
	ds_read_b128 v[112:115], v206 offset:26624
	ds_read_b128 v[84:87], v204 offset:2048
	ds_read_b128 v[88:91], v204 offset:4096
	ds_read_b128 v[92:95], v204 offset:6144
	ds_read_b128 v[96:99], v204 offset:8192
	s_add_u32 m0, s13, 0xd100
	s_waitcnt lgkmcnt(7)
	v_mfma_f32_16x16x32_bf16 v[0:3], v[100:103], v[80:83], v[0:3]
	global_load_lds_dwordx4 v208, s[2:3] sc1
	s_add_u32 m0, s13, 0xe100
	s_waitcnt lgkmcnt(6)
	v_mfma_f32_16x16x32_bf16 v[4:7], v[104:107], v[80:83], v[4:7]
	global_load_lds_dwordx4 v209, s[2:3] sc1
	s_add_u32 m0, s13, 0xf100
	s_waitcnt lgkmcnt(5)
	v_mfma_f32_16x16x32_bf16 v[8:11], v[108:111], v[80:83], v[8:11]
	global_load_lds_dwordx4 v210, s[2:3] sc1
	s_add_u32 m0, s13, 0x10100
	s_waitcnt lgkmcnt(4)
	v_mfma_f32_16x16x32_bf16 v[12:15], v[112:115], v[80:83], v[12:15]
	global_load_lds_dwordx4 v211, s[2:3] sc1
	s_add_u32 m0, s13, 0x11100
	ds_read_b128 v[168:171], v205 offset:0
	ds_read_b128 v[188:191], v207 offset:20480
	ds_read_b128 v[192:195], v207 offset:22528
	ds_read_b128 v[196:199], v207 offset:24576
	ds_read_b128 v[200:203], v207 offset:26624
	s_waitcnt lgkmcnt(8)
	v_mfma_f32_16x16x32_bf16 v[16:19], v[100:103], v[84:87], v[16:19]
	global_load_lds_dwordx4 v212, s[2:3] sc1
	s_add_u32 m0, s13, 0x9000
	v_mfma_f32_16x16x32_bf16 v[20:23], v[104:107], v[84:87], v[20:23]
	global_load_lds_dwordx4 v213, s[6:7]
	s_add_u32 m0, s13, 0xa000
	v_mfma_f32_16x16x32_bf16 v[24:27], v[108:111], v[84:87], v[24:27]
	global_load_lds_dwordx4 v214, s[6:7]
	s_add_u32 m0, s13, 0xb000
	v_mfma_f32_16x16x32_bf16 v[28:31], v[112:115], v[84:87], v[28:31]
	global_load_lds_dwordx4 v215, s[6:7]
	s_add_u32 m0, s13, 0xc000
	ds_read_b128 v[172:175], v205 offset:2048
	ds_read_b128 v[176:179], v205 offset:4096
	ds_read_b128 v[180:183], v205 offset:6144
	ds_read_b128 v[184:187], v205 offset:8192
	s_waitcnt lgkmcnt(11)
	v_mfma_f32_16x16x32_bf16 v[32:35], v[100:103], v[88:91], v[32:35]
	global_load_lds_dwordx4 v216, s[6:7]
	v_mfma_f32_16x16x32_bf16 v[36:39], v[104:107], v[88:91], v[36:39]
	v_mfma_f32_16x16x32_bf16 v[40:43], v[108:111], v[88:91], v[40:43]
	v_mfma_f32_16x16x32_bf16 v[44:47], v[112:115], v[88:91], v[44:47]
	s_waitcnt lgkmcnt(10)
	v_mfma_f32_16x16x32_bf16 v[48:51], v[100:103], v[92:95], v[48:51]
	v_mfma_f32_16x16x32_bf16 v[52:55], v[104:107], v[92:95], v[52:55]
	v_mfma_f32_16x16x32_bf16 v[56:59], v[108:111], v[92:95], v[56:59]
	v_mfma_f32_16x16x32_bf16 v[60:63], v[112:115], v[92:95], v[60:63]
	s_waitcnt lgkmcnt(9)
	v_mfma_f32_16x16x32_bf16 v[64:67], v[100:103], v[96:99], v[64:67]
	v_mfma_f32_16x16x32_bf16 v[68:71], v[104:107], v[96:99], v[68:71]
	v_mfma_f32_16x16x32_bf16 v[72:75], v[108:111], v[96:99], v[72:75]
	v_mfma_f32_16x16x32_bf16 v[76:79], v[112:115], v[96:99], v[76:79]
	s_waitcnt lgkmcnt(7)
	v_mfma_f32_16x16x32_bf16 v[0:3], v[188:191], v[168:171], v[0:3]
	s_waitcnt lgkmcnt(6)
	v_mfma_f32_16x16x32_bf16 v[4:7], v[192:195], v[168:171], v[4:7]
	s_waitcnt lgkmcnt(5)
	v_mfma_f32_16x16x32_bf16 v[8:11], v[196:199], v[168:171], v[8:11]
	s_waitcnt lgkmcnt(4)
	v_mfma_f32_16x16x32_bf16 v[12:15], v[200:203], v[168:171], v[12:15]
	s_waitcnt lgkmcnt(3)
	v_mfma_f32_16x16x32_bf16 v[16:19], v[188:191], v[172:175], v[16:19]
	v_mfma_f32_16x16x32_bf16 v[20:23], v[192:195], v[172:175], v[20:23]
	v_mfma_f32_16x16x32_bf16 v[24:27], v[196:199], v[172:175], v[24:27]
	v_mfma_f32_16x16x32_bf16 v[28:31], v[200:203], v[172:175], v[28:31]
	s_waitcnt lgkmcnt(2)
	v_mfma_f32_16x16x32_bf16 v[32:35], v[188:191], v[176:179], v[32:35]
	v_mfma_f32_16x16x32_bf16 v[36:39], v[192:195], v[176:179], v[36:39]
	v_mfma_f32_16x16x32_bf16 v[40:43], v[196:199], v[176:179], v[40:43]
	v_mfma_f32_16x16x32_bf16 v[44:47], v[200:203], v[176:179], v[44:47]
	s_waitcnt lgkmcnt(1)
	v_mfma_f32_16x16x32_bf16 v[48:51], v[188:191], v[180:183], v[48:51]
	v_mfma_f32_16x16x32_bf16 v[52:55], v[192:195], v[180:183], v[52:55]
	v_mfma_f32_16x16x32_bf16 v[56:59], v[196:199], v[180:183], v[56:59]
	v_mfma_f32_16x16x32_bf16 v[60:63], v[200:203], v[180:183], v[60:63]
	s_add_u32 s2, s2, 0x80
	s_addc_u32 s3, s3, 0
	s_add_u32 s6, s6, 0x80
	s_addc_u32 s7, s7, 0
	s_waitcnt lgkmcnt(0)
	v_mfma_f32_16x16x32_bf16 v[64:67], v[188:191], v[184:187], v[64:67]
	v_mfma_f32_16x16x32_bf16 v[68:71], v[192:195], v[184:187], v[68:71]
	v_mfma_f32_16x16x32_bf16 v[72:75], v[196:199], v[184:187], v[72:75]
	v_mfma_f32_16x16x32_bf16 v[76:79], v[200:203], v[184:187], v[76:79]
	s_cmp_eq_u32 s12, 1
	s_cselect_b32 s2, s20, s2
	s_cselect_b32 s3, s21, s3
	s_cselect_b32 s6, s22, s6
	s_cselect_b32 s7, s23, s7
	s_waitcnt vmcnt(0)
	s_barrier
	ds_read_b128 v[80:83], v204 offset:53504
	ds_read_b128 v[100:103], v206 offset:36864
	ds_read_b128 v[104:107], v206 offset:38912
	ds_read_b128 v[108:111], v206 offset:40960
	ds_read_b128 v[112:115], v206 offset:43008
	ds_read_b128 v[84:87], v204 offset:55552
	ds_read_b128 v[88:91], v204 offset:57600
	ds_read_b128 v[92:95], v204 offset:59648
	ds_read_b128 v[96:99], v204 offset:61696
	s_add_u32 m0, s13, 0x0
	s_waitcnt lgkmcnt(7)
	v_mfma_f32_16x16x32_bf16 v[0:3], v[100:103], v[80:83], v[0:3]
	global_load_lds_dwordx4 v208, s[2:3] sc1
	s_add_u32 m0, s13, 0x1000
	s_waitcnt lgkmcnt(6)
	v_mfma_f32_16x16x32_bf16 v[4:7], v[104:107], v[80:83], v[4:7]
	global_load_lds_dwordx4 v209, s[2:3] sc1
	s_add_u32 m0, s13, 0x2000
	s_waitcnt lgkmcnt(5)
	v_mfma_f32_16x16x32_bf16 v[8:11], v[108:111], v[80:83], v[8:11]
	global_load_lds_dwordx4 v210, s[2:3] sc1
	s_add_u32 m0, s13, 0x3000
	s_waitcnt lgkmcnt(4)
	v_mfma_f32_16x16x32_bf16 v[12:15], v[112:115], v[80:83], v[12:15]
	global_load_lds_dwordx4 v211, s[2:3] sc1
	s_add_u32 m0, s13, 0x4000
	ds_read_b128 v[168:171], v205 offset:53504
	ds_read_b128 v[188:191], v207 offset:36864
	ds_read_b128 v[192:195], v207 offset:38912
	ds_read_b128 v[196:199], v207 offset:40960
	ds_read_b128 v[200:203], v207 offset:43008
	s_waitcnt lgkmcnt(8)
	v_mfma_f32_16x16x32_bf16 v[16:19], v[100:103], v[84:87], v[16:19]
	global_load_lds_dwordx4 v212, s[2:3] sc1
	s_add_u32 m0, s13, 0x5000
	v_mfma_f32_16x16x32_bf16 v[20:23], v[104:107], v[84:87], v[20:23]
	global_load_lds_dwordx4 v213, s[6:7]
	s_add_u32 m0, s13, 0x6000
	v_mfma_f32_16x16x32_bf16 v[24:27], v[108:111], v[84:87], v[24:27]
	global_load_lds_dwordx4 v214, s[6:7]
	s_add_u32 m0, s13, 0x7000
	v_mfma_f32_16x16x32_bf16 v[28:31], v[112:115], v[84:87], v[28:31]
	global_load_lds_dwordx4 v215, s[6:7]
	s_add_u32 m0, s13, 0x8000
	ds_read_b128 v[172:175], v205 offset:55552
	ds_read_b128 v[176:179], v205 offset:57600
	ds_read_b128 v[180:183], v205 offset:59648
	ds_read_b128 v[184:187], v205 offset:61696
	s_waitcnt lgkmcnt(11)
	v_mfma_f32_16x16x32_bf16 v[32:35], v[100:103], v[88:91], v[32:35]
	global_load_lds_dwordx4 v216, s[6:7]
	v_mfma_f32_16x16x32_bf16 v[36:39], v[104:107], v[88:91], v[36:39]
	v_mfma_f32_16x16x32_bf16 v[40:43], v[108:111], v[88:91], v[40:43]
	v_mfma_f32_16x16x32_bf16 v[44:47], v[112:115], v[88:91], v[44:47]
	s_waitcnt lgkmcnt(10)
	v_mfma_f32_16x16x32_bf16 v[48:51], v[100:103], v[92:95], v[48:51]
	v_mfma_f32_16x16x32_bf16 v[52:55], v[104:107], v[92:95], v[52:55]
	v_mfma_f32_16x16x32_bf16 v[56:59], v[108:111], v[92:95], v[56:59]
	v_mfma_f32_16x16x32_bf16 v[60:63], v[112:115], v[92:95], v[60:63]
	s_waitcnt lgkmcnt(9)
	v_mfma_f32_16x16x32_bf16 v[64:67], v[100:103], v[96:99], v[64:67]
	v_mfma_f32_16x16x32_bf16 v[68:71], v[104:107], v[96:99], v[68:71]
	v_mfma_f32_16x16x32_bf16 v[72:75], v[108:111], v[96:99], v[72:75]
	v_mfma_f32_16x16x32_bf16 v[76:79], v[112:115], v[96:99], v[76:79]
	s_waitcnt lgkmcnt(7)
	v_mfma_f32_16x16x32_bf16 v[0:3], v[188:191], v[168:171], v[0:3]
	s_waitcnt lgkmcnt(6)
	v_mfma_f32_16x16x32_bf16 v[4:7], v[192:195], v[168:171], v[4:7]
	s_waitcnt lgkmcnt(5)
	v_mfma_f32_16x16x32_bf16 v[8:11], v[196:199], v[168:171], v[8:11]
	s_waitcnt lgkmcnt(4)
	v_mfma_f32_16x16x32_bf16 v[12:15], v[200:203], v[168:171], v[12:15]
	s_waitcnt lgkmcnt(3)
	v_mfma_f32_16x16x32_bf16 v[16:19], v[188:191], v[172:175], v[16:19]
	v_mfma_f32_16x16x32_bf16 v[20:23], v[192:195], v[172:175], v[20:23]
	v_mfma_f32_16x16x32_bf16 v[24:27], v[196:199], v[172:175], v[24:27]
	v_mfma_f32_16x16x32_bf16 v[28:31], v[200:203], v[172:175], v[28:31]
	s_waitcnt lgkmcnt(2)
	v_mfma_f32_16x16x32_bf16 v[32:35], v[188:191], v[176:179], v[32:35]
	v_mfma_f32_16x16x32_bf16 v[36:39], v[192:195], v[176:179], v[36:39]
	v_mfma_f32_16x16x32_bf16 v[40:43], v[196:199], v[176:179], v[40:43]
	v_mfma_f32_16x16x32_bf16 v[44:47], v[200:203], v[176:179], v[44:47]
	s_waitcnt lgkmcnt(1)
	v_mfma_f32_16x16x32_bf16 v[48:51], v[188:191], v[180:183], v[48:51]
	v_mfma_f32_16x16x32_bf16 v[52:55], v[192:195], v[180:183], v[52:55]
	v_mfma_f32_16x16x32_bf16 v[56:59], v[196:199], v[180:183], v[56:59]
	v_mfma_f32_16x16x32_bf16 v[60:63], v[200:203], v[180:183], v[60:63]
	s_add_u32 s2, s2, 0x80
	s_addc_u32 s3, s3, 0
	s_add_u32 s6, s6, 0x80
	s_addc_u32 s7, s7, 0
	s_waitcnt lgkmcnt(0)
	v_mfma_f32_16x16x32_bf16 v[64:67], v[188:191], v[184:187], v[64:67]
	v_mfma_f32_16x16x32_bf16 v[68:71], v[192:195], v[184:187], v[68:71]
	v_mfma_f32_16x16x32_bf16 v[72:75], v[196:199], v[184:187], v[72:75]
	v_mfma_f32_16x16x32_bf16 v[76:79], v[200:203], v[184:187], v[76:79]
	s_sub_u32 s12, s12, 1
	s_cmp_lg_u32 s12, 0
	s_cbranch_scc1 .Lgdn0_pair
	s_and_b32 s4, s10, 7
	s_lshl_b32 s4, s4, 3
	s_bfe_u32 s14, s10, 0x30003
	s_or_b32 s14, s14, s4
	s_lshr_b32 s15, s10, 6
	s_mul_i32 s4, s14, 0x50000
	s_lshl_b32 s32, s15, 8
	s_add_u32 s4, s4, s32
	s_add_u32 s8, s78, s4
	s_addc_u32 s9, s79, 0
	s_nop 7
	v_cvt_pk_bf16_f32 v80, v0, v1
	v_cvt_pk_bf16_f32 v81, v2, v3
	v_cvt_pk_bf16_f32 v82, v4, v5
	v_cvt_pk_bf16_f32 v83, v6, v7
	global_store_dwordx4 v217, v[80:83], s[8:9]
	v_cvt_pk_bf16_f32 v84, v8, v9
	v_cvt_pk_bf16_f32 v85, v10, v11
	v_cvt_pk_bf16_f32 v86, v12, v13
	v_cvt_pk_bf16_f32 v87, v14, v15
	global_store_dwordx4 v217, v[84:87], s[8:9] offset:64
	s_add_u32 s8, s8, 0x8000
	s_addc_u32 s9, s9, 0
	v_cvt_pk_bf16_f32 v88, v16, v17
	v_cvt_pk_bf16_f32 v89, v18, v19
	v_cvt_pk_bf16_f32 v90, v20, v21
	v_cvt_pk_bf16_f32 v91, v22, v23
	global_store_dwordx4 v217, v[88:91], s[8:9]
	v_cvt_pk_bf16_f32 v92, v24, v25
	v_cvt_pk_bf16_f32 v93, v26, v27
	v_cvt_pk_bf16_f32 v94, v28, v29
	v_cvt_pk_bf16_f32 v95, v30, v31
	global_store_dwordx4 v217, v[92:95], s[8:9] offset:64
	s_add_u32 s8, s8, 0x8000
	s_addc_u32 s9, s9, 0
	v_cvt_pk_bf16_f32 v96, v32, v33
	v_cvt_pk_bf16_f32 v97, v34, v35
	v_cvt_pk_bf16_f32 v98, v36, v37
	v_cvt_pk_bf16_f32 v99, v38, v39
	global_store_dwordx4 v217, v[96:99], s[8:9]
	v_cvt_pk_bf16_f32 v100, v40, v41
	v_cvt_pk_bf16_f32 v101, v42, v43
	v_cvt_pk_bf16_f32 v102, v44, v45
	v_cvt_pk_bf16_f32 v103, v46, v47
	global_store_dwordx4 v217, v[100:103], s[8:9] offset:64
	s_add_u32 s8, s8, 0x8000
	s_addc_u32 s9, s9, 0
	v_cvt_pk_bf16_f32 v104, v48, v49
	v_cvt_pk_bf16_f32 v105, v50, v51
	v_cvt_pk_bf16_f32 v106, v52, v53
	v_cvt_pk_bf16_f32 v107, v54, v55
	global_store_dwordx4 v217, v[104:107], s[8:9]
	v_cvt_pk_bf16_f32 v108, v56, v57
	v_cvt_pk_bf16_f32 v109, v58, v59
	v_cvt_pk_bf16_f32 v110, v60, v61
	v_cvt_pk_bf16_f32 v111, v62, v63
	global_store_dwordx4 v217, v[108:111], s[8:9] offset:64
	s_add_u32 s8, s8, 0x8000
	s_addc_u32 s9, s9, 0
	v_cvt_pk_bf16_f32 v112, v64, v65
	v_cvt_pk_bf16_f32 v113, v66, v67
	v_cvt_pk_bf16_f32 v114, v68, v69
	v_cvt_pk_bf16_f32 v115, v70, v71
	global_store_dwordx4 v217, v[112:115], s[8:9]
	v_cvt_pk_bf16_f32 v80, v72, v73
	v_cvt_pk_bf16_f32 v81, v74, v75
	v_cvt_pk_bf16_f32 v82, v76, v77
	v_cvt_pk_bf16_f32 v83, v78, v79
	global_store_dwordx4 v217, v[80:83], s[8:9] offset:64
	s_add_u32 s10, s10, s11
	s_cmp_lt_u32 s10, 0x200
	s_cbranch_scc1 .Lgdn0_tile

.LBB0_267:
	s_mul_i32 s2, s34, 12
	v_readlane_b32 s20, v162, 12
	s_add_i32 s35, s2, 4
	v_readlane_b32 s21, v162, 13
	s_cmp_ge_i32 s35, s21
	v_readlane_b32 s22, v162, 14
	v_readlane_b32 s23, v162, 15
	s_cbranch_scc1 .LBB0_317
	s_waitcnt vmcnt(0)
	v_readlane_b32 s4, v163, 17
	v_readlane_b32 s5, v163, 18
	s_barrier
	v_readlane_b32 s21, v162, 62
	s_nop 1
	s_cmp_eq_u32 s21, 1
	s_cbranch_scc1 .Lxb1_noinv
	v_lshrrev_b32_e32 v0, 6, v128
	v_readfirstlane_b32 s20, v0
	s_cmp_lg_u32 s20, 1
	s_cbranch_scc1 .Lxb1_ninv
	buffer_inv sc1

.Lgro2_batch:
	s_mov_b32 s20, s13
	s_min_u32 s21, s20, 0x27ff
	s_lshl_b32 s21, s21, 11
	s_add_u32 s22, s86, s21
	s_addc_u32 s23, s87, 0
	global_load_dwordx4 v[168:171], v82, s[22:23] sc1
	global_load_dwordx4 v[172:175], v82, s[22:23] offset:1024 sc1
	s_add_u32 s22, s78, s21
	s_addc_u32 s23, s79, 0
	global_load_dwordx4 v[176:179], v82, s[22:23] sc1
	global_load_dwordx4 v[180:183], v82, s[22:23] offset:1024 sc1
	s_add_u32 s20, s20, s14
	s_min_u32 s21, s20, 0x27ff
	s_lshl_b32 s21, s21, 11
	s_add_u32 s22, s86, s21
	s_addc_u32 s23, s87, 0
	global_load_dwordx4 v[184:187], v82, s[22:23] sc1
	global_load_dwordx4 v[188:191], v82, s[22:23] offset:1024 sc1
	s_add_u32 s22, s78, s21
	s_addc_u32 s23, s79, 0
	global_load_dwordx4 v[192:195], v82, s[22:23] sc1
	global_load_dwordx4 v[196:199], v82, s[22:23] offset:1024 sc1
	s_add_u32 s20, s20, s14
	s_min_u32 s21, s20, 0x27ff
	s_lshl_b32 s21, s21, 11
	s_add_u32 s22, s86, s21
	s_addc_u32 s23, s87, 0
	global_load_dwordx4 v[200:203], v82, s[22:23] sc1
	global_load_dwordx4 v[204:207], v82, s[22:23] offset:1024 sc1
	s_add_u32 s22, s78, s21
	s_addc_u32 s23, s79, 0
	global_load_dwordx4 v[208:211], v82, s[22:23] sc1
	global_load_dwordx4 v[212:215], v82, s[22:23] offset:1024 sc1
	s_add_u32 s20, s20, s14
	s_min_u32 s21, s20, 0x27ff
	s_lshl_b32 s21, s21, 11
	s_add_u32 s22, s86, s21
	s_addc_u32 s23, s87, 0
	global_load_dwordx4 v[216:219], v82, s[22:23] sc1
	global_load_dwordx4 v[220:223], v82, s[22:23] offset:1024 sc1
	s_add_u32 s22, s78, s21
	s_addc_u32 s23, s79, 0
	global_load_dwordx4 v[224:227], v82, s[22:23] sc1
	global_load_dwordx4 v[228:231], v82, s[22:23] offset:1024 sc1
	s_add_u32 s20, s20, s14
	s_min_u32 s21, s20, 0x27ff
	s_lshl_b32 s21, s21, 11
	s_add_u32 s22, s86, s21
	s_addc_u32 s23, s87, 0
	global_load_dwordx4 v[232:235], v82, s[22:23] sc1
	global_load_dwordx4 v[236:239], v82, s[22:23] offset:1024 sc1
	s_add_u32 s22, s78, s21
	s_addc_u32 s23, s79, 0
	global_load_dwordx4 v[240:243], v82, s[22:23] sc1
	global_load_dwordx4 v[244:247], v82, s[22:23] offset:1024 sc1
	s_mov_b32 s15, -1
	s_mov_b32 s20, s13
	s_cmp_ge_u32 s20, 0x2800
	s_cbranch_scc1 .Lgro2_bend
	s_sub_u32 s4, s20, 0x2000
	s_lshr_b32 s4, s4, 10
	s_add_u32 s4, s4, 1
	s_cmp_lt_u32 s20, 0x2000
	s_cselect_b32 s4, 0, s4
	s_cmp_eq_u32 s4, s15
	s_cbranch_scc1 .Lgro2_r0_same
	s_mov_b32 s15, s4
	s_mul_i32 s4, s4, 0x9000
	s_add_u32 s32, s4, s6
	s_add_u32 s22, s16, s32
	s_addc_u32 s23, s17, 0
	global_load_dwordx4 v[0:3], v83, s[22:23]
	global_load_dwordx4 v[4:7], v83, s[22:23] offset:16
	global_load_dwordx4 v[8:11], v83, s[22:23] offset:2048
	global_load_dwordx4 v[12:15], v83, s[22:23] offset:2064
	s_add_u32 s32, s4, s7
	s_add_u32 s22, s16, s32
	s_addc_u32 s23, s17, 0
	global_load_dwordx4 v[16:19], v83, s[22:23]
	global_load_dwordx4 v[20:23], v83, s[22:23] offset:16
	global_load_dwordx4 v[24:27], v83, s[22:23] offset:2048
	global_load_dwordx4 v[28:31], v83, s[22:23] offset:2064
	s_add_u32 s22, s22, 0x1000
	s_addc_u32 s23, s23, 0
	global_load_dwordx4 v[32:35], v83, s[22:23]
	global_load_dwordx4 v[36:39], v83, s[22:23] offset:16
	global_load_dwordx4 v[40:43], v83, s[22:23] offset:2048
	global_load_dwordx4 v[44:47], v83, s[22:23] offset:2064
	s_waitcnt vmcnt(0)
	s_branch .Lgro2_r0_go

.LBB0_323:
	s_or_b64 exec, exec, s[2:3]
	s_mul_i32 s2, s34, 12
	v_readlane_b32 s20, v162, 12
	s_add_i32 s35, s2, 5
	v_readlane_b32 s21, v162, 13
	s_cmp_ge_i32 s35, s21
	v_readlane_b32 s22, v162, 14
	v_readlane_b32 s23, v162, 15
	s_cbranch_scc1 .LBB0_373
	s_waitcnt vmcnt(0)
	v_readlane_b32 s4, v163, 17
	v_readlane_b32 s5, v163, 18
	s_barrier
	v_readlane_b32 s21, v162, 62
	s_nop 1
	s_cmp_eq_u32 s21, 1
	s_cbranch_scc1 .Lxb2_noinv
	v_lshrrev_b32_e32 v0, 6, v128
	v_readfirstlane_b32 s20, v0
	s_cmp_lg_u32 s20, 1
	s_cbranch_scc1 .Lxb2_ninv
	buffer_inv sc1

.Lgzin_noprio:
	s_and_b32 s4, s10, 7
	s_lshl_b32 s4, s4, 3
	s_bfe_u32 s32, s10, 0x30003
	s_or_b32 s4, s4, s32
	s_mul_i32 s4, s4, 0x50000
	s_add_u32 s2, s16, s4
	s_addc_u32 s3, s17, 0
	s_lshr_b32 s4, s10, 6
	s_mul_i32 s4, s4, 0x40000
	s_add_u32 s6, s18, s4
	s_addc_u32 s7, s19, 0
	s_add_u32 m0, s13, 0x0
	s_nop 0
	global_load_lds_dwordx4 v208, s[2:3] sc1
	s_add_u32 m0, s13, 0x1000
	s_nop 0
	global_load_lds_dwordx4 v209, s[2:3] sc1
	s_add_u32 m0, s13, 0x2000
	s_nop 0
	global_load_lds_dwordx4 v210, s[2:3] sc1
	s_add_u32 m0, s13, 0x3000
	s_nop 0
	global_load_lds_dwordx4 v211, s[2:3] sc1
	s_add_u32 m0, s13, 0x4000
	s_nop 0
	global_load_lds_dwordx4 v212, s[2:3] sc1
	s_add_u32 m0, s13, 0x5000
	s_nop 0
	global_load_lds_dwordx4 v213, s[6:7]
	s_add_u32 m0, s13, 0x6000
	s_nop 0
	global_load_lds_dwordx4 v214, s[6:7]
	s_add_u32 m0, s13, 0x7000
	s_nop 0
	global_load_lds_dwordx4 v215, s[6:7]
	s_add_u32 m0, s13, 0x8000
	s_nop 0
	global_load_lds_dwordx4 v216, s[6:7]
	s_add_u32 s2, s2, 0x80
	s_addc_u32 s3, s3, 0
	s_add_u32 s6, s6, 0x80
	s_addc_u32 s7, s7, 0

.Lgzin_pair:
	s_waitcnt vmcnt(0)
	s_barrier
	ds_read_b128 v[80:83], v204 offset:0
	ds_read_b128 v[100:103], v206 offset:20480
	ds_read_b128 v[104:107], v206 offset:22528
	ds_read_b128 v[108:111], v206 offset:24576
	ds_read_b128 v[112:115], v206 offset:26624
	ds_read_b128 v[84:87], v204 offset:2048
	ds_read_b128 v[88:91], v204 offset:4096
	ds_read_b128 v[92:95], v204 offset:6144
	ds_read_b128 v[96:99], v204 offset:8192
	s_add_u32 m0, s13, 0xd100
	s_waitcnt lgkmcnt(7)
	v_mfma_f32_16x16x32_bf16 v[0:3], v[100:103], v[80:83], v[0:3]
	global_load_lds_dwordx4 v208, s[2:3] sc1
	s_add_u32 m0, s13, 0xe100
	s_waitcnt lgkmcnt(6)
	v_mfma_f32_16x16x32_bf16 v[4:7], v[104:107], v[80:83], v[4:7]
	global_load_lds_dwordx4 v209, s[2:3] sc1
	s_add_u32 m0, s13, 0xf100
	s_waitcnt lgkmcnt(5)
	v_mfma_f32_16x16x32_bf16 v[8:11], v[108:111], v[80:83], v[8:11]
	global_load_lds_dwordx4 v210, s[2:3] sc1
	s_add_u32 m0, s13, 0x10100
	s_waitcnt lgkmcnt(4)
	v_mfma_f32_16x16x32_bf16 v[12:15], v[112:115], v[80:83], v[12:15]
	global_load_lds_dwordx4 v211, s[2:3] sc1
	s_add_u32 m0, s13, 0x11100
	ds_read_b128 v[168:171], v205 offset:0
	ds_read_b128 v[188:191], v207 offset:20480
	ds_read_b128 v[192:195], v207 offset:22528
	ds_read_b128 v[196:199], v207 offset:24576
	ds_read_b128 v[200:203], v207 offset:26624
	s_waitcnt lgkmcnt(8)
	v_mfma_f32_16x16x32_bf16 v[16:19], v[100:103], v[84:87], v[16:19]
	global_load_lds_dwordx4 v212, s[2:3] sc1
	s_add_u32 m0, s13, 0x9000
	v_mfma_f32_16x16x32_bf16 v[20:23], v[104:107], v[84:87], v[20:23]
	global_load_lds_dwordx4 v213, s[6:7]
	s_add_u32 m0, s13, 0xa000
	v_mfma_f32_16x16x32_bf16 v[24:27], v[108:111], v[84:87], v[24:27]
	global_load_lds_dwordx4 v214, s[6:7]
	s_add_u32 m0, s13, 0xb000
	v_mfma_f32_16x16x32_bf16 v[28:31], v[112:115], v[84:87], v[28:31]
	global_load_lds_dwordx4 v215, s[6:7]
	s_add_u32 m0, s13, 0xc000
	ds_read_b128 v[172:175], v205 offset:2048
	ds_read_b128 v[176:179], v205 offset:4096
	ds_read_b128 v[180:183], v205 offset:6144
	ds_read_b128 v[184:187], v205 offset:8192
	s_waitcnt lgkmcnt(11)
	v_mfma_f32_16x16x32_bf16 v[32:35], v[100:103], v[88:91], v[32:35]
	global_load_lds_dwordx4 v216, s[6:7]
	v_mfma_f32_16x16x32_bf16 v[36:39], v[104:107], v[88:91], v[36:39]
	v_mfma_f32_16x16x32_bf16 v[40:43], v[108:111], v[88:91], v[40:43]
	v_mfma_f32_16x16x32_bf16 v[44:47], v[112:115], v[88:91], v[44:47]
	s_waitcnt lgkmcnt(10)
	v_mfma_f32_16x16x32_bf16 v[48:51], v[100:103], v[92:95], v[48:51]
	v_mfma_f32_16x16x32_bf16 v[52:55], v[104:107], v[92:95], v[52:55]
	v_mfma_f32_16x16x32_bf16 v[56:59], v[108:111], v[92:95], v[56:59]
	v_mfma_f32_16x16x32_bf16 v[60:63], v[112:115], v[92:95], v[60:63]
	s_waitcnt lgkmcnt(9)
	v_mfma_f32_16x16x32_bf16 v[64:67], v[100:103], v[96:99], v[64:67]
	v_mfma_f32_16x16x32_bf16 v[68:71], v[104:107], v[96:99], v[68:71]
	v_mfma_f32_16x16x32_bf16 v[72:75], v[108:111], v[96:99], v[72:75]
	v_mfma_f32_16x16x32_bf16 v[76:79], v[112:115], v[96:99], v[76:79]
	s_waitcnt lgkmcnt(7)
	v_mfma_f32_16x16x32_bf16 v[0:3], v[188:191], v[168:171], v[0:3]
	s_waitcnt lgkmcnt(6)
	v_mfma_f32_16x16x32_bf16 v[4:7], v[192:195], v[168:171], v[4:7]
	s_waitcnt lgkmcnt(5)
	v_mfma_f32_16x16x32_bf16 v[8:11], v[196:199], v[168:171], v[8:11]
	s_waitcnt lgkmcnt(4)
	v_mfma_f32_16x16x32_bf16 v[12:15], v[200:203], v[168:171], v[12:15]
	s_waitcnt lgkmcnt(3)
	v_mfma_f32_16x16x32_bf16 v[16:19], v[188:191], v[172:175], v[16:19]
	v_mfma_f32_16x16x32_bf16 v[20:23], v[192:195], v[172:175], v[20:23]
	v_mfma_f32_16x16x32_bf16 v[24:27], v[196:199], v[172:175], v[24:27]
	v_mfma_f32_16x16x32_bf16 v[28:31], v[200:203], v[172:175], v[28:31]
	s_waitcnt lgkmcnt(2)
	v_mfma_f32_16x16x32_bf16 v[32:35], v[188:191], v[176:179], v[32:35]
	v_mfma_f32_16x16x32_bf16 v[36:39], v[192:195], v[176:179], v[36:39]
	v_mfma_f32_16x16x32_bf16 v[40:43], v[196:199], v[176:179], v[40:43]
	v_mfma_f32_16x16x32_bf16 v[44:47], v[200:203], v[176:179], v[44:47]
	s_waitcnt lgkmcnt(1)
	v_mfma_f32_16x16x32_bf16 v[48:51], v[188:191], v[180:183], v[48:51]
	v_mfma_f32_16x16x32_bf16 v[52:55], v[192:195], v[180:183], v[52:55]
	v_mfma_f32_16x16x32_bf16 v[56:59], v[196:199], v[180:183], v[56:59]
	v_mfma_f32_16x16x32_bf16 v[60:63], v[200:203], v[180:183], v[60:63]
	s_add_u32 s2, s2, 0x80
	s_addc_u32 s3, s3, 0
	s_add_u32 s6, s6, 0x80
	s_addc_u32 s7, s7, 0
	s_waitcnt lgkmcnt(0)
	v_mfma_f32_16x16x32_bf16 v[64:67], v[188:191], v[184:187], v[64:67]
	v_mfma_f32_16x16x32_bf16 v[68:71], v[192:195], v[184:187], v[68:71]
	v_mfma_f32_16x16x32_bf16 v[72:75], v[196:199], v[184:187], v[72:75]
	v_mfma_f32_16x16x32_bf16 v[76:79], v[200:203], v[184:187], v[76:79]
	s_cmp_eq_u32 s12, 1
	s_cselect_b32 s2, s20, s2
	s_cselect_b32 s3, s21, s3
	s_cselect_b32 s6, s22, s6
	s_cselect_b32 s7, s23, s7
	s_waitcnt vmcnt(0)
	s_barrier
	ds_read_b128 v[80:83], v204 offset:53504
	ds_read_b128 v[100:103], v206 offset:36864
	ds_read_b128 v[104:107], v206 offset:38912
	ds_read_b128 v[108:111], v206 offset:40960
	ds_read_b128 v[112:115], v206 offset:43008
	ds_read_b128 v[84:87], v204 offset:55552
	ds_read_b128 v[88:91], v204 offset:57600
	ds_read_b128 v[92:95], v204 offset:59648
	ds_read_b128 v[96:99], v204 offset:61696
	s_add_u32 m0, s13, 0x0
	s_waitcnt lgkmcnt(7)
	v_mfma_f32_16x16x32_bf16 v[0:3], v[100:103], v[80:83], v[0:3]
	global_load_lds_dwordx4 v208, s[2:3] sc1
	s_add_u32 m0, s13, 0x1000
	s_waitcnt lgkmcnt(6)
	v_mfma_f32_16x16x32_bf16 v[4:7], v[104:107], v[80:83], v[4:7]
	global_load_lds_dwordx4 v209, s[2:3] sc1
	s_add_u32 m0, s13, 0x2000
	s_waitcnt lgkmcnt(5)
	v_mfma_f32_16x16x32_bf16 v[8:11], v[108:111], v[80:83], v[8:11]
	global_load_lds_dwordx4 v210, s[2:3] sc1
	s_add_u32 m0, s13, 0x3000
	s_waitcnt lgkmcnt(4)
	v_mfma_f32_16x16x32_bf16 v[12:15], v[112:115], v[80:83], v[12:15]
	global_load_lds_dwordx4 v211, s[2:3] sc1
	s_add_u32 m0, s13, 0x4000
	ds_read_b128 v[168:171], v205 offset:53504
	ds_read_b128 v[188:191], v207 offset:36864
	ds_read_b128 v[192:195], v207 offset:38912
	ds_read_b128 v[196:199], v207 offset:40960
	ds_read_b128 v[200:203], v207 offset:43008
	s_waitcnt lgkmcnt(8)
	v_mfma_f32_16x16x32_bf16 v[16:19], v[100:103], v[84:87], v[16:19]
	global_load_lds_dwordx4 v212, s[2:3] sc1
	s_add_u32 m0, s13, 0x5000
	v_mfma_f32_16x16x32_bf16 v[20:23], v[104:107], v[84:87], v[20:23]
	global_load_lds_dwordx4 v213, s[6:7]
	s_add_u32 m0, s13, 0x6000
	v_mfma_f32_16x16x32_bf16 v[24:27], v[108:111], v[84:87], v[24:27]
	global_load_lds_dwordx4 v214, s[6:7]
	s_add_u32 m0, s13, 0x7000
	v_mfma_f32_16x16x32_bf16 v[28:31], v[112:115], v[84:87], v[28:31]
	global_load_lds_dwordx4 v215, s[6:7]
	s_add_u32 m0, s13, 0x8000
	ds_read_b128 v[172:175], v205 offset:55552
	ds_read_b128 v[176:179], v205 offset:57600
	ds_read_b128 v[180:183], v205 offset:59648
	ds_read_b128 v[184:187], v205 offset:61696
	s_waitcnt lgkmcnt(11)
	v_mfma_f32_16x16x32_bf16 v[32:35], v[100:103], v[88:91], v[32:35]
	global_load_lds_dwordx4 v216, s[6:7]
	v_mfma_f32_16x16x32_bf16 v[36:39], v[104:107], v[88:91], v[36:39]
	v_mfma_f32_16x16x32_bf16 v[40:43], v[108:111], v[88:91], v[40:43]
	v_mfma_f32_16x16x32_bf16 v[44:47], v[112:115], v[88:91], v[44:47]
	s_waitcnt lgkmcnt(10)
	v_mfma_f32_16x16x32_bf16 v[48:51], v[100:103], v[92:95], v[48:51]
	v_mfma_f32_16x16x32_bf16 v[52:55], v[104:107], v[92:95], v[52:55]
	v_mfma_f32_16x16x32_bf16 v[56:59], v[108:111], v[92:95], v[56:59]
	v_mfma_f32_16x16x32_bf16 v[60:63], v[112:115], v[92:95], v[60:63]
	s_waitcnt lgkmcnt(9)
	v_mfma_f32_16x16x32_bf16 v[64:67], v[100:103], v[96:99], v[64:67]
	v_mfma_f32_16x16x32_bf16 v[68:71], v[104:107], v[96:99], v[68:71]
	v_mfma_f32_16x16x32_bf16 v[72:75], v[108:111], v[96:99], v[72:75]
	v_mfma_f32_16x16x32_bf16 v[76:79], v[112:115], v[96:99], v[76:79]
	s_waitcnt lgkmcnt(7)
	v_mfma_f32_16x16x32_bf16 v[0:3], v[188:191], v[168:171], v[0:3]
	s_waitcnt lgkmcnt(6)
	v_mfma_f32_16x16x32_bf16 v[4:7], v[192:195], v[168:171], v[4:7]
	s_waitcnt lgkmcnt(5)
	v_mfma_f32_16x16x32_bf16 v[8:11], v[196:199], v[168:171], v[8:11]
	s_waitcnt lgkmcnt(4)
	v_mfma_f32_16x16x32_bf16 v[12:15], v[200:203], v[168:171], v[12:15]
	s_waitcnt lgkmcnt(3)
	v_mfma_f32_16x16x32_bf16 v[16:19], v[188:191], v[172:175], v[16:19]
	v_mfma_f32_16x16x32_bf16 v[20:23], v[192:195], v[172:175], v[20:23]
	v_mfma_f32_16x16x32_bf16 v[24:27], v[196:199], v[172:175], v[24:27]
	v_mfma_f32_16x16x32_bf16 v[28:31], v[200:203], v[172:175], v[28:31]
	s_waitcnt lgkmcnt(2)
	v_mfma_f32_16x16x32_bf16 v[32:35], v[188:191], v[176:179], v[32:35]
	v_mfma_f32_16x16x32_bf16 v[36:39], v[192:195], v[176:179], v[36:39]
	v_mfma_f32_16x16x32_bf16 v[40:43], v[196:199], v[176:179], v[40:43]
	v_mfma_f32_16x16x32_bf16 v[44:47], v[200:203], v[176:179], v[44:47]
	s_waitcnt lgkmcnt(1)
	v_mfma_f32_16x16x32_bf16 v[48:51], v[188:191], v[180:183], v[48:51]
	v_mfma_f32_16x16x32_bf16 v[52:55], v[192:195], v[180:183], v[52:55]
	v_mfma_f32_16x16x32_bf16 v[56:59], v[196:199], v[180:183], v[56:59]
	v_mfma_f32_16x16x32_bf16 v[60:63], v[200:203], v[180:183], v[60:63]
	s_add_u32 s2, s2, 0x80
	s_addc_u32 s3, s3, 0
	s_add_u32 s6, s6, 0x80
	s_addc_u32 s7, s7, 0
	s_waitcnt lgkmcnt(0)
	v_mfma_f32_16x16x32_bf16 v[64:67], v[188:191], v[184:187], v[64:67]
	v_mfma_f32_16x16x32_bf16 v[68:71], v[192:195], v[184:187], v[68:71]
	v_mfma_f32_16x16x32_bf16 v[72:75], v[196:199], v[184:187], v[72:75]
	v_mfma_f32_16x16x32_bf16 v[76:79], v[200:203], v[184:187], v[76:79]
	s_sub_u32 s12, s12, 1
	s_cmp_lg_u32 s12, 0
	s_cbranch_scc1 .Lgzin_pair
	s_and_b32 s4, s10, 7
	s_lshl_b32 s4, s4, 3
	s_bfe_u32 s14, s10, 0x30003
	s_or_b32 s14, s14, s4
	s_lshr_b32 s15, s10, 6
	s_mul_i32 s44, s14, 0xa0
	s_mul_i32 s4, s35, 0x50
	s_add_u32 s4, s4, s44
	v_add_u32_e32 v219, s4, v222
	s_nop 7
	s_lshl_b32 s46, s15, 7
	s_lshl_b32 s4, s36, 6
	s_add_u32 s46, s46, s4
	s_cmp_ge_u32 s46, 0xbc0
	s_cbranch_scc1 .Lgzin_z0_end
	s_cmp_lt_u32 s46, 0x200
	s_cbranch_scc1 .Lgzin_z0_q
	s_cmp_lt_u32 s46, 0x600
	s_cbranch_scc1 .Lgzin_z0_kv
	s_cmp_lt_u32 s46, 0x800
	s_cbranch_scc1 .Lgzin_z0_u
	s_mul_i32 s4, s44, 0x2f00
	s_lshl_b32 s32, s46, 2
	s_add_u32 s4, s4, s32
	s_add_u32 s8, s74, s4
	s_addc_u32 s9, s75, 0
	global_store_dwordx4 v218, v[0:3], s[8:9]
	global_store_dwordx4 v218, v[4:7], s[8:9] offset:16
	s_add_u32 s8, s8, 0x2f000
	s_addc_u32 s9, s9, 0
	global_store_dwordx4 v218, v[16:19], s[8:9]
	global_store_dwordx4 v218, v[20:23], s[8:9] offset:16
	s_add_u32 s8, s8, 0x2f000
	s_addc_u32 s9, s9, 0
	global_store_dwordx4 v218, v[32:35], s[8:9]
	global_store_dwordx4 v218, v[36:39], s[8:9] offset:16
	s_add_u32 s8, s8, 0x2f000
	s_addc_u32 s9, s9, 0
	global_store_dwordx4 v218, v[48:51], s[8:9]
	global_store_dwordx4 v218, v[52:55], s[8:9] offset:16
	s_add_u32 s8, s8, 0x2f000
	s_addc_u32 s9, s9, 0
	global_store_dwordx4 v218, v[64:67], s[8:9]
	global_store_dwordx4 v218, v[68:71], s[8:9] offset:16
	s_branch .Lgzin_z0_end

.LBB0_471:
	s_mul_i32 s2, s34, 12
	v_readlane_b32 s20, v162, 12
	s_add_i32 s35, s2, 6
	v_readlane_b32 s21, v162, 13
	s_cmp_ge_i32 s35, s21
	v_readlane_b32 s22, v162, 14
	v_readlane_b32 s23, v162, 15
	s_cbranch_scc1 .LBB0_521
	s_waitcnt vmcnt(0)
	v_readlane_b32 s4, v163, 17
	v_readlane_b32 s5, v163, 18
	s_barrier
	v_readlane_b32 s21, v162, 62
	s_nop 1
	s_cmp_eq_u32 s21, 1
	s_cbranch_scc1 .Lxb3_noinv
	v_lshrrev_b32_e32 v0, 6, v128
	v_readfirstlane_b32 s20, v0
	s_cmp_lg_u32 s20, 1
	s_cbranch_scc1 .Lxb3_ninv
	buffer_inv sc1

.Lgprep_batch:
	s_mov_b32 s6, s13
	s_min_u32 s6, s6, 0x27ff
	s_mul_i32 s7, s6, 0x2f00
	s_add_u32 s7, s7, 0x2400
	s_add_u32 s8, s74, s7
	s_addc_u32 s9, s75, 0
	global_load_dword v20, v233, s[8:9] offset:2048 sc1
	global_load_dword v25, v233, s[8:9] offset:2304 sc1
	s_add_u32 s6, s13, 1
	s_min_u32 s6, s6, 0x27ff
	s_mul_i32 s7, s6, 0x2f00
	s_add_u32 s7, s7, 0x2400
	s_add_u32 s8, s74, s7
	s_addc_u32 s9, s75, 0
	global_load_dword v21, v233, s[8:9] offset:2048 sc1
	global_load_dword v26, v233, s[8:9] offset:2304 sc1
	s_add_u32 s6, s13, 2
	s_min_u32 s6, s6, 0x27ff
	s_mul_i32 s7, s6, 0x2f00
	s_add_u32 s7, s7, 0x2400
	s_add_u32 s8, s74, s7
	s_addc_u32 s9, s75, 0
	global_load_dword v22, v233, s[8:9] offset:2048 sc1
	global_load_dword v27, v233, s[8:9] offset:2304 sc1
	s_add_u32 s6, s13, 3
	s_min_u32 s6, s6, 0x27ff
	s_mul_i32 s7, s6, 0x2f00
	s_add_u32 s7, s7, 0x2400
	s_add_u32 s8, s74, s7
	s_addc_u32 s9, s75, 0
	global_load_dword v23, v233, s[8:9] offset:2048 sc1
	global_load_dword v28, v233, s[8:9] offset:2304 sc1
	s_add_u32 s6, s13, 4
	s_min_u32 s6, s6, 0x27ff
	s_mul_i32 s7, s6, 0x2f00
	s_add_u32 s7, s7, 0x2400
	s_add_u32 s8, s74, s7
	s_addc_u32 s9, s75, 0
	global_load_dword v24, v233, s[8:9] offset:2048 sc1
	global_load_dword v29, v233, s[8:9] offset:2304 sc1
	s_mov_b32 s6, s13
	s_min_u32 s6, s6, 0x27ff
	s_mul_i32 s7, s6, 0x2f00
	s_add_u32 s7, s7, 0x2400
	s_add_u32 s8, s74, s7
	s_addc_u32 s9, s75, 0
	global_load_dwordx4 v[0:3], v232, s[8:9] sc1
	s_add_u32 s6, s13, 1
	s_min_u32 s6, s6, 0x27ff
	s_mul_i32 s7, s6, 0x2f00
	s_add_u32 s7, s7, 0x2400
	s_add_u32 s8, s74, s7
	s_addc_u32 s9, s75, 0
	global_load_dwordx4 v[4:7], v232, s[8:9] sc1
	s_add_u32 s6, s13, 2
	s_min_u32 s6, s6, 0x27ff
	s_mul_i32 s7, s6, 0x2f00
	s_add_u32 s7, s7, 0x2400
	s_add_u32 s8, s74, s7
	s_addc_u32 s9, s75, 0
	global_load_dwordx4 v[8:11], v232, s[8:9] sc1
	s_add_u32 s6, s13, 3
	s_min_u32 s6, s6, 0x27ff
	s_mul_i32 s7, s6, 0x2f00
	s_add_u32 s7, s7, 0x2400
	s_add_u32 s8, s74, s7
	s_addc_u32 s9, s75, 0
	global_load_dwordx4 v[12:15], v232, s[8:9] sc1
	s_add_u32 s6, s13, 4
	s_min_u32 s6, s6, 0x27ff
	s_mul_i32 s7, s6, 0x2f00
	s_add_u32 s7, s7, 0x2400
	s_add_u32 s8, s74, s7
	s_addc_u32 s9, s75, 0
	global_load_dwordx4 v[16:19], v232, s[8:9] sc1
	s_add_u32 s2, s16, 0x0
	s_addc_u32 s3, s17, 0
	s_add_u32 s40, s18, 0x0
	s_addc_u32 s41, s19, 0
	global_load_dwordx4 v[168:171], v232, s[2:3]
	global_load_dwordx4 v[172:175], v232, s[40:41]
	global_load_dwordx4 v[176:179], v232, s[2:3] offset:1024
	global_load_dwordx4 v[180:183], v232, s[40:41] offset:1024
	global_load_dwordx4 v[184:187], v232, s[2:3] offset:2048
	global_load_dwordx4 v[188:191], v232, s[40:41] offset:2048
	global_load_dwordx4 v[192:195], v232, s[2:3] offset:3072
	global_load_dwordx4 v[196:199], v232, s[40:41] offset:3072
	s_add_u32 s2, s2, 0x1000
	s_addc_u32 s3, s3, 0
	s_add_u32 s40, s40, 0x1000
	s_addc_u32 s41, s41, 0
	global_load_dwordx4 v[200:203], v232, s[2:3]
	global_load_dwordx4 v[204:207], v232, s[40:41]
	global_load_dwordx4 v[208:211], v232, s[2:3] offset:1024
	global_load_dwordx4 v[212:215], v232, s[40:41] offset:1024
	s_waitcnt vmcnt(17)
	v_add_f32_e64 v92, |v20|, |v20|
	v_mul_f32_e32 v93, 0x3fb8aa3b, v92
	v_rndne_f32_e32 v94, v93
	s_mov_b32 s4, 0x3fb8aa3b
	v_sub_f32_e32 v95, v93, v94
	v_fma_f32 v93, v92, s4, -v93
	v_fmac_f32_e32 v93, 0x32a5705f, v92
	v_add_f32_e32 v93, v95, v93
	v_cvt_i32_f32_e32 v94, v94
	v_exp_f32_e32 v93, v93
	s_mov_b32 s4, 0xc2ce8ed0
	v_cmp_ngt_f32_e32 vcc, s4, v92
	s_mov_b32 s4, 0x42b17218
	v_ldexp_f32 v93, v93, v94
	s_nop 0
	v_cndmask_b32_e32 v93, 0, v93, vcc
	v_cmp_nlt_f32_e32 vcc, s4, v92
	s_nop 1
	v_cndmask_b32_e32 v92, v134, v93, vcc
	v_add_f32_e32 v92, 1.0, v92
	v_rcp_f32_e32 v92, v92
	s_nop 0
	v_fma_f32 v96, v92, -2.0, 1.0
	v_mul_f32_e32 v98, v20, v20
	v_fmamk_f32 v97, v98, 0xbbbac73d, v131
	v_fmaak_f32 v97, v98, v97, 0xbd5c1c4e
	v_fmaak_f32 v97, v98, v97, 0x3e088382
	v_fmaak_f32 v97, v98, v97, 0xbeaaaa99
	v_mul_f32_e64 v97, |v20|, v97
	v_fma_f32 v97, v98, v97, |v20|
	s_mov_b32 s4, 0x3f200000
	v_cmp_nlt_f32_e64 vcc, |v20|, s4
	s_nop 1
	v_cndmask_b32_e32 v97, v97, v96, vcc
	s_brev_b32 s4, -2
	v_bfi_b32 v20, s4, v97, v20
	v_add_f32_e64 v92, |v21|, |v21|
	v_mul_f32_e32 v93, 0x3fb8aa3b, v92
	v_rndne_f32_e32 v94, v93
	s_mov_b32 s4, 0x3fb8aa3b
	v_sub_f32_e32 v95, v93, v94
	v_fma_f32 v93, v92, s4, -v93
	v_fmac_f32_e32 v93, 0x32a5705f, v92
	v_add_f32_e32 v93, v95, v93
	v_cvt_i32_f32_e32 v94, v94
	v_exp_f32_e32 v93, v93
	s_mov_b32 s4, 0xc2ce8ed0
	v_cmp_ngt_f32_e32 vcc, s4, v92
	s_mov_b32 s4, 0x42b17218
	v_ldexp_f32 v93, v93, v94
	s_nop 0
	v_cndmask_b32_e32 v93, 0, v93, vcc
	v_cmp_nlt_f32_e32 vcc, s4, v92
	s_nop 1
	v_cndmask_b32_e32 v92, v134, v93, vcc
	v_add_f32_e32 v92, 1.0, v92
	v_rcp_f32_e32 v92, v92
	s_nop 0
	v_fma_f32 v96, v92, -2.0, 1.0
	v_mul_f32_e32 v98, v21, v21
	v_fmamk_f32 v97, v98, 0xbbbac73d, v131
	v_fmaak_f32 v97, v98, v97, 0xbd5c1c4e
	v_fmaak_f32 v97, v98, v97, 0x3e088382
	v_fmaak_f32 v97, v98, v97, 0xbeaaaa99
	v_mul_f32_e64 v97, |v21|, v97
	v_fma_f32 v97, v98, v97, |v21|
	s_mov_b32 s4, 0x3f200000
	v_cmp_nlt_f32_e64 vcc, |v21|, s4
	s_nop 1
	v_cndmask_b32_e32 v97, v97, v96, vcc
	s_brev_b32 s4, -2
	v_bfi_b32 v21, s4, v97, v21
	v_add_f32_e64 v92, |v22|, |v22|
	v_mul_f32_e32 v93, 0x3fb8aa3b, v92
	v_rndne_f32_e32 v94, v93
	s_mov_b32 s4, 0x3fb8aa3b
	v_sub_f32_e32 v95, v93, v94
	v_fma_f32 v93, v92, s4, -v93
	v_fmac_f32_e32 v93, 0x32a5705f, v92
	v_add_f32_e32 v93, v95, v93
	v_cvt_i32_f32_e32 v94, v94
	v_exp_f32_e32 v93, v93
	s_mov_b32 s4, 0xc2ce8ed0
	v_cmp_ngt_f32_e32 vcc, s4, v92
	s_mov_b32 s4, 0x42b17218
	v_ldexp_f32 v93, v93, v94
	s_nop 0
	v_cndmask_b32_e32 v93, 0, v93, vcc
	v_cmp_nlt_f32_e32 vcc, s4, v92
	s_nop 1
	v_cndmask_b32_e32 v92, v134, v93, vcc
	v_add_f32_e32 v92, 1.0, v92
	v_rcp_f32_e32 v92, v92
	s_nop 0
	v_fma_f32 v96, v92, -2.0, 1.0
	v_mul_f32_e32 v98, v22, v22
	v_fmamk_f32 v97, v98, 0xbbbac73d, v131
	v_fmaak_f32 v97, v98, v97, 0xbd5c1c4e
	v_fmaak_f32 v97, v98, v97, 0x3e088382
	v_fmaak_f32 v97, v98, v97, 0xbeaaaa99
	v_mul_f32_e64 v97, |v22|, v97
	v_fma_f32 v97, v98, v97, |v22|
	s_mov_b32 s4, 0x3f200000
	v_cmp_nlt_f32_e64 vcc, |v22|, s4
	s_nop 1
	v_cndmask_b32_e32 v97, v97, v96, vcc
	s_brev_b32 s4, -2
	v_bfi_b32 v22, s4, v97, v22
	v_add_f32_e64 v92, |v23|, |v23|
	v_mul_f32_e32 v93, 0x3fb8aa3b, v92
	v_rndne_f32_e32 v94, v93
	s_mov_b32 s4, 0x3fb8aa3b
	v_sub_f32_e32 v95, v93, v94
	v_fma_f32 v93, v92, s4, -v93
	v_fmac_f32_e32 v93, 0x32a5705f, v92
	v_add_f32_e32 v93, v95, v93
	v_cvt_i32_f32_e32 v94, v94
	v_exp_f32_e32 v93, v93
	s_mov_b32 s4, 0xc2ce8ed0
	v_cmp_ngt_f32_e32 vcc, s4, v92
	s_mov_b32 s4, 0x42b17218
	v_ldexp_f32 v93, v93, v94
	s_nop 0
	v_cndmask_b32_e32 v93, 0, v93, vcc
	v_cmp_nlt_f32_e32 vcc, s4, v92
	s_nop 1
	v_cndmask_b32_e32 v92, v134, v93, vcc
	v_add_f32_e32 v92, 1.0, v92
	v_rcp_f32_e32 v92, v92
	s_nop 0
	v_fma_f32 v96, v92, -2.0, 1.0
	v_mul_f32_e32 v98, v23, v23
	v_fmamk_f32 v97, v98, 0xbbbac73d, v131
	v_fmaak_f32 v97, v98, v97, 0xbd5c1c4e
	v_fmaak_f32 v97, v98, v97, 0x3e088382
	v_fmaak_f32 v97, v98, v97, 0xbeaaaa99
	v_mul_f32_e64 v97, |v23|, v97
	v_fma_f32 v97, v98, v97, |v23|
	s_mov_b32 s4, 0x3f200000
	v_cmp_nlt_f32_e64 vcc, |v23|, s4
	s_nop 1
	v_cndmask_b32_e32 v97, v97, v96, vcc
	s_brev_b32 s4, -2
	v_bfi_b32 v23, s4, v97, v23
	v_add_f32_e64 v92, |v24|, |v24|
	v_mul_f32_e32 v93, 0x3fb8aa3b, v92
	v_rndne_f32_e32 v94, v93
	s_mov_b32 s4, 0x3fb8aa3b
	v_sub_f32_e32 v95, v93, v94
	v_fma_f32 v93, v92, s4, -v93
	v_fmac_f32_e32 v93, 0x32a5705f, v92
	v_add_f32_e32 v93, v95, v93
	v_cvt_i32_f32_e32 v94, v94
	v_exp_f32_e32 v93, v93
	s_mov_b32 s4, 0xc2ce8ed0
	v_cmp_ngt_f32_e32 vcc, s4, v92
	s_mov_b32 s4, 0x42b17218
	v_ldexp_f32 v93, v93, v94
	s_nop 0
	v_cndmask_b32_e32 v93, 0, v93, vcc
	v_cmp_nlt_f32_e32 vcc, s4, v92
	s_nop 1
	v_cndmask_b32_e32 v92, v134, v93, vcc
	v_add_f32_e32 v92, 1.0, v92
	v_rcp_f32_e32 v92, v92
	s_nop 0
	v_fma_f32 v96, v92, -2.0, 1.0
	v_mul_f32_e32 v98, v24, v24
	v_fmamk_f32 v97, v98, 0xbbbac73d, v131
	v_fmaak_f32 v97, v98, v97, 0xbd5c1c4e
	v_fmaak_f32 v97, v98, v97, 0x3e088382
	v_fmaak_f32 v97, v98, v97, 0xbeaaaa99
	v_mul_f32_e64 v97, |v24|, v97
	v_fma_f32 v97, v98, v97, |v24|
	s_mov_b32 s4, 0x3f200000
	v_cmp_nlt_f32_e64 vcc, |v24|, s4
	s_nop 1
	v_cndmask_b32_e32 v97, v97, v96, vcc
	s_brev_b32 s4, -2
	v_bfi_b32 v24, s4, v97, v24
	s_waitcnt vmcnt(12)
	v_mul_f32_e32 v0, v30, v0
	v_mul_f32_e32 v1, v31, v1
	v_mul_f32_e32 v2, v32, v2
	v_mul_f32_e32 v3, v33, v3
	v_mul_f32_e32 v92, v0, v0
	v_mul_f32_e32 v93, v2, v2
	v_fmac_f32_e32 v92, v1, v1
	v_fmac_f32_e32 v93, v3, v3
	v_add_f32_e32 v92, v92, v93
	s_nop 1
	v_add_f32_dpp v92, v92, v92 quad_perm:[1,0,3,2] row_mask:0xf bank_mask:0xf bound_ctrl:1
	s_nop 1
	v_add_f32_dpp v92, v92, v92 quad_perm:[2,3,0,1] row_mask:0xf bank_mask:0xf bound_ctrl:1
	s_nop 1
	v_add_f32_dpp v92, v92, v92 row_half_mirror row_mask:0xf bank_mask:0xf bound_ctrl:1
	s_nop 1
	v_add_f32_dpp v92, v92, v92 row_mirror row_mask:0xf bank_mask:0xf bound_ctrl:1
	v_add_f32_e32 v92, 0x358637bd, v92
	v_rsq_f32_e32 v92, v92
	s_nop 0
	v_mul_f32_e32 v0, v0, v92
	v_mul_f32_e32 v1, v1, v92
	v_mul_f32_e32 v2, v2, v92
	v_mul_f32_e32 v3, v3, v92
	v_mul_f32_e32 v4, v30, v4
	v_mul_f32_e32 v5, v31, v5
	v_mul_f32_e32 v6, v32, v6
	v_mul_f32_e32 v7, v33, v7
	v_mul_f32_e32 v92, v4, v4
	v_mul_f32_e32 v93, v6, v6
	v_fmac_f32_e32 v92, v5, v5
	v_fmac_f32_e32 v93, v7, v7
	v_add_f32_e32 v92, v92, v93
	s_nop 1
	v_add_f32_dpp v92, v92, v92 quad_perm:[1,0,3,2] row_mask:0xf bank_mask:0xf bound_ctrl:1
	s_nop 1
	v_add_f32_dpp v92, v92, v92 quad_perm:[2,3,0,1] row_mask:0xf bank_mask:0xf bound_ctrl:1
	s_nop 1
	v_add_f32_dpp v92, v92, v92 row_half_mirror row_mask:0xf bank_mask:0xf bound_ctrl:1
	s_nop 1
	v_add_f32_dpp v92, v92, v92 row_mirror row_mask:0xf bank_mask:0xf bound_ctrl:1
	v_add_f32_e32 v92, 0x358637bd, v92
	v_rsq_f32_e32 v92, v92
	s_nop 0
	v_mul_f32_e32 v4, v4, v92
	v_mul_f32_e32 v5, v5, v92
	v_mul_f32_e32 v6, v6, v92
	v_mul_f32_e32 v7, v7, v92
	v_mul_f32_e32 v8, v30, v8
	v_mul_f32_e32 v9, v31, v9
	v_mul_f32_e32 v10, v32, v10
	v_mul_f32_e32 v11, v33, v11
	v_mul_f32_e32 v92, v8, v8
	v_mul_f32_e32 v93, v10, v10
	v_fmac_f32_e32 v92, v9, v9
	v_fmac_f32_e32 v93, v11, v11
	v_add_f32_e32 v92, v92, v93
	s_nop 1
	v_add_f32_dpp v92, v92, v92 quad_perm:[1,0,3,2] row_mask:0xf bank_mask:0xf bound_ctrl:1
	s_nop 1
	v_add_f32_dpp v92, v92, v92 quad_perm:[2,3,0,1] row_mask:0xf bank_mask:0xf bound_ctrl:1
	s_nop 1
	v_add_f32_dpp v92, v92, v92 row_half_mirror row_mask:0xf bank_mask:0xf bound_ctrl:1
	s_nop 1
	v_add_f32_dpp v92, v92, v92 row_mirror row_mask:0xf bank_mask:0xf bound_ctrl:1
	v_add_f32_e32 v92, 0x358637bd, v92
	v_rsq_f32_e32 v92, v92
	s_nop 0
	v_mul_f32_e32 v8, v8, v92
	v_mul_f32_e32 v9, v9, v92
	v_mul_f32_e32 v10, v10, v92
	v_mul_f32_e32 v11, v11, v92
	v_mul_f32_e32 v12, v30, v12
	v_mul_f32_e32 v13, v31, v13
	v_mul_f32_e32 v14, v32, v14
	v_mul_f32_e32 v15, v33, v15
	v_mul_f32_e32 v92, v12, v12
	v_mul_f32_e32 v93, v14, v14
	v_fmac_f32_e32 v92, v13, v13
	v_fmac_f32_e32 v93, v15, v15
	v_add_f32_e32 v92, v92, v93
	s_nop 1
	v_add_f32_dpp v92, v92, v92 quad_perm:[1,0,3,2] row_mask:0xf bank_mask:0xf bound_ctrl:1
	s_nop 1
	v_add_f32_dpp v92, v92, v92 quad_perm:[2,3,0,1] row_mask:0xf bank_mask:0xf bound_ctrl:1
	s_nop 1
	v_add_f32_dpp v92, v92, v92 row_half_mirror row_mask:0xf bank_mask:0xf bound_ctrl:1
	s_nop 1
	v_add_f32_dpp v92, v92, v92 row_mirror row_mask:0xf bank_mask:0xf bound_ctrl:1
	v_add_f32_e32 v92, 0x358637bd, v92
	v_rsq_f32_e32 v92, v92
	s_nop 0
	v_mul_f32_e32 v12, v12, v92
	v_mul_f32_e32 v13, v13, v92
	v_mul_f32_e32 v14, v14, v92
	v_mul_f32_e32 v15, v15, v92
	v_mul_f32_e32 v16, v30, v16
	v_mul_f32_e32 v17, v31, v17
	v_mul_f32_e32 v18, v32, v18
	v_mul_f32_e32 v19, v33, v19
	v_mul_f32_e32 v92, v16, v16
	v_mul_f32_e32 v93, v18, v18
	v_fmac_f32_e32 v92, v17, v17
	v_fmac_f32_e32 v93, v19, v19
	v_add_f32_e32 v92, v92, v93
	s_nop 1
	v_add_f32_dpp v92, v92, v92 quad_perm:[1,0,3,2] row_mask:0xf bank_mask:0xf bound_ctrl:1
	s_nop 1
	v_add_f32_dpp v92, v92, v92 quad_perm:[2,3,0,1] row_mask:0xf bank_mask:0xf bound_ctrl:1
	s_nop 1
	v_add_f32_dpp v92, v92, v92 row_half_mirror row_mask:0xf bank_mask:0xf bound_ctrl:1
	s_nop 1
	v_add_f32_dpp v92, v92, v92 row_mirror row_mask:0xf bank_mask:0xf bound_ctrl:1
	v_add_f32_e32 v92, 0x358637bd, v92
	v_rsq_f32_e32 v92, v92
	s_nop 0
	v_mul_f32_e32 v16, v16, v92
	v_mul_f32_e32 v17, v17, v92
	v_mul_f32_e32 v18, v18, v92
	v_mul_f32_e32 v19, v19, v92
	v_mov_b32_e32 v52, v34
	v_mov_b32_e32 v56, v42
	v_mov_b32_e32 v53, v35
	v_mov_b32_e32 v57, v43
	v_mov_b32_e32 v54, v36
	v_mov_b32_e32 v58, v44
	v_mov_b32_e32 v55, v37
	v_mov_b32_e32 v59, v45
	v_mov_b32_e32 v60, v34
	v_mov_b32_e32 v64, v42
	v_mov_b32_e32 v61, v35
	v_mov_b32_e32 v65, v43
	v_mov_b32_e32 v62, v36
	v_mov_b32_e32 v66, v44
	v_mov_b32_e32 v63, v37
	v_mov_b32_e32 v67, v45
	v_mov_b32_e32 v68, v34
	v_mov_b32_e32 v72, v42
	v_mov_b32_e32 v69, v35
	v_mov_b32_e32 v73, v43
	v_mov_b32_e32 v70, v36
	v_mov_b32_e32 v74, v44
	v_mov_b32_e32 v71, v37
	v_mov_b32_e32 v75, v45
	v_mov_b32_e32 v76, v34
	v_mov_b32_e32 v80, v42
	v_mov_b32_e32 v77, v35
	v_mov_b32_e32 v81, v43
	v_mov_b32_e32 v78, v36
	v_mov_b32_e32 v82, v44
	v_mov_b32_e32 v79, v37
	v_mov_b32_e32 v83, v45
	v_mov_b32_e32 v84, v34
	v_mov_b32_e32 v88, v42
	v_mov_b32_e32 v85, v35
	v_mov_b32_e32 v89, v43
	v_mov_b32_e32 v86, v36
	v_mov_b32_e32 v90, v44
	v_mov_b32_e32 v87, v37
	v_mov_b32_e32 v91, v45
	global_load_dwordx4 v[216:219], v232, s[2:3] offset:2048
	global_load_dwordx4 v[220:223], v232, s[40:41] offset:2048
	s_waitcnt vmcnt(12)
	v_readlane_b32 s48, v20, 0
	v_readlane_b32 s58, v25, 0
	v_readlane_b32 s50, v21, 0
	v_readlane_b32 s60, v26, 0
	v_readlane_b32 s52, v22, 0
	v_readlane_b32 s62, v27, 0
	v_readlane_b32 s54, v23, 0
	v_readlane_b32 s64, v28, 0
	v_readlane_b32 s56, v24, 0
	v_readlane_b32 s66, v29, 0
	v_pk_fma_f32 v[52:53], v[168:169], s[48:49], v[52:53] op_sel_hi:[1,0,1]
	v_pk_fma_f32 v[54:55], v[170:171], s[48:49], v[54:55] op_sel_hi:[1,0,1]
	v_pk_fma_f32 v[56:57], v[172:173], s[58:59], v[56:57] op_sel_hi:[1,0,1]
	v_pk_fma_f32 v[58:59], v[174:175], s[58:59], v[58:59] op_sel_hi:[1,0,1]
	v_pk_fma_f32 v[60:61], v[168:169], s[50:51], v[60:61] op_sel_hi:[1,0,1]
	v_pk_fma_f32 v[62:63], v[170:171], s[50:51], v[62:63] op_sel_hi:[1,0,1]
	v_pk_fma_f32 v[64:65], v[172:173], s[60:61], v[64:65] op_sel_hi:[1,0,1]
	v_pk_fma_f32 v[66:67], v[174:175], s[60:61], v[66:67] op_sel_hi:[1,0,1]
	v_pk_fma_f32 v[68:69], v[168:169], s[52:53], v[68:69] op_sel_hi:[1,0,1]
	v_pk_fma_f32 v[70:71], v[170:171], s[52:53], v[70:71] op_sel_hi:[1,0,1]
	v_pk_fma_f32 v[72:73], v[172:173], s[62:63], v[72:73] op_sel_hi:[1,0,1]
	v_pk_fma_f32 v[74:75], v[174:175], s[62:63], v[74:75] op_sel_hi:[1,0,1]
	v_pk_fma_f32 v[76:77], v[168:169], s[54:55], v[76:77] op_sel_hi:[1,0,1]
	v_pk_fma_f32 v[78:79], v[170:171], s[54:55], v[78:79] op_sel_hi:[1,0,1]
	v_pk_fma_f32 v[80:81], v[172:173], s[64:65], v[80:81] op_sel_hi:[1,0,1]
	v_pk_fma_f32 v[82:83], v[174:175], s[64:65], v[82:83] op_sel_hi:[1,0,1]
	v_pk_fma_f32 v[84:85], v[168:169], s[56:57], v[84:85] op_sel_hi:[1,0,1]
	v_pk_fma_f32 v[86:87], v[170:171], s[56:57], v[86:87] op_sel_hi:[1,0,1]
	v_pk_fma_f32 v[88:89], v[172:173], s[66:67], v[88:89] op_sel_hi:[1,0,1]
	v_pk_fma_f32 v[90:91], v[174:175], s[66:67], v[90:91] op_sel_hi:[1,0,1]
	global_load_dwordx4 v[224:227], v232, s[2:3] offset:3072
	global_load_dwordx4 v[228:231], v232, s[40:41] offset:3072
	s_add_u32 s2, s2, 0x1000
	s_addc_u32 s3, s3, 0
	s_add_u32 s40, s40, 0x1000
	s_addc_u32 s41, s41, 0
	s_waitcnt vmcnt(12)
	v_readlane_b32 s48, v20, 1
	v_readlane_b32 s58, v25, 1
	v_readlane_b32 s50, v21, 1
	v_readlane_b32 s60, v26, 1
	v_readlane_b32 s52, v22, 1
	v_readlane_b32 s62, v27, 1
	v_readlane_b32 s54, v23, 1
	v_readlane_b32 s64, v28, 1
	v_readlane_b32 s56, v24, 1
	v_readlane_b32 s66, v29, 1
	v_pk_fma_f32 v[52:53], v[176:177], s[48:49], v[52:53] op_sel_hi:[1,0,1]
	v_pk_fma_f32 v[54:55], v[178:179], s[48:49], v[54:55] op_sel_hi:[1,0,1]
	v_pk_fma_f32 v[56:57], v[180:181], s[58:59], v[56:57] op_sel_hi:[1,0,1]
	v_pk_fma_f32 v[58:59], v[182:183], s[58:59], v[58:59] op_sel_hi:[1,0,1]
	v_pk_fma_f32 v[60:61], v[176:177], s[50:51], v[60:61] op_sel_hi:[1,0,1]
	v_pk_fma_f32 v[62:63], v[178:179], s[50:51], v[62:63] op_sel_hi:[1,0,1]
	v_pk_fma_f32 v[64:65], v[180:181], s[60:61], v[64:65] op_sel_hi:[1,0,1]
	v_pk_fma_f32 v[66:67], v[182:183], s[60:61], v[66:67] op_sel_hi:[1,0,1]
	v_pk_fma_f32 v[68:69], v[176:177], s[52:53], v[68:69] op_sel_hi:[1,0,1]
	v_pk_fma_f32 v[70:71], v[178:179], s[52:53], v[70:71] op_sel_hi:[1,0,1]
	v_pk_fma_f32 v[72:73], v[180:181], s[62:63], v[72:73] op_sel_hi:[1,0,1]
	v_pk_fma_f32 v[74:75], v[182:183], s[62:63], v[74:75] op_sel_hi:[1,0,1]
	v_pk_fma_f32 v[76:77], v[176:177], s[54:55], v[76:77] op_sel_hi:[1,0,1]
	v_pk_fma_f32 v[78:79], v[178:179], s[54:55], v[78:79] op_sel_hi:[1,0,1]
	v_pk_fma_f32 v[80:81], v[180:181], s[64:65], v[80:81] op_sel_hi:[1,0,1]
	v_pk_fma_f32 v[82:83], v[182:183], s[64:65], v[82:83] op_sel_hi:[1,0,1]
	v_pk_fma_f32 v[84:85], v[176:177], s[56:57], v[84:85] op_sel_hi:[1,0,1]
	v_pk_fma_f32 v[86:87], v[178:179], s[56:57], v[86:87] op_sel_hi:[1,0,1]
	v_pk_fma_f32 v[88:89], v[180:181], s[66:67], v[88:89] op_sel_hi:[1,0,1]
	v_pk_fma_f32 v[90:91], v[182:183], s[66:67], v[90:91] op_sel_hi:[1,0,1]
	global_load_dwordx4 v[168:171], v232, s[2:3]
	global_load_dwordx4 v[172:175], v232, s[40:41]
	s_waitcnt vmcnt(12)
	v_readlane_b32 s48, v20, 2
	v_readlane_b32 s58, v25, 2
	v_readlane_b32 s50, v21, 2
	v_readlane_b32 s60, v26, 2
	v_readlane_b32 s52, v22, 2
	v_readlane_b32 s62, v27, 2
	v_readlane_b32 s54, v23, 2
	v_readlane_b32 s64, v28, 2
	v_readlane_b32 s56, v24, 2
	v_readlane_b32 s66, v29, 2
	v_pk_fma_f32 v[52:53], v[184:185], s[48:49], v[52:53] op_sel_hi:[1,0,1]
	v_pk_fma_f32 v[54:55], v[186:187], s[48:49], v[54:55] op_sel_hi:[1,0,1]
	v_pk_fma_f32 v[56:57], v[188:189], s[58:59], v[56:57] op_sel_hi:[1,0,1]
	v_pk_fma_f32 v[58:59], v[190:191], s[58:59], v[58:59] op_sel_hi:[1,0,1]
	v_pk_fma_f32 v[60:61], v[184:185], s[50:51], v[60:61] op_sel_hi:[1,0,1]
	v_pk_fma_f32 v[62:63], v[186:187], s[50:51], v[62:63] op_sel_hi:[1,0,1]
	v_pk_fma_f32 v[64:65], v[188:189], s[60:61], v[64:65] op_sel_hi:[1,0,1]
	v_pk_fma_f32 v[66:67], v[190:191], s[60:61], v[66:67] op_sel_hi:[1,0,1]
	v_pk_fma_f32 v[68:69], v[184:185], s[52:53], v[68:69] op_sel_hi:[1,0,1]
	v_pk_fma_f32 v[70:71], v[186:187], s[52:53], v[70:71] op_sel_hi:[1,0,1]
	v_pk_fma_f32 v[72:73], v[188:189], s[62:63], v[72:73] op_sel_hi:[1,0,1]
	v_pk_fma_f32 v[74:75], v[190:191], s[62:63], v[74:75] op_sel_hi:[1,0,1]
	v_pk_fma_f32 v[76:77], v[184:185], s[54:55], v[76:77] op_sel_hi:[1,0,1]
	v_pk_fma_f32 v[78:79], v[186:187], s[54:55], v[78:79] op_sel_hi:[1,0,1]
	v_pk_fma_f32 v[80:81], v[188:189], s[64:65], v[80:81] op_sel_hi:[1,0,1]
	v_pk_fma_f32 v[82:83], v[190:191], s[64:65], v[82:83] op_sel_hi:[1,0,1]
	v_pk_fma_f32 v[84:85], v[184:185], s[56:57], v[84:85] op_sel_hi:[1,0,1]
	v_pk_fma_f32 v[86:87], v[186:187], s[56:57], v[86:87] op_sel_hi:[1,0,1]
	v_pk_fma_f32 v[88:89], v[188:189], s[66:67], v[88:89] op_sel_hi:[1,0,1]
	v_pk_fma_f32 v[90:91], v[190:191], s[66:67], v[90:91] op_sel_hi:[1,0,1]
	global_load_dwordx4 v[176:179], v232, s[2:3] offset:1024
	global_load_dwordx4 v[180:183], v232, s[40:41] offset:1024
	s_waitcnt vmcnt(12)
	v_readlane_b32 s48, v20, 3
	v_readlane_b32 s58, v25, 3
	v_readlane_b32 s50, v21, 3
	v_readlane_b32 s60, v26, 3
	v_readlane_b32 s52, v22, 3
	v_readlane_b32 s62, v27, 3
	v_readlane_b32 s54, v23, 3
	v_readlane_b32 s64, v28, 3
	v_readlane_b32 s56, v24, 3
	v_readlane_b32 s66, v29, 3
	v_pk_fma_f32 v[52:53], v[192:193], s[48:49], v[52:53] op_sel_hi:[1,0,1]
	v_pk_fma_f32 v[54:55], v[194:195], s[48:49], v[54:55] op_sel_hi:[1,0,1]
	v_pk_fma_f32 v[56:57], v[196:197], s[58:59], v[56:57] op_sel_hi:[1,0,1]
	v_pk_fma_f32 v[58:59], v[198:199], s[58:59], v[58:59] op_sel_hi:[1,0,1]
	v_pk_fma_f32 v[60:61], v[192:193], s[50:51], v[60:61] op_sel_hi:[1,0,1]
	v_pk_fma_f32 v[62:63], v[194:195], s[50:51], v[62:63] op_sel_hi:[1,0,1]
	v_pk_fma_f32 v[64:65], v[196:197], s[60:61], v[64:65] op_sel_hi:[1,0,1]
	v_pk_fma_f32 v[66:67], v[198:199], s[60:61], v[66:67] op_sel_hi:[1,0,1]
	v_pk_fma_f32 v[68:69], v[192:193], s[52:53], v[68:69] op_sel_hi:[1,0,1]
	v_pk_fma_f32 v[70:71], v[194:195], s[52:53], v[70:71] op_sel_hi:[1,0,1]
	v_pk_fma_f32 v[72:73], v[196:197], s[62:63], v[72:73] op_sel_hi:[1,0,1]
	v_pk_fma_f32 v[74:75], v[198:199], s[62:63], v[74:75] op_sel_hi:[1,0,1]
	v_pk_fma_f32 v[76:77], v[192:193], s[54:55], v[76:77] op_sel_hi:[1,0,1]
	v_pk_fma_f32 v[78:79], v[194:195], s[54:55], v[78:79] op_sel_hi:[1,0,1]
	v_pk_fma_f32 v[80:81], v[196:197], s[64:65], v[80:81] op_sel_hi:[1,0,1]
	v_pk_fma_f32 v[82:83], v[198:199], s[64:65], v[82:83] op_sel_hi:[1,0,1]
	v_pk_fma_f32 v[84:85], v[192:193], s[56:57], v[84:85] op_sel_hi:[1,0,1]
	v_pk_fma_f32 v[86:87], v[194:195], s[56:57], v[86:87] op_sel_hi:[1,0,1]
	v_pk_fma_f32 v[88:89], v[196:197], s[66:67], v[88:89] op_sel_hi:[1,0,1]
	v_pk_fma_f32 v[90:91], v[198:199], s[66:67], v[90:91] op_sel_hi:[1,0,1]
	global_load_dwordx4 v[184:187], v232, s[2:3] offset:2048
	global_load_dwordx4 v[188:191], v232, s[40:41] offset:2048
	s_waitcnt vmcnt(12)
	v_readlane_b32 s48, v20, 4
	v_readlane_b32 s58, v25, 4
	v_readlane_b32 s50, v21, 4
	v_readlane_b32 s60, v26, 4
	v_readlane_b32 s52, v22, 4
	v_readlane_b32 s62, v27, 4
	v_readlane_b32 s54, v23, 4
	v_readlane_b32 s64, v28, 4
	v_readlane_b32 s56, v24, 4
	v_readlane_b32 s66, v29, 4
	v_pk_fma_f32 v[52:53], v[200:201], s[48:49], v[52:53] op_sel_hi:[1,0,1]
	v_pk_fma_f32 v[54:55], v[202:203], s[48:49], v[54:55] op_sel_hi:[1,0,1]
	v_pk_fma_f32 v[56:57], v[204:205], s[58:59], v[56:57] op_sel_hi:[1,0,1]
	v_pk_fma_f32 v[58:59], v[206:207], s[58:59], v[58:59] op_sel_hi:[1,0,1]
	v_pk_fma_f32 v[60:61], v[200:201], s[50:51], v[60:61] op_sel_hi:[1,0,1]
	v_pk_fma_f32 v[62:63], v[202:203], s[50:51], v[62:63] op_sel_hi:[1,0,1]
	v_pk_fma_f32 v[64:65], v[204:205], s[60:61], v[64:65] op_sel_hi:[1,0,1]
	v_pk_fma_f32 v[66:67], v[206:207], s[60:61], v[66:67] op_sel_hi:[1,0,1]
	v_pk_fma_f32 v[68:69], v[200:201], s[52:53], v[68:69] op_sel_hi:[1,0,1]
	v_pk_fma_f32 v[70:71], v[202:203], s[52:53], v[70:71] op_sel_hi:[1,0,1]
	v_pk_fma_f32 v[72:73], v[204:205], s[62:63], v[72:73] op_sel_hi:[1,0,1]
	v_pk_fma_f32 v[74:75], v[206:207], s[62:63], v[74:75] op_sel_hi:[1,0,1]
	v_pk_fma_f32 v[76:77], v[200:201], s[54:55], v[76:77] op_sel_hi:[1,0,1]
	v_pk_fma_f32 v[78:79], v[202:203], s[54:55], v[78:79] op_sel_hi:[1,0,1]
	v_pk_fma_f32 v[80:81], v[204:205], s[64:65], v[80:81] op_sel_hi:[1,0,1]
	v_pk_fma_f32 v[82:83], v[206:207], s[64:65], v[82:83] op_sel_hi:[1,0,1]
	v_pk_fma_f32 v[84:85], v[200:201], s[56:57], v[84:85] op_sel_hi:[1,0,1]
	v_pk_fma_f32 v[86:87], v[202:203], s[56:57], v[86:87] op_sel_hi:[1,0,1]
	v_pk_fma_f32 v[88:89], v[204:205], s[66:67], v[88:89] op_sel_hi:[1,0,1]
	v_pk_fma_f32 v[90:91], v[206:207], s[66:67], v[90:91] op_sel_hi:[1,0,1]
	global_load_dwordx4 v[192:195], v232, s[2:3] offset:3072
	global_load_dwordx4 v[196:199], v232, s[40:41] offset:3072
	s_add_u32 s2, s2, 0x1000
	s_addc_u32 s3, s3, 0
	s_add_u32 s40, s40, 0x1000
	s_addc_u32 s41, s41, 0
	s_waitcnt vmcnt(12)
	v_readlane_b32 s48, v20, 5
	v_readlane_b32 s58, v25, 5
	v_readlane_b32 s50, v21, 5
	v_readlane_b32 s60, v26, 5
	v_readlane_b32 s52, v22, 5
	v_readlane_b32 s62, v27, 5
	v_readlane_b32 s54, v23, 5
	v_readlane_b32 s64, v28, 5
	v_readlane_b32 s56, v24, 5
	v_readlane_b32 s66, v29, 5
	v_pk_fma_f32 v[52:53], v[208:209], s[48:49], v[52:53] op_sel_hi:[1,0,1]
	v_pk_fma_f32 v[54:55], v[210:211], s[48:49], v[54:55] op_sel_hi:[1,0,1]
	v_pk_fma_f32 v[56:57], v[212:213], s[58:59], v[56:57] op_sel_hi:[1,0,1]
	v_pk_fma_f32 v[58:59], v[214:215], s[58:59], v[58:59] op_sel_hi:[1,0,1]
	v_pk_fma_f32 v[60:61], v[208:209], s[50:51], v[60:61] op_sel_hi:[1,0,1]
	v_pk_fma_f32 v[62:63], v[210:211], s[50:51], v[62:63] op_sel_hi:[1,0,1]
	v_pk_fma_f32 v[64:65], v[212:213], s[60:61], v[64:65] op_sel_hi:[1,0,1]
	v_pk_fma_f32 v[66:67], v[214:215], s[60:61], v[66:67] op_sel_hi:[1,0,1]
	v_pk_fma_f32 v[68:69], v[208:209], s[52:53], v[68:69] op_sel_hi:[1,0,1]
	v_pk_fma_f32 v[70:71], v[210:211], s[52:53], v[70:71] op_sel_hi:[1,0,1]
	v_pk_fma_f32 v[72:73], v[212:213], s[62:63], v[72:73] op_sel_hi:[1,0,1]
	v_pk_fma_f32 v[74:75], v[214:215], s[62:63], v[74:75] op_sel_hi:[1,0,1]
	v_pk_fma_f32 v[76:77], v[208:209], s[54:55], v[76:77] op_sel_hi:[1,0,1]
	v_pk_fma_f32 v[78:79], v[210:211], s[54:55], v[78:79] op_sel_hi:[1,0,1]
	v_pk_fma_f32 v[80:81], v[212:213], s[64:65], v[80:81] op_sel_hi:[1,0,1]
	v_pk_fma_f32 v[82:83], v[214:215], s[64:65], v[82:83] op_sel_hi:[1,0,1]
	v_pk_fma_f32 v[84:85], v[208:209], s[56:57], v[84:85] op_sel_hi:[1,0,1]
	v_pk_fma_f32 v[86:87], v[210:211], s[56:57], v[86:87] op_sel_hi:[1,0,1]
	v_pk_fma_f32 v[88:89], v[212:213], s[66:67], v[88:89] op_sel_hi:[1,0,1]
	v_pk_fma_f32 v[90:91], v[214:215], s[66:67], v[90:91] op_sel_hi:[1,0,1]
	global_load_dwordx4 v[200:203], v232, s[2:3]
	global_load_dwordx4 v[204:207], v232, s[40:41]
	s_waitcnt vmcnt(12)
	v_readlane_b32 s48, v20, 6
	v_readlane_b32 s58, v25, 6
	v_readlane_b32 s50, v21, 6
	v_readlane_b32 s60, v26, 6
	v_readlane_b32 s52, v22, 6
	v_readlane_b32 s62, v27, 6
	v_readlane_b32 s54, v23, 6
	v_readlane_b32 s64, v28, 6
	v_readlane_b32 s56, v24, 6
	v_readlane_b32 s66, v29, 6
	v_pk_fma_f32 v[52:53], v[216:217], s[48:49], v[52:53] op_sel_hi:[1,0,1]
	v_pk_fma_f32 v[54:55], v[218:219], s[48:49], v[54:55] op_sel_hi:[1,0,1]
	v_pk_fma_f32 v[56:57], v[220:221], s[58:59], v[56:57] op_sel_hi:[1,0,1]
	v_pk_fma_f32 v[58:59], v[222:223], s[58:59], v[58:59] op_sel_hi:[1,0,1]
	v_pk_fma_f32 v[60:61], v[216:217], s[50:51], v[60:61] op_sel_hi:[1,0,1]
	v_pk_fma_f32 v[62:63], v[218:219], s[50:51], v[62:63] op_sel_hi:[1,0,1]
	v_pk_fma_f32 v[64:65], v[220:221], s[60:61], v[64:65] op_sel_hi:[1,0,1]
	v_pk_fma_f32 v[66:67], v[222:223], s[60:61], v[66:67] op_sel_hi:[1,0,1]
	v_pk_fma_f32 v[68:69], v[216:217], s[52:53], v[68:69] op_sel_hi:[1,0,1]
	v_pk_fma_f32 v[70:71], v[218:219], s[52:53], v[70:71] op_sel_hi:[1,0,1]
	v_pk_fma_f32 v[72:73], v[220:221], s[62:63], v[72:73] op_sel_hi:[1,0,1]
	v_pk_fma_f32 v[74:75], v[222:223], s[62:63], v[74:75] op_sel_hi:[1,0,1]
	v_pk_fma_f32 v[76:77], v[216:217], s[54:55], v[76:77] op_sel_hi:[1,0,1]
	v_pk_fma_f32 v[78:79], v[218:219], s[54:55], v[78:79] op_sel_hi:[1,0,1]
	v_pk_fma_f32 v[80:81], v[220:221], s[64:65], v[80:81] op_sel_hi:[1,0,1]
	v_pk_fma_f32 v[82:83], v[222:223], s[64:65], v[82:83] op_sel_hi:[1,0,1]
	v_pk_fma_f32 v[84:85], v[216:217], s[56:57], v[84:85] op_sel_hi:[1,0,1]
	v_pk_fma_f32 v[86:87], v[218:219], s[56:57], v[86:87] op_sel_hi:[1,0,1]
	v_pk_fma_f32 v[88:89], v[220:221], s[66:67], v[88:89] op_sel_hi:[1,0,1]
	v_pk_fma_f32 v[90:91], v[222:223], s[66:67], v[90:91] op_sel_hi:[1,0,1]
	global_load_dwordx4 v[208:211], v232, s[2:3] offset:1024
	global_load_dwordx4 v[212:215], v232, s[40:41] offset:1024
	s_waitcnt vmcnt(12)
	v_readlane_b32 s48, v20, 7
	v_readlane_b32 s58, v25, 7
	v_readlane_b32 s50, v21, 7
	v_readlane_b32 s60, v26, 7
	v_readlane_b32 s52, v22, 7
	v_readlane_b32 s62, v27, 7
	v_readlane_b32 s54, v23, 7
	v_readlane_b32 s64, v28, 7
	v_readlane_b32 s56, v24, 7
	v_readlane_b32 s66, v29, 7
	v_pk_fma_f32 v[52:53], v[224:225], s[48:49], v[52:53] op_sel_hi:[1,0,1]
	v_pk_fma_f32 v[54:55], v[226:227], s[48:49], v[54:55] op_sel_hi:[1,0,1]
	v_pk_fma_f32 v[56:57], v[228:229], s[58:59], v[56:57] op_sel_hi:[1,0,1]
	v_pk_fma_f32 v[58:59], v[230:231], s[58:59], v[58:59] op_sel_hi:[1,0,1]
	v_pk_fma_f32 v[60:61], v[224:225], s[50:51], v[60:61] op_sel_hi:[1,0,1]
	v_pk_fma_f32 v[62:63], v[226:227], s[50:51], v[62:63] op_sel_hi:[1,0,1]
	v_pk_fma_f32 v[64:65], v[228:229], s[60:61], v[64:65] op_sel_hi:[1,0,1]
	v_pk_fma_f32 v[66:67], v[230:231], s[60:61], v[66:67] op_sel_hi:[1,0,1]
	v_pk_fma_f32 v[68:69], v[224:225], s[52:53], v[68:69] op_sel_hi:[1,0,1]
	v_pk_fma_f32 v[70:71], v[226:227], s[52:53], v[70:71] op_sel_hi:[1,0,1]
	v_pk_fma_f32 v[72:73], v[228:229], s[62:63], v[72:73] op_sel_hi:[1,0,1]
	v_pk_fma_f32 v[74:75], v[230:231], s[62:63], v[74:75] op_sel_hi:[1,0,1]
	v_pk_fma_f32 v[76:77], v[224:225], s[54:55], v[76:77] op_sel_hi:[1,0,1]
	v_pk_fma_f32 v[78:79], v[226:227], s[54:55], v[78:79] op_sel_hi:[1,0,1]
	v_pk_fma_f32 v[80:81], v[228:229], s[64:65], v[80:81] op_sel_hi:[1,0,1]
	v_pk_fma_f32 v[82:83], v[230:231], s[64:65], v[82:83] op_sel_hi:[1,0,1]
	v_pk_fma_f32 v[84:85], v[224:225], s[56:57], v[84:85] op_sel_hi:[1,0,1]
	v_pk_fma_f32 v[86:87], v[226:227], s[56:57], v[86:87] op_sel_hi:[1,0,1]
	v_pk_fma_f32 v[88:89], v[228:229], s[66:67], v[88:89] op_sel_hi:[1,0,1]
	v_pk_fma_f32 v[90:91], v[230:231], s[66:67], v[90:91] op_sel_hi:[1,0,1]
	global_load_dwordx4 v[216:219], v232, s[2:3] offset:2048
	global_load_dwordx4 v[220:223], v232, s[40:41] offset:2048
	s_waitcnt vmcnt(12)
	v_readlane_b32 s48, v20, 8
	v_readlane_b32 s58, v25, 8
	v_readlane_b32 s50, v21, 8
	v_readlane_b32 s60, v26, 8
	v_readlane_b32 s52, v22, 8
	v_readlane_b32 s62, v27, 8
	v_readlane_b32 s54, v23, 8
	v_readlane_b32 s64, v28, 8
	v_readlane_b32 s56, v24, 8
	v_readlane_b32 s66, v29, 8
	v_pk_fma_f32 v[52:53], v[168:169], s[48:49], v[52:53] op_sel_hi:[1,0,1]
	v_pk_fma_f32 v[54:55], v[170:171], s[48:49], v[54:55] op_sel_hi:[1,0,1]
	v_pk_fma_f32 v[56:57], v[172:173], s[58:59], v[56:57] op_sel_hi:[1,0,1]
	v_pk_fma_f32 v[58:59], v[174:175], s[58:59], v[58:59] op_sel_hi:[1,0,1]
	v_pk_fma_f32 v[60:61], v[168:169], s[50:51], v[60:61] op_sel_hi:[1,0,1]
	v_pk_fma_f32 v[62:63], v[170:171], s[50:51], v[62:63] op_sel_hi:[1,0,1]
	v_pk_fma_f32 v[64:65], v[172:173], s[60:61], v[64:65] op_sel_hi:[1,0,1]
	v_pk_fma_f32 v[66:67], v[174:175], s[60:61], v[66:67] op_sel_hi:[1,0,1]
	v_pk_fma_f32 v[68:69], v[168:169], s[52:53], v[68:69] op_sel_hi:[1,0,1]
	v_pk_fma_f32 v[70:71], v[170:171], s[52:53], v[70:71] op_sel_hi:[1,0,1]
	v_pk_fma_f32 v[72:73], v[172:173], s[62:63], v[72:73] op_sel_hi:[1,0,1]
	v_pk_fma_f32 v[74:75], v[174:175], s[62:63], v[74:75] op_sel_hi:[1,0,1]
	v_pk_fma_f32 v[76:77], v[168:169], s[54:55], v[76:77] op_sel_hi:[1,0,1]
	v_pk_fma_f32 v[78:79], v[170:171], s[54:55], v[78:79] op_sel_hi:[1,0,1]
	v_pk_fma_f32 v[80:81], v[172:173], s[64:65], v[80:81] op_sel_hi:[1,0,1]
	v_pk_fma_f32 v[82:83], v[174:175], s[64:65], v[82:83] op_sel_hi:[1,0,1]
	v_pk_fma_f32 v[84:85], v[168:169], s[56:57], v[84:85] op_sel_hi:[1,0,1]
	v_pk_fma_f32 v[86:87], v[170:171], s[56:57], v[86:87] op_sel_hi:[1,0,1]
	v_pk_fma_f32 v[88:89], v[172:173], s[66:67], v[88:89] op_sel_hi:[1,0,1]
	v_pk_fma_f32 v[90:91], v[174:175], s[66:67], v[90:91] op_sel_hi:[1,0,1]
	global_load_dwordx4 v[224:227], v232, s[2:3] offset:3072
	global_load_dwordx4 v[228:231], v232, s[40:41] offset:3072
	s_add_u32 s2, s2, 0x1000
	s_addc_u32 s3, s3, 0
	s_add_u32 s40, s40, 0x1000
	s_addc_u32 s41, s41, 0
	s_waitcnt vmcnt(12)
	v_readlane_b32 s48, v20, 9
	v_readlane_b32 s58, v25, 9
	v_readlane_b32 s50, v21, 9
	v_readlane_b32 s60, v26, 9
	v_readlane_b32 s52, v22, 9
	v_readlane_b32 s62, v27, 9
	v_readlane_b32 s54, v23, 9
	v_readlane_b32 s64, v28, 9
	v_readlane_b32 s56, v24, 9
	v_readlane_b32 s66, v29, 9
	v_pk_fma_f32 v[52:53], v[176:177], s[48:49], v[52:53] op_sel_hi:[1,0,1]
	v_pk_fma_f32 v[54:55], v[178:179], s[48:49], v[54:55] op_sel_hi:[1,0,1]
	v_pk_fma_f32 v[56:57], v[180:181], s[58:59], v[56:57] op_sel_hi:[1,0,1]
	v_pk_fma_f32 v[58:59], v[182:183], s[58:59], v[58:59] op_sel_hi:[1,0,1]
	v_pk_fma_f32 v[60:61], v[176:177], s[50:51], v[60:61] op_sel_hi:[1,0,1]
	v_pk_fma_f32 v[62:63], v[178:179], s[50:51], v[62:63] op_sel_hi:[1,0,1]
	v_pk_fma_f32 v[64:65], v[180:181], s[60:61], v[64:65] op_sel_hi:[1,0,1]
	v_pk_fma_f32 v[66:67], v[182:183], s[60:61], v[66:67] op_sel_hi:[1,0,1]
	v_pk_fma_f32 v[68:69], v[176:177], s[52:53], v[68:69] op_sel_hi:[1,0,1]
	v_pk_fma_f32 v[70:71], v[178:179], s[52:53], v[70:71] op_sel_hi:[1,0,1]
	v_pk_fma_f32 v[72:73], v[180:181], s[62:63], v[72:73] op_sel_hi:[1,0,1]
	v_pk_fma_f32 v[74:75], v[182:183], s[62:63], v[74:75] op_sel_hi:[1,0,1]
	v_pk_fma_f32 v[76:77], v[176:177], s[54:55], v[76:77] op_sel_hi:[1,0,1]
	v_pk_fma_f32 v[78:79], v[178:179], s[54:55], v[78:79] op_sel_hi:[1,0,1]
	v_pk_fma_f32 v[80:81], v[180:181], s[64:65], v[80:81] op_sel_hi:[1,0,1]
	v_pk_fma_f32 v[82:83], v[182:183], s[64:65], v[82:83] op_sel_hi:[1,0,1]
	v_pk_fma_f32 v[84:85], v[176:177], s[56:57], v[84:85] op_sel_hi:[1,0,1]
	v_pk_fma_f32 v[86:87], v[178:179], s[56:57], v[86:87] op_sel_hi:[1,0,1]
	v_pk_fma_f32 v[88:89], v[180:181], s[66:67], v[88:89] op_sel_hi:[1,0,1]
	v_pk_fma_f32 v[90:91], v[182:183], s[66:67], v[90:91] op_sel_hi:[1,0,1]
	global_load_dwordx4 v[168:171], v232, s[2:3]
	global_load_dwordx4 v[172:175], v232, s[40:41]
	s_waitcnt vmcnt(12)
	v_readlane_b32 s48, v20, 10
	v_readlane_b32 s58, v25, 10
	v_readlane_b32 s50, v21, 10
	v_readlane_b32 s60, v26, 10
	v_readlane_b32 s52, v22, 10
	v_readlane_b32 s62, v27, 10
	v_readlane_b32 s54, v23, 10
	v_readlane_b32 s64, v28, 10
	v_readlane_b32 s56, v24, 10
	v_readlane_b32 s66, v29, 10
	v_pk_fma_f32 v[52:53], v[184:185], s[48:49], v[52:53] op_sel_hi:[1,0,1]
	v_pk_fma_f32 v[54:55], v[186:187], s[48:49], v[54:55] op_sel_hi:[1,0,1]
	v_pk_fma_f32 v[56:57], v[188:189], s[58:59], v[56:57] op_sel_hi:[1,0,1]
	v_pk_fma_f32 v[58:59], v[190:191], s[58:59], v[58:59] op_sel_hi:[1,0,1]
	v_pk_fma_f32 v[60:61], v[184:185], s[50:51], v[60:61] op_sel_hi:[1,0,1]
	v_pk_fma_f32 v[62:63], v[186:187], s[50:51], v[62:63] op_sel_hi:[1,0,1]
	v_pk_fma_f32 v[64:65], v[188:189], s[60:61], v[64:65] op_sel_hi:[1,0,1]
	v_pk_fma_f32 v[66:67], v[190:191], s[60:61], v[66:67] op_sel_hi:[1,0,1]
	v_pk_fma_f32 v[68:69], v[184:185], s[52:53], v[68:69] op_sel_hi:[1,0,1]
	v_pk_fma_f32 v[70:71], v[186:187], s[52:53], v[70:71] op_sel_hi:[1,0,1]
	v_pk_fma_f32 v[72:73], v[188:189], s[62:63], v[72:73] op_sel_hi:[1,0,1]
	v_pk_fma_f32 v[74:75], v[190:191], s[62:63], v[74:75] op_sel_hi:[1,0,1]
	v_pk_fma_f32 v[76:77], v[184:185], s[54:55], v[76:77] op_sel_hi:[1,0,1]
	v_pk_fma_f32 v[78:79], v[186:187], s[54:55], v[78:79] op_sel_hi:[1,0,1]
	v_pk_fma_f32 v[80:81], v[188:189], s[64:65], v[80:81] op_sel_hi:[1,0,1]
	v_pk_fma_f32 v[82:83], v[190:191], s[64:65], v[82:83] op_sel_hi:[1,0,1]
	v_pk_fma_f32 v[84:85], v[184:185], s[56:57], v[84:85] op_sel_hi:[1,0,1]
	v_pk_fma_f32 v[86:87], v[186:187], s[56:57], v[86:87] op_sel_hi:[1,0,1]
	v_pk_fma_f32 v[88:89], v[188:189], s[66:67], v[88:89] op_sel_hi:[1,0,1]
	v_pk_fma_f32 v[90:91], v[190:191], s[66:67], v[90:91] op_sel_hi:[1,0,1]
	global_load_dwordx4 v[176:179], v232, s[2:3] offset:1024
	global_load_dwordx4 v[180:183], v232, s[40:41] offset:1024
	s_waitcnt vmcnt(12)
	v_readlane_b32 s48, v20, 11
	v_readlane_b32 s58, v25, 11
	v_readlane_b32 s50, v21, 11
	v_readlane_b32 s60, v26, 11
	v_readlane_b32 s52, v22, 11
	v_readlane_b32 s62, v27, 11
	v_readlane_b32 s54, v23, 11
	v_readlane_b32 s64, v28, 11
	v_readlane_b32 s56, v24, 11
	v_readlane_b32 s66, v29, 11
	v_pk_fma_f32 v[52:53], v[192:193], s[48:49], v[52:53] op_sel_hi:[1,0,1]
	v_pk_fma_f32 v[54:55], v[194:195], s[48:49], v[54:55] op_sel_hi:[1,0,1]
	v_pk_fma_f32 v[56:57], v[196:197], s[58:59], v[56:57] op_sel_hi:[1,0,1]
	v_pk_fma_f32 v[58:59], v[198:199], s[58:59], v[58:59] op_sel_hi:[1,0,1]
	v_pk_fma_f32 v[60:61], v[192:193], s[50:51], v[60:61] op_sel_hi:[1,0,1]
	v_pk_fma_f32 v[62:63], v[194:195], s[50:51], v[62:63] op_sel_hi:[1,0,1]
	v_pk_fma_f32 v[64:65], v[196:197], s[60:61], v[64:65] op_sel_hi:[1,0,1]
	v_pk_fma_f32 v[66:67], v[198:199], s[60:61], v[66:67] op_sel_hi:[1,0,1]
	v_pk_fma_f32 v[68:69], v[192:193], s[52:53], v[68:69] op_sel_hi:[1,0,1]
	v_pk_fma_f32 v[70:71], v[194:195], s[52:53], v[70:71] op_sel_hi:[1,0,1]
	v_pk_fma_f32 v[72:73], v[196:197], s[62:63], v[72:73] op_sel_hi:[1,0,1]
	v_pk_fma_f32 v[74:75], v[198:199], s[62:63], v[74:75] op_sel_hi:[1,0,1]
	v_pk_fma_f32 v[76:77], v[192:193], s[54:55], v[76:77] op_sel_hi:[1,0,1]
	v_pk_fma_f32 v[78:79], v[194:195], s[54:55], v[78:79] op_sel_hi:[1,0,1]
	v_pk_fma_f32 v[80:81], v[196:197], s[64:65], v[80:81] op_sel_hi:[1,0,1]
	v_pk_fma_f32 v[82:83], v[198:199], s[64:65], v[82:83] op_sel_hi:[1,0,1]
	v_pk_fma_f32 v[84:85], v[192:193], s[56:57], v[84:85] op_sel_hi:[1,0,1]
	v_pk_fma_f32 v[86:87], v[194:195], s[56:57], v[86:87] op_sel_hi:[1,0,1]
	v_pk_fma_f32 v[88:89], v[196:197], s[66:67], v[88:89] op_sel_hi:[1,0,1]
	v_pk_fma_f32 v[90:91], v[198:199], s[66:67], v[90:91] op_sel_hi:[1,0,1]
	global_load_dwordx4 v[184:187], v232, s[2:3] offset:2048
	global_load_dwordx4 v[188:191], v232, s[40:41] offset:2048
	s_waitcnt vmcnt(12)
	v_readlane_b32 s48, v20, 12
	v_readlane_b32 s58, v25, 12
	v_readlane_b32 s50, v21, 12
	v_readlane_b32 s60, v26, 12
	v_readlane_b32 s52, v22, 12
	v_readlane_b32 s62, v27, 12
	v_readlane_b32 s54, v23, 12
	v_readlane_b32 s64, v28, 12
	v_readlane_b32 s56, v24, 12
	v_readlane_b32 s66, v29, 12
	v_pk_fma_f32 v[52:53], v[200:201], s[48:49], v[52:53] op_sel_hi:[1,0,1]
	v_pk_fma_f32 v[54:55], v[202:203], s[48:49], v[54:55] op_sel_hi:[1,0,1]
	v_pk_fma_f32 v[56:57], v[204:205], s[58:59], v[56:57] op_sel_hi:[1,0,1]
	v_pk_fma_f32 v[58:59], v[206:207], s[58:59], v[58:59] op_sel_hi:[1,0,1]
	v_pk_fma_f32 v[60:61], v[200:201], s[50:51], v[60:61] op_sel_hi:[1,0,1]
	v_pk_fma_f32 v[62:63], v[202:203], s[50:51], v[62:63] op_sel_hi:[1,0,1]
	v_pk_fma_f32 v[64:65], v[204:205], s[60:61], v[64:65] op_sel_hi:[1,0,1]
	v_pk_fma_f32 v[66:67], v[206:207], s[60:61], v[66:67] op_sel_hi:[1,0,1]
	v_pk_fma_f32 v[68:69], v[200:201], s[52:53], v[68:69] op_sel_hi:[1,0,1]
	v_pk_fma_f32 v[70:71], v[202:203], s[52:53], v[70:71] op_sel_hi:[1,0,1]
	v_pk_fma_f32 v[72:73], v[204:205], s[62:63], v[72:73] op_sel_hi:[1,0,1]
	v_pk_fma_f32 v[74:75], v[206:207], s[62:63], v[74:75] op_sel_hi:[1,0,1]
	v_pk_fma_f32 v[76:77], v[200:201], s[54:55], v[76:77] op_sel_hi:[1,0,1]
	v_pk_fma_f32 v[78:79], v[202:203], s[54:55], v[78:79] op_sel_hi:[1,0,1]
	v_pk_fma_f32 v[80:81], v[204:205], s[64:65], v[80:81] op_sel_hi:[1,0,1]
	v_pk_fma_f32 v[82:83], v[206:207], s[64:65], v[82:83] op_sel_hi:[1,0,1]
	v_pk_fma_f32 v[84:85], v[200:201], s[56:57], v[84:85] op_sel_hi:[1,0,1]
	v_pk_fma_f32 v[86:87], v[202:203], s[56:57], v[86:87] op_sel_hi:[1,0,1]
	v_pk_fma_f32 v[88:89], v[204:205], s[66:67], v[88:89] op_sel_hi:[1,0,1]
	v_pk_fma_f32 v[90:91], v[206:207], s[66:67], v[90:91] op_sel_hi:[1,0,1]
	global_load_dwordx4 v[192:195], v232, s[2:3] offset:3072
	global_load_dwordx4 v[196:199], v232, s[40:41] offset:3072
	s_add_u32 s2, s2, 0x1000
	s_addc_u32 s3, s3, 0
	s_add_u32 s40, s40, 0x1000
	s_addc_u32 s41, s41, 0
	s_waitcnt vmcnt(12)
	v_readlane_b32 s48, v20, 13
	v_readlane_b32 s58, v25, 13
	v_readlane_b32 s50, v21, 13
	v_readlane_b32 s60, v26, 13
	v_readlane_b32 s52, v22, 13
	v_readlane_b32 s62, v27, 13
	v_readlane_b32 s54, v23, 13
	v_readlane_b32 s64, v28, 13
	v_readlane_b32 s56, v24, 13
	v_readlane_b32 s66, v29, 13
	v_pk_fma_f32 v[52:53], v[208:209], s[48:49], v[52:53] op_sel_hi:[1,0,1]
	v_pk_fma_f32 v[54:55], v[210:211], s[48:49], v[54:55] op_sel_hi:[1,0,1]
	v_pk_fma_f32 v[56:57], v[212:213], s[58:59], v[56:57] op_sel_hi:[1,0,1]
	v_pk_fma_f32 v[58:59], v[214:215], s[58:59], v[58:59] op_sel_hi:[1,0,1]
	v_pk_fma_f32 v[60:61], v[208:209], s[50:51], v[60:61] op_sel_hi:[1,0,1]
	v_pk_fma_f32 v[62:63], v[210:211], s[50:51], v[62:63] op_sel_hi:[1,0,1]
	v_pk_fma_f32 v[64:65], v[212:213], s[60:61], v[64:65] op_sel_hi:[1,0,1]
	v_pk_fma_f32 v[66:67], v[214:215], s[60:61], v[66:67] op_sel_hi:[1,0,1]
	v_pk_fma_f32 v[68:69], v[208:209], s[52:53], v[68:69] op_sel_hi:[1,0,1]
	v_pk_fma_f32 v[70:71], v[210:211], s[52:53], v[70:71] op_sel_hi:[1,0,1]
	v_pk_fma_f32 v[72:73], v[212:213], s[62:63], v[72:73] op_sel_hi:[1,0,1]
	v_pk_fma_f32 v[74:75], v[214:215], s[62:63], v[74:75] op_sel_hi:[1,0,1]
	v_pk_fma_f32 v[76:77], v[208:209], s[54:55], v[76:77] op_sel_hi:[1,0,1]
	v_pk_fma_f32 v[78:79], v[210:211], s[54:55], v[78:79] op_sel_hi:[1,0,1]
	v_pk_fma_f32 v[80:81], v[212:213], s[64:65], v[80:81] op_sel_hi:[1,0,1]
	v_pk_fma_f32 v[82:83], v[214:215], s[64:65], v[82:83] op_sel_hi:[1,0,1]
	v_pk_fma_f32 v[84:85], v[208:209], s[56:57], v[84:85] op_sel_hi:[1,0,1]
	v_pk_fma_f32 v[86:87], v[210:211], s[56:57], v[86:87] op_sel_hi:[1,0,1]
	v_pk_fma_f32 v[88:89], v[212:213], s[66:67], v[88:89] op_sel_hi:[1,0,1]
	v_pk_fma_f32 v[90:91], v[214:215], s[66:67], v[90:91] op_sel_hi:[1,0,1]
	global_load_dwordx4 v[200:203], v232, s[2:3]
	global_load_dwordx4 v[204:207], v232, s[40:41]
	s_waitcnt vmcnt(12)
	v_readlane_b32 s48, v20, 14
	v_readlane_b32 s58, v25, 14
	v_readlane_b32 s50, v21, 14
	v_readlane_b32 s60, v26, 14
	v_readlane_b32 s52, v22, 14
	v_readlane_b32 s62, v27, 14
	v_readlane_b32 s54, v23, 14
	v_readlane_b32 s64, v28, 14
	v_readlane_b32 s56, v24, 14
	v_readlane_b32 s66, v29, 14
	v_pk_fma_f32 v[52:53], v[216:217], s[48:49], v[52:53] op_sel_hi:[1,0,1]
	v_pk_fma_f32 v[54:55], v[218:219], s[48:49], v[54:55] op_sel_hi:[1,0,1]
	v_pk_fma_f32 v[56:57], v[220:221], s[58:59], v[56:57] op_sel_hi:[1,0,1]
	v_pk_fma_f32 v[58:59], v[222:223], s[58:59], v[58:59] op_sel_hi:[1,0,1]
	v_pk_fma_f32 v[60:61], v[216:217], s[50:51], v[60:61] op_sel_hi:[1,0,1]
	v_pk_fma_f32 v[62:63], v[218:219], s[50:51], v[62:63] op_sel_hi:[1,0,1]
	v_pk_fma_f32 v[64:65], v[220:221], s[60:61], v[64:65] op_sel_hi:[1,0,1]
	v_pk_fma_f32 v[66:67], v[222:223], s[60:61], v[66:67] op_sel_hi:[1,0,1]
	v_pk_fma_f32 v[68:69], v[216:217], s[52:53], v[68:69] op_sel_hi:[1,0,1]
	v_pk_fma_f32 v[70:71], v[218:219], s[52:53], v[70:71] op_sel_hi:[1,0,1]
	v_pk_fma_f32 v[72:73], v[220:221], s[62:63], v[72:73] op_sel_hi:[1,0,1]
	v_pk_fma_f32 v[74:75], v[222:223], s[62:63], v[74:75] op_sel_hi:[1,0,1]
	v_pk_fma_f32 v[76:77], v[216:217], s[54:55], v[76:77] op_sel_hi:[1,0,1]
	v_pk_fma_f32 v[78:79], v[218:219], s[54:55], v[78:79] op_sel_hi:[1,0,1]
	v_pk_fma_f32 v[80:81], v[220:221], s[64:65], v[80:81] op_sel_hi:[1,0,1]
	v_pk_fma_f32 v[82:83], v[222:223], s[64:65], v[82:83] op_sel_hi:[1,0,1]
	v_pk_fma_f32 v[84:85], v[216:217], s[56:57], v[84:85] op_sel_hi:[1,0,1]
	v_pk_fma_f32 v[86:87], v[218:219], s[56:57], v[86:87] op_sel_hi:[1,0,1]
	v_pk_fma_f32 v[88:89], v[220:221], s[66:67], v[88:89] op_sel_hi:[1,0,1]
	v_pk_fma_f32 v[90:91], v[222:223], s[66:67], v[90:91] op_sel_hi:[1,0,1]
	global_load_dwordx4 v[208:211], v232, s[2:3] offset:1024
	global_load_dwordx4 v[212:215], v232, s[40:41] offset:1024
	s_waitcnt vmcnt(12)
	v_readlane_b32 s48, v20, 15
	v_readlane_b32 s58, v25, 15
	v_readlane_b32 s50, v21, 15
	v_readlane_b32 s60, v26, 15
	v_readlane_b32 s52, v22, 15
	v_readlane_b32 s62, v27, 15
	v_readlane_b32 s54, v23, 15
	v_readlane_b32 s64, v28, 15
	v_readlane_b32 s56, v24, 15
	v_readlane_b32 s66, v29, 15
	v_pk_fma_f32 v[52:53], v[224:225], s[48:49], v[52:53] op_sel_hi:[1,0,1]
	v_pk_fma_f32 v[54:55], v[226:227], s[48:49], v[54:55] op_sel_hi:[1,0,1]
	v_pk_fma_f32 v[56:57], v[228:229], s[58:59], v[56:57] op_sel_hi:[1,0,1]
	v_pk_fma_f32 v[58:59], v[230:231], s[58:59], v[58:59] op_sel_hi:[1,0,1]
	v_pk_fma_f32 v[60:61], v[224:225], s[50:51], v[60:61] op_sel_hi:[1,0,1]
	v_pk_fma_f32 v[62:63], v[226:227], s[50:51], v[62:63] op_sel_hi:[1,0,1]
	v_pk_fma_f32 v[64:65], v[228:229], s[60:61], v[64:65] op_sel_hi:[1,0,1]
	v_pk_fma_f32 v[66:67], v[230:231], s[60:61], v[66:67] op_sel_hi:[1,0,1]
	v_pk_fma_f32 v[68:69], v[224:225], s[52:53], v[68:69] op_sel_hi:[1,0,1]
	v_pk_fma_f32 v[70:71], v[226:227], s[52:53], v[70:71] op_sel_hi:[1,0,1]
	v_pk_fma_f32 v[72:73], v[228:229], s[62:63], v[72:73] op_sel_hi:[1,0,1]
	v_pk_fma_f32 v[74:75], v[230:231], s[62:63], v[74:75] op_sel_hi:[1,0,1]
	v_pk_fma_f32 v[76:77], v[224:225], s[54:55], v[76:77] op_sel_hi:[1,0,1]
	v_pk_fma_f32 v[78:79], v[226:227], s[54:55], v[78:79] op_sel_hi:[1,0,1]
	v_pk_fma_f32 v[80:81], v[228:229], s[64:65], v[80:81] op_sel_hi:[1,0,1]
	v_pk_fma_f32 v[82:83], v[230:231], s[64:65], v[82:83] op_sel_hi:[1,0,1]
	v_pk_fma_f32 v[84:85], v[224:225], s[56:57], v[84:85] op_sel_hi:[1,0,1]
	v_pk_fma_f32 v[86:87], v[226:227], s[56:57], v[86:87] op_sel_hi:[1,0,1]
	v_pk_fma_f32 v[88:89], v[228:229], s[66:67], v[88:89] op_sel_hi:[1,0,1]
	v_pk_fma_f32 v[90:91], v[230:231], s[66:67], v[90:91] op_sel_hi:[1,0,1]
	global_load_dwordx4 v[216:219], v232, s[2:3] offset:2048
	global_load_dwordx4 v[220:223], v232, s[40:41] offset:2048
	s_waitcnt vmcnt(12)
	v_readlane_b32 s48, v20, 16
	v_readlane_b32 s58, v25, 16
	v_readlane_b32 s50, v21, 16
	v_readlane_b32 s60, v26, 16
	v_readlane_b32 s52, v22, 16
	v_readlane_b32 s62, v27, 16
	v_readlane_b32 s54, v23, 16
	v_readlane_b32 s64, v28, 16
	v_readlane_b32 s56, v24, 16
	v_readlane_b32 s66, v29, 16
	v_pk_fma_f32 v[52:53], v[168:169], s[48:49], v[52:53] op_sel_hi:[1,0,1]
	v_pk_fma_f32 v[54:55], v[170:171], s[48:49], v[54:55] op_sel_hi:[1,0,1]
	v_pk_fma_f32 v[56:57], v[172:173], s[58:59], v[56:57] op_sel_hi:[1,0,1]
	v_pk_fma_f32 v[58:59], v[174:175], s[58:59], v[58:59] op_sel_hi:[1,0,1]
	v_pk_fma_f32 v[60:61], v[168:169], s[50:51], v[60:61] op_sel_hi:[1,0,1]
	v_pk_fma_f32 v[62:63], v[170:171], s[50:51], v[62:63] op_sel_hi:[1,0,1]
	v_pk_fma_f32 v[64:65], v[172:173], s[60:61], v[64:65] op_sel_hi:[1,0,1]
	v_pk_fma_f32 v[66:67], v[174:175], s[60:61], v[66:67] op_sel_hi:[1,0,1]
	v_pk_fma_f32 v[68:69], v[168:169], s[52:53], v[68:69] op_sel_hi:[1,0,1]
	v_pk_fma_f32 v[70:71], v[170:171], s[52:53], v[70:71] op_sel_hi:[1,0,1]
	v_pk_fma_f32 v[72:73], v[172:173], s[62:63], v[72:73] op_sel_hi:[1,0,1]
	v_pk_fma_f32 v[74:75], v[174:175], s[62:63], v[74:75] op_sel_hi:[1,0,1]
	v_pk_fma_f32 v[76:77], v[168:169], s[54:55], v[76:77] op_sel_hi:[1,0,1]
	v_pk_fma_f32 v[78:79], v[170:171], s[54:55], v[78:79] op_sel_hi:[1,0,1]
	v_pk_fma_f32 v[80:81], v[172:173], s[64:65], v[80:81] op_sel_hi:[1,0,1]
	v_pk_fma_f32 v[82:83], v[174:175], s[64:65], v[82:83] op_sel_hi:[1,0,1]
	v_pk_fma_f32 v[84:85], v[168:169], s[56:57], v[84:85] op_sel_hi:[1,0,1]
	v_pk_fma_f32 v[86:87], v[170:171], s[56:57], v[86:87] op_sel_hi:[1,0,1]
	v_pk_fma_f32 v[88:89], v[172:173], s[66:67], v[88:89] op_sel_hi:[1,0,1]
	v_pk_fma_f32 v[90:91], v[174:175], s[66:67], v[90:91] op_sel_hi:[1,0,1]
	global_load_dwordx4 v[224:227], v232, s[2:3] offset:3072
	global_load_dwordx4 v[228:231], v232, s[40:41] offset:3072
	s_add_u32 s2, s2, 0x1000
	s_addc_u32 s3, s3, 0
	s_add_u32 s40, s40, 0x1000
	s_addc_u32 s41, s41, 0
	s_waitcnt vmcnt(12)
	v_readlane_b32 s48, v20, 17
	v_readlane_b32 s58, v25, 17
	v_readlane_b32 s50, v21, 17
	v_readlane_b32 s60, v26, 17
	v_readlane_b32 s52, v22, 17
	v_readlane_b32 s62, v27, 17
	v_readlane_b32 s54, v23, 17
	v_readlane_b32 s64, v28, 17
	v_readlane_b32 s56, v24, 17
	v_readlane_b32 s66, v29, 17
	v_pk_fma_f32 v[52:53], v[176:177], s[48:49], v[52:53] op_sel_hi:[1,0,1]
	v_pk_fma_f32 v[54:55], v[178:179], s[48:49], v[54:55] op_sel_hi:[1,0,1]
	v_pk_fma_f32 v[56:57], v[180:181], s[58:59], v[56:57] op_sel_hi:[1,0,1]
	v_pk_fma_f32 v[58:59], v[182:183], s[58:59], v[58:59] op_sel_hi:[1,0,1]
	v_pk_fma_f32 v[60:61], v[176:177], s[50:51], v[60:61] op_sel_hi:[1,0,1]
	v_pk_fma_f32 v[62:63], v[178:179], s[50:51], v[62:63] op_sel_hi:[1,0,1]
	v_pk_fma_f32 v[64:65], v[180:181], s[60:61], v[64:65] op_sel_hi:[1,0,1]
	v_pk_fma_f32 v[66:67], v[182:183], s[60:61], v[66:67] op_sel_hi:[1,0,1]
	v_pk_fma_f32 v[68:69], v[176:177], s[52:53], v[68:69] op_sel_hi:[1,0,1]
	v_pk_fma_f32 v[70:71], v[178:179], s[52:53], v[70:71] op_sel_hi:[1,0,1]
	v_pk_fma_f32 v[72:73], v[180:181], s[62:63], v[72:73] op_sel_hi:[1,0,1]
	v_pk_fma_f32 v[74:75], v[182:183], s[62:63], v[74:75] op_sel_hi:[1,0,1]
	v_pk_fma_f32 v[76:77], v[176:177], s[54:55], v[76:77] op_sel_hi:[1,0,1]
	v_pk_fma_f32 v[78:79], v[178:179], s[54:55], v[78:79] op_sel_hi:[1,0,1]
	v_pk_fma_f32 v[80:81], v[180:181], s[64:65], v[80:81] op_sel_hi:[1,0,1]
	v_pk_fma_f32 v[82:83], v[182:183], s[64:65], v[82:83] op_sel_hi:[1,0,1]
	v_pk_fma_f32 v[84:85], v[176:177], s[56:57], v[84:85] op_sel_hi:[1,0,1]
	v_pk_fma_f32 v[86:87], v[178:179], s[56:57], v[86:87] op_sel_hi:[1,0,1]
	v_pk_fma_f32 v[88:89], v[180:181], s[66:67], v[88:89] op_sel_hi:[1,0,1]
	v_pk_fma_f32 v[90:91], v[182:183], s[66:67], v[90:91] op_sel_hi:[1,0,1]
	global_load_dwordx4 v[168:171], v232, s[2:3]
	global_load_dwordx4 v[172:175], v232, s[40:41]
	s_waitcnt vmcnt(12)
	v_readlane_b32 s48, v20, 18
	v_readlane_b32 s58, v25, 18
	v_readlane_b32 s50, v21, 18
	v_readlane_b32 s60, v26, 18
	v_readlane_b32 s52, v22, 18
	v_readlane_b32 s62, v27, 18
	v_readlane_b32 s54, v23, 18
	v_readlane_b32 s64, v28, 18
	v_readlane_b32 s56, v24, 18
	v_readlane_b32 s66, v29, 18
	v_pk_fma_f32 v[52:53], v[184:185], s[48:49], v[52:53] op_sel_hi:[1,0,1]
	v_pk_fma_f32 v[54:55], v[186:187], s[48:49], v[54:55] op_sel_hi:[1,0,1]
	v_pk_fma_f32 v[56:57], v[188:189], s[58:59], v[56:57] op_sel_hi:[1,0,1]
	v_pk_fma_f32 v[58:59], v[190:191], s[58:59], v[58:59] op_sel_hi:[1,0,1]
	v_pk_fma_f32 v[60:61], v[184:185], s[50:51], v[60:61] op_sel_hi:[1,0,1]
	v_pk_fma_f32 v[62:63], v[186:187], s[50:51], v[62:63] op_sel_hi:[1,0,1]
	v_pk_fma_f32 v[64:65], v[188:189], s[60:61], v[64:65] op_sel_hi:[1,0,1]
	v_pk_fma_f32 v[66:67], v[190:191], s[60:61], v[66:67] op_sel_hi:[1,0,1]
	v_pk_fma_f32 v[68:69], v[184:185], s[52:53], v[68:69] op_sel_hi:[1,0,1]
	v_pk_fma_f32 v[70:71], v[186:187], s[52:53], v[70:71] op_sel_hi:[1,0,1]
	v_pk_fma_f32 v[72:73], v[188:189], s[62:63], v[72:73] op_sel_hi:[1,0,1]
	v_pk_fma_f32 v[74:75], v[190:191], s[62:63], v[74:75] op_sel_hi:[1,0,1]
	v_pk_fma_f32 v[76:77], v[184:185], s[54:55], v[76:77] op_sel_hi:[1,0,1]
	v_pk_fma_f32 v[78:79], v[186:187], s[54:55], v[78:79] op_sel_hi:[1,0,1]
	v_pk_fma_f32 v[80:81], v[188:189], s[64:65], v[80:81] op_sel_hi:[1,0,1]
	v_pk_fma_f32 v[82:83], v[190:191], s[64:65], v[82:83] op_sel_hi:[1,0,1]
	v_pk_fma_f32 v[84:85], v[184:185], s[56:57], v[84:85] op_sel_hi:[1,0,1]
	v_pk_fma_f32 v[86:87], v[186:187], s[56:57], v[86:87] op_sel_hi:[1,0,1]
	v_pk_fma_f32 v[88:89], v[188:189], s[66:67], v[88:89] op_sel_hi:[1,0,1]
	v_pk_fma_f32 v[90:91], v[190:191], s[66:67], v[90:91] op_sel_hi:[1,0,1]
	global_load_dwordx4 v[176:179], v232, s[2:3] offset:1024
	global_load_dwordx4 v[180:183], v232, s[40:41] offset:1024
	s_waitcnt vmcnt(12)
	v_readlane_b32 s48, v20, 19
	v_readlane_b32 s58, v25, 19
	v_readlane_b32 s50, v21, 19
	v_readlane_b32 s60, v26, 19
	v_readlane_b32 s52, v22, 19
	v_readlane_b32 s62, v27, 19
	v_readlane_b32 s54, v23, 19
	v_readlane_b32 s64, v28, 19
	v_readlane_b32 s56, v24, 19
	v_readlane_b32 s66, v29, 19
	v_pk_fma_f32 v[52:53], v[192:193], s[48:49], v[52:53] op_sel_hi:[1,0,1]
	v_pk_fma_f32 v[54:55], v[194:195], s[48:49], v[54:55] op_sel_hi:[1,0,1]
	v_pk_fma_f32 v[56:57], v[196:197], s[58:59], v[56:57] op_sel_hi:[1,0,1]
	v_pk_fma_f32 v[58:59], v[198:199], s[58:59], v[58:59] op_sel_hi:[1,0,1]
	v_pk_fma_f32 v[60:61], v[192:193], s[50:51], v[60:61] op_sel_hi:[1,0,1]
	v_pk_fma_f32 v[62:63], v[194:195], s[50:51], v[62:63] op_sel_hi:[1,0,1]
	v_pk_fma_f32 v[64:65], v[196:197], s[60:61], v[64:65] op_sel_hi:[1,0,1]
	v_pk_fma_f32 v[66:67], v[198:199], s[60:61], v[66:67] op_sel_hi:[1,0,1]
	v_pk_fma_f32 v[68:69], v[192:193], s[52:53], v[68:69] op_sel_hi:[1,0,1]
	v_pk_fma_f32 v[70:71], v[194:195], s[52:53], v[70:71] op_sel_hi:[1,0,1]
	v_pk_fma_f32 v[72:73], v[196:197], s[62:63], v[72:73] op_sel_hi:[1,0,1]
	v_pk_fma_f32 v[74:75], v[198:199], s[62:63], v[74:75] op_sel_hi:[1,0,1]
	v_pk_fma_f32 v[76:77], v[192:193], s[54:55], v[76:77] op_sel_hi:[1,0,1]
	v_pk_fma_f32 v[78:79], v[194:195], s[54:55], v[78:79] op_sel_hi:[1,0,1]
	v_pk_fma_f32 v[80:81], v[196:197], s[64:65], v[80:81] op_sel_hi:[1,0,1]
	v_pk_fma_f32 v[82:83], v[198:199], s[64:65], v[82:83] op_sel_hi:[1,0,1]
	v_pk_fma_f32 v[84:85], v[192:193], s[56:57], v[84:85] op_sel_hi:[1,0,1]
	v_pk_fma_f32 v[86:87], v[194:195], s[56:57], v[86:87] op_sel_hi:[1,0,1]
	v_pk_fma_f32 v[88:89], v[196:197], s[66:67], v[88:89] op_sel_hi:[1,0,1]
	v_pk_fma_f32 v[90:91], v[198:199], s[66:67], v[90:91] op_sel_hi:[1,0,1]
	global_load_dwordx4 v[184:187], v232, s[2:3] offset:2048
	global_load_dwordx4 v[188:191], v232, s[40:41] offset:2048
	s_waitcnt vmcnt(12)
	v_readlane_b32 s48, v20, 20
	v_readlane_b32 s58, v25, 20
	v_readlane_b32 s50, v21, 20
	v_readlane_b32 s60, v26, 20
	v_readlane_b32 s52, v22, 20
	v_readlane_b32 s62, v27, 20
	v_readlane_b32 s54, v23, 20
	v_readlane_b32 s64, v28, 20
	v_readlane_b32 s56, v24, 20
	v_readlane_b32 s66, v29, 20
	v_pk_fma_f32 v[52:53], v[200:201], s[48:49], v[52:53] op_sel_hi:[1,0,1]
	v_pk_fma_f32 v[54:55], v[202:203], s[48:49], v[54:55] op_sel_hi:[1,0,1]
	v_pk_fma_f32 v[56:57], v[204:205], s[58:59], v[56:57] op_sel_hi:[1,0,1]
	v_pk_fma_f32 v[58:59], v[206:207], s[58:59], v[58:59] op_sel_hi:[1,0,1]
	v_pk_fma_f32 v[60:61], v[200:201], s[50:51], v[60:61] op_sel_hi:[1,0,1]
	v_pk_fma_f32 v[62:63], v[202:203], s[50:51], v[62:63] op_sel_hi:[1,0,1]
	v_pk_fma_f32 v[64:65], v[204:205], s[60:61], v[64:65] op_sel_hi:[1,0,1]
	v_pk_fma_f32 v[66:67], v[206:207], s[60:61], v[66:67] op_sel_hi:[1,0,1]
	v_pk_fma_f32 v[68:69], v[200:201], s[52:53], v[68:69] op_sel_hi:[1,0,1]
	v_pk_fma_f32 v[70:71], v[202:203], s[52:53], v[70:71] op_sel_hi:[1,0,1]
	v_pk_fma_f32 v[72:73], v[204:205], s[62:63], v[72:73] op_sel_hi:[1,0,1]
	v_pk_fma_f32 v[74:75], v[206:207], s[62:63], v[74:75] op_sel_hi:[1,0,1]
	v_pk_fma_f32 v[76:77], v[200:201], s[54:55], v[76:77] op_sel_hi:[1,0,1]
	v_pk_fma_f32 v[78:79], v[202:203], s[54:55], v[78:79] op_sel_hi:[1,0,1]
	v_pk_fma_f32 v[80:81], v[204:205], s[64:65], v[80:81] op_sel_hi:[1,0,1]
	v_pk_fma_f32 v[82:83], v[206:207], s[64:65], v[82:83] op_sel_hi:[1,0,1]
	v_pk_fma_f32 v[84:85], v[200:201], s[56:57], v[84:85] op_sel_hi:[1,0,1]
	v_pk_fma_f32 v[86:87], v[202:203], s[56:57], v[86:87] op_sel_hi:[1,0,1]
	v_pk_fma_f32 v[88:89], v[204:205], s[66:67], v[88:89] op_sel_hi:[1,0,1]
	v_pk_fma_f32 v[90:91], v[206:207], s[66:67], v[90:91] op_sel_hi:[1,0,1]
	global_load_dwordx4 v[192:195], v232, s[2:3] offset:3072
	global_load_dwordx4 v[196:199], v232, s[40:41] offset:3072
	s_add_u32 s2, s2, 0x1000
	s_addc_u32 s3, s3, 0
	s_add_u32 s40, s40, 0x1000
	s_addc_u32 s41, s41, 0
	s_waitcnt vmcnt(12)
	v_readlane_b32 s48, v20, 21
	v_readlane_b32 s58, v25, 21
	v_readlane_b32 s50, v21, 21
	v_readlane_b32 s60, v26, 21
	v_readlane_b32 s52, v22, 21
	v_readlane_b32 s62, v27, 21
	v_readlane_b32 s54, v23, 21
	v_readlane_b32 s64, v28, 21
	v_readlane_b32 s56, v24, 21
	v_readlane_b32 s66, v29, 21
	v_pk_fma_f32 v[52:53], v[208:209], s[48:49], v[52:53] op_sel_hi:[1,0,1]
	v_pk_fma_f32 v[54:55], v[210:211], s[48:49], v[54:55] op_sel_hi:[1,0,1]
	v_pk_fma_f32 v[56:57], v[212:213], s[58:59], v[56:57] op_sel_hi:[1,0,1]
	v_pk_fma_f32 v[58:59], v[214:215], s[58:59], v[58:59] op_sel_hi:[1,0,1]
	v_pk_fma_f32 v[60:61], v[208:209], s[50:51], v[60:61] op_sel_hi:[1,0,1]
	v_pk_fma_f32 v[62:63], v[210:211], s[50:51], v[62:63] op_sel_hi:[1,0,1]
	v_pk_fma_f32 v[64:65], v[212:213], s[60:61], v[64:65] op_sel_hi:[1,0,1]
	v_pk_fma_f32 v[66:67], v[214:215], s[60:61], v[66:67] op_sel_hi:[1,0,1]
	v_pk_fma_f32 v[68:69], v[208:209], s[52:53], v[68:69] op_sel_hi:[1,0,1]
	v_pk_fma_f32 v[70:71], v[210:211], s[52:53], v[70:71] op_sel_hi:[1,0,1]
	v_pk_fma_f32 v[72:73], v[212:213], s[62:63], v[72:73] op_sel_hi:[1,0,1]
	v_pk_fma_f32 v[74:75], v[214:215], s[62:63], v[74:75] op_sel_hi:[1,0,1]
	v_pk_fma_f32 v[76:77], v[208:209], s[54:55], v[76:77] op_sel_hi:[1,0,1]
	v_pk_fma_f32 v[78:79], v[210:211], s[54:55], v[78:79] op_sel_hi:[1,0,1]
	v_pk_fma_f32 v[80:81], v[212:213], s[64:65], v[80:81] op_sel_hi:[1,0,1]
	v_pk_fma_f32 v[82:83], v[214:215], s[64:65], v[82:83] op_sel_hi:[1,0,1]
	v_pk_fma_f32 v[84:85], v[208:209], s[56:57], v[84:85] op_sel_hi:[1,0,1]
	v_pk_fma_f32 v[86:87], v[210:211], s[56:57], v[86:87] op_sel_hi:[1,0,1]
	v_pk_fma_f32 v[88:89], v[212:213], s[66:67], v[88:89] op_sel_hi:[1,0,1]
	v_pk_fma_f32 v[90:91], v[214:215], s[66:67], v[90:91] op_sel_hi:[1,0,1]
	global_load_dwordx4 v[200:203], v232, s[2:3]
	global_load_dwordx4 v[204:207], v232, s[40:41]
	s_waitcnt vmcnt(12)
	v_readlane_b32 s48, v20, 22
	v_readlane_b32 s58, v25, 22
	v_readlane_b32 s50, v21, 22
	v_readlane_b32 s60, v26, 22
	v_readlane_b32 s52, v22, 22
	v_readlane_b32 s62, v27, 22
	v_readlane_b32 s54, v23, 22
	v_readlane_b32 s64, v28, 22
	v_readlane_b32 s56, v24, 22
	v_readlane_b32 s66, v29, 22
	v_pk_fma_f32 v[52:53], v[216:217], s[48:49], v[52:53] op_sel_hi:[1,0,1]
	v_pk_fma_f32 v[54:55], v[218:219], s[48:49], v[54:55] op_sel_hi:[1,0,1]
	v_pk_fma_f32 v[56:57], v[220:221], s[58:59], v[56:57] op_sel_hi:[1,0,1]
	v_pk_fma_f32 v[58:59], v[222:223], s[58:59], v[58:59] op_sel_hi:[1,0,1]
	v_pk_fma_f32 v[60:61], v[216:217], s[50:51], v[60:61] op_sel_hi:[1,0,1]
	v_pk_fma_f32 v[62:63], v[218:219], s[50:51], v[62:63] op_sel_hi:[1,0,1]
	v_pk_fma_f32 v[64:65], v[220:221], s[60:61], v[64:65] op_sel_hi:[1,0,1]
	v_pk_fma_f32 v[66:67], v[222:223], s[60:61], v[66:67] op_sel_hi:[1,0,1]
	v_pk_fma_f32 v[68:69], v[216:217], s[52:53], v[68:69] op_sel_hi:[1,0,1]
	v_pk_fma_f32 v[70:71], v[218:219], s[52:53], v[70:71] op_sel_hi:[1,0,1]
	v_pk_fma_f32 v[72:73], v[220:221], s[62:63], v[72:73] op_sel_hi:[1,0,1]
	v_pk_fma_f32 v[74:75], v[222:223], s[62:63], v[74:75] op_sel_hi:[1,0,1]
	v_pk_fma_f32 v[76:77], v[216:217], s[54:55], v[76:77] op_sel_hi:[1,0,1]
	v_pk_fma_f32 v[78:79], v[218:219], s[54:55], v[78:79] op_sel_hi:[1,0,1]
	v_pk_fma_f32 v[80:81], v[220:221], s[64:65], v[80:81] op_sel_hi:[1,0,1]
	v_pk_fma_f32 v[82:83], v[222:223], s[64:65], v[82:83] op_sel_hi:[1,0,1]
	v_pk_fma_f32 v[84:85], v[216:217], s[56:57], v[84:85] op_sel_hi:[1,0,1]
	v_pk_fma_f32 v[86:87], v[218:219], s[56:57], v[86:87] op_sel_hi:[1,0,1]
	v_pk_fma_f32 v[88:89], v[220:221], s[66:67], v[88:89] op_sel_hi:[1,0,1]
	v_pk_fma_f32 v[90:91], v[222:223], s[66:67], v[90:91] op_sel_hi:[1,0,1]
	global_load_dwordx4 v[208:211], v232, s[2:3] offset:1024
	global_load_dwordx4 v[212:215], v232, s[40:41] offset:1024
	s_waitcnt vmcnt(12)
	v_readlane_b32 s48, v20, 23
	v_readlane_b32 s58, v25, 23
	v_readlane_b32 s50, v21, 23
	v_readlane_b32 s60, v26, 23
	v_readlane_b32 s52, v22, 23
	v_readlane_b32 s62, v27, 23
	v_readlane_b32 s54, v23, 23
	v_readlane_b32 s64, v28, 23
	v_readlane_b32 s56, v24, 23
	v_readlane_b32 s66, v29, 23
	v_pk_fma_f32 v[52:53], v[224:225], s[48:49], v[52:53] op_sel_hi:[1,0,1]
	v_pk_fma_f32 v[54:55], v[226:227], s[48:49], v[54:55] op_sel_hi:[1,0,1]
	v_pk_fma_f32 v[56:57], v[228:229], s[58:59], v[56:57] op_sel_hi:[1,0,1]
	v_pk_fma_f32 v[58:59], v[230:231], s[58:59], v[58:59] op_sel_hi:[1,0,1]
	v_pk_fma_f32 v[60:61], v[224:225], s[50:51], v[60:61] op_sel_hi:[1,0,1]
	v_pk_fma_f32 v[62:63], v[226:227], s[50:51], v[62:63] op_sel_hi:[1,0,1]
	v_pk_fma_f32 v[64:65], v[228:229], s[60:61], v[64:65] op_sel_hi:[1,0,1]
	v_pk_fma_f32 v[66:67], v[230:231], s[60:61], v[66:67] op_sel_hi:[1,0,1]
	v_pk_fma_f32 v[68:69], v[224:225], s[52:53], v[68:69] op_sel_hi:[1,0,1]
	v_pk_fma_f32 v[70:71], v[226:227], s[52:53], v[70:71] op_sel_hi:[1,0,1]
	v_pk_fma_f32 v[72:73], v[228:229], s[62:63], v[72:73] op_sel_hi:[1,0,1]
	v_pk_fma_f32 v[74:75], v[230:231], s[62:63], v[74:75] op_sel_hi:[1,0,1]
	v_pk_fma_f32 v[76:77], v[224:225], s[54:55], v[76:77] op_sel_hi:[1,0,1]
	v_pk_fma_f32 v[78:79], v[226:227], s[54:55], v[78:79] op_sel_hi:[1,0,1]
	v_pk_fma_f32 v[80:81], v[228:229], s[64:65], v[80:81] op_sel_hi:[1,0,1]
	v_pk_fma_f32 v[82:83], v[230:231], s[64:65], v[82:83] op_sel_hi:[1,0,1]
	v_pk_fma_f32 v[84:85], v[224:225], s[56:57], v[84:85] op_sel_hi:[1,0,1]
	v_pk_fma_f32 v[86:87], v[226:227], s[56:57], v[86:87] op_sel_hi:[1,0,1]
	v_pk_fma_f32 v[88:89], v[228:229], s[66:67], v[88:89] op_sel_hi:[1,0,1]
	v_pk_fma_f32 v[90:91], v[230:231], s[66:67], v[90:91] op_sel_hi:[1,0,1]
	global_load_dwordx4 v[216:219], v232, s[2:3] offset:2048
	global_load_dwordx4 v[220:223], v232, s[40:41] offset:2048
	s_waitcnt vmcnt(12)
	v_readlane_b32 s48, v20, 24
	v_readlane_b32 s58, v25, 24
	v_readlane_b32 s50, v21, 24
	v_readlane_b32 s60, v26, 24
	v_readlane_b32 s52, v22, 24
	v_readlane_b32 s62, v27, 24
	v_readlane_b32 s54, v23, 24
	v_readlane_b32 s64, v28, 24
	v_readlane_b32 s56, v24, 24
	v_readlane_b32 s66, v29, 24
	v_pk_fma_f32 v[52:53], v[168:169], s[48:49], v[52:53] op_sel_hi:[1,0,1]
	v_pk_fma_f32 v[54:55], v[170:171], s[48:49], v[54:55] op_sel_hi:[1,0,1]
	v_pk_fma_f32 v[56:57], v[172:173], s[58:59], v[56:57] op_sel_hi:[1,0,1]
	v_pk_fma_f32 v[58:59], v[174:175], s[58:59], v[58:59] op_sel_hi:[1,0,1]
	v_pk_fma_f32 v[60:61], v[168:169], s[50:51], v[60:61] op_sel_hi:[1,0,1]
	v_pk_fma_f32 v[62:63], v[170:171], s[50:51], v[62:63] op_sel_hi:[1,0,1]
	v_pk_fma_f32 v[64:65], v[172:173], s[60:61], v[64:65] op_sel_hi:[1,0,1]
	v_pk_fma_f32 v[66:67], v[174:175], s[60:61], v[66:67] op_sel_hi:[1,0,1]
	v_pk_fma_f32 v[68:69], v[168:169], s[52:53], v[68:69] op_sel_hi:[1,0,1]
	v_pk_fma_f32 v[70:71], v[170:171], s[52:53], v[70:71] op_sel_hi:[1,0,1]
	v_pk_fma_f32 v[72:73], v[172:173], s[62:63], v[72:73] op_sel_hi:[1,0,1]
	v_pk_fma_f32 v[74:75], v[174:175], s[62:63], v[74:75] op_sel_hi:[1,0,1]
	v_pk_fma_f32 v[76:77], v[168:169], s[54:55], v[76:77] op_sel_hi:[1,0,1]
	v_pk_fma_f32 v[78:79], v[170:171], s[54:55], v[78:79] op_sel_hi:[1,0,1]
	v_pk_fma_f32 v[80:81], v[172:173], s[64:65], v[80:81] op_sel_hi:[1,0,1]
	v_pk_fma_f32 v[82:83], v[174:175], s[64:65], v[82:83] op_sel_hi:[1,0,1]
	v_pk_fma_f32 v[84:85], v[168:169], s[56:57], v[84:85] op_sel_hi:[1,0,1]
	v_pk_fma_f32 v[86:87], v[170:171], s[56:57], v[86:87] op_sel_hi:[1,0,1]
	v_pk_fma_f32 v[88:89], v[172:173], s[66:67], v[88:89] op_sel_hi:[1,0,1]
	v_pk_fma_f32 v[90:91], v[174:175], s[66:67], v[90:91] op_sel_hi:[1,0,1]
	global_load_dwordx4 v[224:227], v232, s[2:3] offset:3072
	global_load_dwordx4 v[228:231], v232, s[40:41] offset:3072
	s_add_u32 s2, s2, 0x1000
	s_addc_u32 s3, s3, 0
	s_add_u32 s40, s40, 0x1000
	s_addc_u32 s41, s41, 0
	s_waitcnt vmcnt(12)
	v_readlane_b32 s48, v20, 25
	v_readlane_b32 s58, v25, 25
	v_readlane_b32 s50, v21, 25
	v_readlane_b32 s60, v26, 25
	v_readlane_b32 s52, v22, 25
	v_readlane_b32 s62, v27, 25
	v_readlane_b32 s54, v23, 25
	v_readlane_b32 s64, v28, 25
	v_readlane_b32 s56, v24, 25
	v_readlane_b32 s66, v29, 25
	v_pk_fma_f32 v[52:53], v[176:177], s[48:49], v[52:53] op_sel_hi:[1,0,1]
	v_pk_fma_f32 v[54:55], v[178:179], s[48:49], v[54:55] op_sel_hi:[1,0,1]
	v_pk_fma_f32 v[56:57], v[180:181], s[58:59], v[56:57] op_sel_hi:[1,0,1]
	v_pk_fma_f32 v[58:59], v[182:183], s[58:59], v[58:59] op_sel_hi:[1,0,1]
	v_pk_fma_f32 v[60:61], v[176:177], s[50:51], v[60:61] op_sel_hi:[1,0,1]
	v_pk_fma_f32 v[62:63], v[178:179], s[50:51], v[62:63] op_sel_hi:[1,0,1]
	v_pk_fma_f32 v[64:65], v[180:181], s[60:61], v[64:65] op_sel_hi:[1,0,1]
	v_pk_fma_f32 v[66:67], v[182:183], s[60:61], v[66:67] op_sel_hi:[1,0,1]
	v_pk_fma_f32 v[68:69], v[176:177], s[52:53], v[68:69] op_sel_hi:[1,0,1]
	v_pk_fma_f32 v[70:71], v[178:179], s[52:53], v[70:71] op_sel_hi:[1,0,1]
	v_pk_fma_f32 v[72:73], v[180:181], s[62:63], v[72:73] op_sel_hi:[1,0,1]
	v_pk_fma_f32 v[74:75], v[182:183], s[62:63], v[74:75] op_sel_hi:[1,0,1]
	v_pk_fma_f32 v[76:77], v[176:177], s[54:55], v[76:77] op_sel_hi:[1,0,1]
	v_pk_fma_f32 v[78:79], v[178:179], s[54:55], v[78:79] op_sel_hi:[1,0,1]
	v_pk_fma_f32 v[80:81], v[180:181], s[64:65], v[80:81] op_sel_hi:[1,0,1]
	v_pk_fma_f32 v[82:83], v[182:183], s[64:65], v[82:83] op_sel_hi:[1,0,1]
	v_pk_fma_f32 v[84:85], v[176:177], s[56:57], v[84:85] op_sel_hi:[1,0,1]
	v_pk_fma_f32 v[86:87], v[178:179], s[56:57], v[86:87] op_sel_hi:[1,0,1]
	v_pk_fma_f32 v[88:89], v[180:181], s[66:67], v[88:89] op_sel_hi:[1,0,1]
	v_pk_fma_f32 v[90:91], v[182:183], s[66:67], v[90:91] op_sel_hi:[1,0,1]
	s_waitcnt vmcnt(10)
	v_readlane_b32 s48, v20, 26
	v_readlane_b32 s58, v25, 26
	v_readlane_b32 s50, v21, 26
	v_readlane_b32 s60, v26, 26
	v_readlane_b32 s52, v22, 26
	v_readlane_b32 s62, v27, 26
	v_readlane_b32 s54, v23, 26
	v_readlane_b32 s64, v28, 26
	v_readlane_b32 s56, v24, 26
	v_readlane_b32 s66, v29, 26
	v_pk_fma_f32 v[52:53], v[184:185], s[48:49], v[52:53] op_sel_hi:[1,0,1]
	v_pk_fma_f32 v[54:55], v[186:187], s[48:49], v[54:55] op_sel_hi:[1,0,1]
	v_pk_fma_f32 v[56:57], v[188:189], s[58:59], v[56:57] op_sel_hi:[1,0,1]
	v_pk_fma_f32 v[58:59], v[190:191], s[58:59], v[58:59] op_sel_hi:[1,0,1]
	v_pk_fma_f32 v[60:61], v[184:185], s[50:51], v[60:61] op_sel_hi:[1,0,1]
	v_pk_fma_f32 v[62:63], v[186:187], s[50:51], v[62:63] op_sel_hi:[1,0,1]
	v_pk_fma_f32 v[64:65], v[188:189], s[60:61], v[64:65] op_sel_hi:[1,0,1]
	v_pk_fma_f32 v[66:67], v[190:191], s[60:61], v[66:67] op_sel_hi:[1,0,1]
	v_pk_fma_f32 v[68:69], v[184:185], s[52:53], v[68:69] op_sel_hi:[1,0,1]
	v_pk_fma_f32 v[70:71], v[186:187], s[52:53], v[70:71] op_sel_hi:[1,0,1]
	v_pk_fma_f32 v[72:73], v[188:189], s[62:63], v[72:73] op_sel_hi:[1,0,1]
	v_pk_fma_f32 v[74:75], v[190:191], s[62:63], v[74:75] op_sel_hi:[1,0,1]
	v_pk_fma_f32 v[76:77], v[184:185], s[54:55], v[76:77] op_sel_hi:[1,0,1]
	v_pk_fma_f32 v[78:79], v[186:187], s[54:55], v[78:79] op_sel_hi:[1,0,1]
	v_pk_fma_f32 v[80:81], v[188:189], s[64:65], v[80:81] op_sel_hi:[1,0,1]
	v_pk_fma_f32 v[82:83], v[190:191], s[64:65], v[82:83] op_sel_hi:[1,0,1]
	v_pk_fma_f32 v[84:85], v[184:185], s[56:57], v[84:85] op_sel_hi:[1,0,1]
	v_pk_fma_f32 v[86:87], v[186:187], s[56:57], v[86:87] op_sel_hi:[1,0,1]
	v_pk_fma_f32 v[88:89], v[188:189], s[66:67], v[88:89] op_sel_hi:[1,0,1]
	v_pk_fma_f32 v[90:91], v[190:191], s[66:67], v[90:91] op_sel_hi:[1,0,1]
	s_waitcnt vmcnt(8)
	v_readlane_b32 s48, v20, 27
	v_readlane_b32 s58, v25, 27
	v_readlane_b32 s50, v21, 27
	v_readlane_b32 s60, v26, 27
	v_readlane_b32 s52, v22, 27
	v_readlane_b32 s62, v27, 27
	v_readlane_b32 s54, v23, 27
	v_readlane_b32 s64, v28, 27
	v_readlane_b32 s56, v24, 27
	v_readlane_b32 s66, v29, 27
	v_pk_fma_f32 v[52:53], v[192:193], s[48:49], v[52:53] op_sel_hi:[1,0,1]
	v_pk_fma_f32 v[54:55], v[194:195], s[48:49], v[54:55] op_sel_hi:[1,0,1]
	v_pk_fma_f32 v[56:57], v[196:197], s[58:59], v[56:57] op_sel_hi:[1,0,1]
	v_pk_fma_f32 v[58:59], v[198:199], s[58:59], v[58:59] op_sel_hi:[1,0,1]
	v_pk_fma_f32 v[60:61], v[192:193], s[50:51], v[60:61] op_sel_hi:[1,0,1]
	v_pk_fma_f32 v[62:63], v[194:195], s[50:51], v[62:63] op_sel_hi:[1,0,1]
	v_pk_fma_f32 v[64:65], v[196:197], s[60:61], v[64:65] op_sel_hi:[1,0,1]
	v_pk_fma_f32 v[66:67], v[198:199], s[60:61], v[66:67] op_sel_hi:[1,0,1]
	v_pk_fma_f32 v[68:69], v[192:193], s[52:53], v[68:69] op_sel_hi:[1,0,1]
	v_pk_fma_f32 v[70:71], v[194:195], s[52:53], v[70:71] op_sel_hi:[1,0,1]
	v_pk_fma_f32 v[72:73], v[196:197], s[62:63], v[72:73] op_sel_hi:[1,0,1]
	v_pk_fma_f32 v[74:75], v[198:199], s[62:63], v[74:75] op_sel_hi:[1,0,1]
	v_pk_fma_f32 v[76:77], v[192:193], s[54:55], v[76:77] op_sel_hi:[1,0,1]
	v_pk_fma_f32 v[78:79], v[194:195], s[54:55], v[78:79] op_sel_hi:[1,0,1]
	v_pk_fma_f32 v[80:81], v[196:197], s[64:65], v[80:81] op_sel_hi:[1,0,1]
	v_pk_fma_f32 v[82:83], v[198:199], s[64:65], v[82:83] op_sel_hi:[1,0,1]
	v_pk_fma_f32 v[84:85], v[192:193], s[56:57], v[84:85] op_sel_hi:[1,0,1]
	v_pk_fma_f32 v[86:87], v[194:195], s[56:57], v[86:87] op_sel_hi:[1,0,1]
	v_pk_fma_f32 v[88:89], v[196:197], s[66:67], v[88:89] op_sel_hi:[1,0,1]
	v_pk_fma_f32 v[90:91], v[198:199], s[66:67], v[90:91] op_sel_hi:[1,0,1]
	s_waitcnt vmcnt(6)
	v_readlane_b32 s48, v20, 28
	v_readlane_b32 s58, v25, 28
	v_readlane_b32 s50, v21, 28
	v_readlane_b32 s60, v26, 28
	v_readlane_b32 s52, v22, 28
	v_readlane_b32 s62, v27, 28
	v_readlane_b32 s54, v23, 28
	v_readlane_b32 s64, v28, 28
	v_readlane_b32 s56, v24, 28
	v_readlane_b32 s66, v29, 28
	v_pk_fma_f32 v[52:53], v[200:201], s[48:49], v[52:53] op_sel_hi:[1,0,1]
	v_pk_fma_f32 v[54:55], v[202:203], s[48:49], v[54:55] op_sel_hi:[1,0,1]
	v_pk_fma_f32 v[56:57], v[204:205], s[58:59], v[56:57] op_sel_hi:[1,0,1]
	v_pk_fma_f32 v[58:59], v[206:207], s[58:59], v[58:59] op_sel_hi:[1,0,1]
	v_pk_fma_f32 v[60:61], v[200:201], s[50:51], v[60:61] op_sel_hi:[1,0,1]
	v_pk_fma_f32 v[62:63], v[202:203], s[50:51], v[62:63] op_sel_hi:[1,0,1]
	v_pk_fma_f32 v[64:65], v[204:205], s[60:61], v[64:65] op_sel_hi:[1,0,1]
	v_pk_fma_f32 v[66:67], v[206:207], s[60:61], v[66:67] op_sel_hi:[1,0,1]
	v_pk_fma_f32 v[68:69], v[200:201], s[52:53], v[68:69] op_sel_hi:[1,0,1]
	v_pk_fma_f32 v[70:71], v[202:203], s[52:53], v[70:71] op_sel_hi:[1,0,1]
	v_pk_fma_f32 v[72:73], v[204:205], s[62:63], v[72:73] op_sel_hi:[1,0,1]
	v_pk_fma_f32 v[74:75], v[206:207], s[62:63], v[74:75] op_sel_hi:[1,0,1]
	v_pk_fma_f32 v[76:77], v[200:201], s[54:55], v[76:77] op_sel_hi:[1,0,1]
	v_pk_fma_f32 v[78:79], v[202:203], s[54:55], v[78:79] op_sel_hi:[1,0,1]
	v_pk_fma_f32 v[80:81], v[204:205], s[64:65], v[80:81] op_sel_hi:[1,0,1]
	v_pk_fma_f32 v[82:83], v[206:207], s[64:65], v[82:83] op_sel_hi:[1,0,1]
	v_pk_fma_f32 v[84:85], v[200:201], s[56:57], v[84:85] op_sel_hi:[1,0,1]
	v_pk_fma_f32 v[86:87], v[202:203], s[56:57], v[86:87] op_sel_hi:[1,0,1]
	v_pk_fma_f32 v[88:89], v[204:205], s[66:67], v[88:89] op_sel_hi:[1,0,1]
	v_pk_fma_f32 v[90:91], v[206:207], s[66:67], v[90:91] op_sel_hi:[1,0,1]
	s_waitcnt vmcnt(4)
	v_readlane_b32 s48, v20, 29
	v_readlane_b32 s58, v25, 29
	v_readlane_b32 s50, v21, 29
	v_readlane_b32 s60, v26, 29
	v_readlane_b32 s52, v22, 29
	v_readlane_b32 s62, v27, 29
	v_readlane_b32 s54, v23, 29
	v_readlane_b32 s64, v28, 29
	v_readlane_b32 s56, v24, 29
	v_readlane_b32 s66, v29, 29
	v_pk_fma_f32 v[52:53], v[208:209], s[48:49], v[52:53] op_sel_hi:[1,0,1]
	v_pk_fma_f32 v[54:55], v[210:211], s[48:49], v[54:55] op_sel_hi:[1,0,1]
	v_pk_fma_f32 v[56:57], v[212:213], s[58:59], v[56:57] op_sel_hi:[1,0,1]
	v_pk_fma_f32 v[58:59], v[214:215], s[58:59], v[58:59] op_sel_hi:[1,0,1]
	v_pk_fma_f32 v[60:61], v[208:209], s[50:51], v[60:61] op_sel_hi:[1,0,1]
	v_pk_fma_f32 v[62:63], v[210:211], s[50:51], v[62:63] op_sel_hi:[1,0,1]
	v_pk_fma_f32 v[64:65], v[212:213], s[60:61], v[64:65] op_sel_hi:[1,0,1]
	v_pk_fma_f32 v[66:67], v[214:215], s[60:61], v[66:67] op_sel_hi:[1,0,1]
	v_pk_fma_f32 v[68:69], v[208:209], s[52:53], v[68:69] op_sel_hi:[1,0,1]
	v_pk_fma_f32 v[70:71], v[210:211], s[52:53], v[70:71] op_sel_hi:[1,0,1]
	v_pk_fma_f32 v[72:73], v[212:213], s[62:63], v[72:73] op_sel_hi:[1,0,1]
	v_pk_fma_f32 v[74:75], v[214:215], s[62:63], v[74:75] op_sel_hi:[1,0,1]
	v_pk_fma_f32 v[76:77], v[208:209], s[54:55], v[76:77] op_sel_hi:[1,0,1]
	v_pk_fma_f32 v[78:79], v[210:211], s[54:55], v[78:79] op_sel_hi:[1,0,1]
	v_pk_fma_f32 v[80:81], v[212:213], s[64:65], v[80:81] op_sel_hi:[1,0,1]
	v_pk_fma_f32 v[82:83], v[214:215], s[64:65], v[82:83] op_sel_hi:[1,0,1]
	v_pk_fma_f32 v[84:85], v[208:209], s[56:57], v[84:85] op_sel_hi:[1,0,1]
	v_pk_fma_f32 v[86:87], v[210:211], s[56:57], v[86:87] op_sel_hi:[1,0,1]
	v_pk_fma_f32 v[88:89], v[212:213], s[66:67], v[88:89] op_sel_hi:[1,0,1]
	v_pk_fma_f32 v[90:91], v[214:215], s[66:67], v[90:91] op_sel_hi:[1,0,1]
	s_waitcnt vmcnt(2)
	v_readlane_b32 s48, v20, 30
	v_readlane_b32 s58, v25, 30
	v_readlane_b32 s50, v21, 30
	v_readlane_b32 s60, v26, 30
	v_readlane_b32 s52, v22, 30
	v_readlane_b32 s62, v27, 30
	v_readlane_b32 s54, v23, 30
	v_readlane_b32 s64, v28, 30
	v_readlane_b32 s56, v24, 30
	v_readlane_b32 s66, v29, 30
	v_pk_fma_f32 v[52:53], v[216:217], s[48:49], v[52:53] op_sel_hi:[1,0,1]
	v_pk_fma_f32 v[54:55], v[218:219], s[48:49], v[54:55] op_sel_hi:[1,0,1]
	v_pk_fma_f32 v[56:57], v[220:221], s[58:59], v[56:57] op_sel_hi:[1,0,1]
	v_pk_fma_f32 v[58:59], v[222:223], s[58:59], v[58:59] op_sel_hi:[1,0,1]
	v_pk_fma_f32 v[60:61], v[216:217], s[50:51], v[60:61] op_sel_hi:[1,0,1]
	v_pk_fma_f32 v[62:63], v[218:219], s[50:51], v[62:63] op_sel_hi:[1,0,1]
	v_pk_fma_f32 v[64:65], v[220:221], s[60:61], v[64:65] op_sel_hi:[1,0,1]
	v_pk_fma_f32 v[66:67], v[222:223], s[60:61], v[66:67] op_sel_hi:[1,0,1]
	v_pk_fma_f32 v[68:69], v[216:217], s[52:53], v[68:69] op_sel_hi:[1,0,1]
	v_pk_fma_f32 v[70:71], v[218:219], s[52:53], v[70:71] op_sel_hi:[1,0,1]
	v_pk_fma_f32 v[72:73], v[220:221], s[62:63], v[72:73] op_sel_hi:[1,0,1]
	v_pk_fma_f32 v[74:75], v[222:223], s[62:63], v[74:75] op_sel_hi:[1,0,1]
	v_pk_fma_f32 v[76:77], v[216:217], s[54:55], v[76:77] op_sel_hi:[1,0,1]
	v_pk_fma_f32 v[78:79], v[218:219], s[54:55], v[78:79] op_sel_hi:[1,0,1]
	v_pk_fma_f32 v[80:81], v[220:221], s[64:65], v[80:81] op_sel_hi:[1,0,1]
	v_pk_fma_f32 v[82:83], v[222:223], s[64:65], v[82:83] op_sel_hi:[1,0,1]
	v_pk_fma_f32 v[84:85], v[216:217], s[56:57], v[84:85] op_sel_hi:[1,0,1]
	v_pk_fma_f32 v[86:87], v[218:219], s[56:57], v[86:87] op_sel_hi:[1,0,1]
	v_pk_fma_f32 v[88:89], v[220:221], s[66:67], v[88:89] op_sel_hi:[1,0,1]
	v_pk_fma_f32 v[90:91], v[222:223], s[66:67], v[90:91] op_sel_hi:[1,0,1]
	s_waitcnt vmcnt(0)
	v_readlane_b32 s48, v20, 31
	v_readlane_b32 s58, v25, 31
	v_readlane_b32 s50, v21, 31
	v_readlane_b32 s60, v26, 31
	v_readlane_b32 s52, v22, 31
	v_readlane_b32 s62, v27, 31
	v_readlane_b32 s54, v23, 31
	v_readlane_b32 s64, v28, 31
	v_readlane_b32 s56, v24, 31
	v_readlane_b32 s66, v29, 31
	v_pk_fma_f32 v[52:53], v[224:225], s[48:49], v[52:53] op_sel_hi:[1,0,1]
	v_pk_fma_f32 v[54:55], v[226:227], s[48:49], v[54:55] op_sel_hi:[1,0,1]
	v_pk_fma_f32 v[56:57], v[228:229], s[58:59], v[56:57] op_sel_hi:[1,0,1]
	v_pk_fma_f32 v[58:59], v[230:231], s[58:59], v[58:59] op_sel_hi:[1,0,1]
	v_pk_fma_f32 v[60:61], v[224:225], s[50:51], v[60:61] op_sel_hi:[1,0,1]
	v_pk_fma_f32 v[62:63], v[226:227], s[50:51], v[62:63] op_sel_hi:[1,0,1]
	v_pk_fma_f32 v[64:65], v[228:229], s[60:61], v[64:65] op_sel_hi:[1,0,1]
	v_pk_fma_f32 v[66:67], v[230:231], s[60:61], v[66:67] op_sel_hi:[1,0,1]
	v_pk_fma_f32 v[68:69], v[224:225], s[52:53], v[68:69] op_sel_hi:[1,0,1]
	v_pk_fma_f32 v[70:71], v[226:227], s[52:53], v[70:71] op_sel_hi:[1,0,1]
	v_pk_fma_f32 v[72:73], v[228:229], s[62:63], v[72:73] op_sel_hi:[1,0,1]
	v_pk_fma_f32 v[74:75], v[230:231], s[62:63], v[74:75] op_sel_hi:[1,0,1]
	v_pk_fma_f32 v[76:77], v[224:225], s[54:55], v[76:77] op_sel_hi:[1,0,1]
	v_pk_fma_f32 v[78:79], v[226:227], s[54:55], v[78:79] op_sel_hi:[1,0,1]
	v_pk_fma_f32 v[80:81], v[228:229], s[64:65], v[80:81] op_sel_hi:[1,0,1]
	v_pk_fma_f32 v[82:83], v[230:231], s[64:65], v[82:83] op_sel_hi:[1,0,1]
	v_pk_fma_f32 v[84:85], v[224:225], s[56:57], v[84:85] op_sel_hi:[1,0,1]
	v_pk_fma_f32 v[86:87], v[226:227], s[56:57], v[86:87] op_sel_hi:[1,0,1]
	v_pk_fma_f32 v[88:89], v[228:229], s[66:67], v[88:89] op_sel_hi:[1,0,1]
	v_pk_fma_f32 v[90:91], v[230:231], s[66:67], v[90:91] op_sel_hi:[1,0,1]
	s_add_u32 s2, s16, 0x8000
	s_addc_u32 s3, s17, 0
	s_add_u32 s40, s18, 0x8000
	s_addc_u32 s41, s19, 0
	global_load_dwordx4 v[168:171], v232, s[2:3]
	global_load_dwordx4 v[172:175], v232, s[40:41]
	global_load_dwordx4 v[176:179], v232, s[2:3] offset:1024
	global_load_dwordx4 v[180:183], v232, s[40:41] offset:1024
	global_load_dwordx4 v[184:187], v232, s[2:3] offset:2048
	global_load_dwordx4 v[188:191], v232, s[40:41] offset:2048
	global_load_dwordx4 v[192:195], v232, s[2:3] offset:3072
	global_load_dwordx4 v[196:199], v232, s[40:41] offset:3072
	s_add_u32 s2, s2, 0x1000
	s_addc_u32 s3, s3, 0
	s_add_u32 s40, s40, 0x1000
	s_addc_u32 s41, s41, 0
	global_load_dwordx4 v[200:203], v232, s[2:3]
	global_load_dwordx4 v[204:207], v232, s[40:41]
	global_load_dwordx4 v[208:211], v232, s[2:3] offset:1024
	global_load_dwordx4 v[212:215], v232, s[40:41] offset:1024
	s_mov_b32 s6, s13
	s_cmp_ge_u32 s6, 0x2800
	s_cbranch_scc1 .Lgprep_sk0
	v_mul_f32_e32 v92, 0xbfb8aa3b, v52
	v_exp_f32_e32 v92, v92
	s_nop 0
	v_add_f32_e32 v92, 1.0, v92
	v_div_scale_f32 v93, s[24:25], v92, v92, 1.0
	v_rcp_f32_e32 v94, v93
	s_nop 0
	v_fma_f32 v95, -v93, v94, 1.0
	v_fmac_f32_e32 v94, v95, v94
	v_div_scale_f32 v95, vcc, 1.0, v92, 1.0
	v_mul_f32_e32 v96, v95, v94
	v_fma_f32 v97, -v93, v96, v95
	v_fmac_f32_e32 v96, v97, v94
	v_fma_f32 v93, -v93, v96, v95
	v_div_fmas_f32 v93, v93, v94, v96
	v_div_fixup_f32 v52, v93, v92, 1.0
	v_mul_f32_e32 v52, 0xbf1b4598, v52
	v_mul_f32_e32 v52, 0x3fb8aa3b, v52
	v_exp_f32_e32 v52, v52
	v_mul_f32_e32 v92, 0xbfb8aa3b, v56
	v_exp_f32_e32 v92, v92
	s_nop 0
	v_add_f32_e32 v92, 1.0, v92
	v_div_scale_f32 v93, s[24:25], v92, v92, 1.0
	v_rcp_f32_e32 v94, v93
	s_nop 0
	v_fma_f32 v95, -v93, v94, 1.0
	v_fmac_f32_e32 v94, v95, v94
	v_div_scale_f32 v95, vcc, 1.0, v92, 1.0
	v_mul_f32_e32 v96, v95, v94
	v_fma_f32 v97, -v93, v96, v95
	v_fmac_f32_e32 v96, v97, v94
	v_fma_f32 v93, -v93, v96, v95
	v_div_fmas_f32 v93, v93, v94, v96
	v_div_fixup_f32 v56, v93, v92, 1.0
	v_mul_f32_e32 v92, 0xbfb8aa3b, v53
	v_exp_f32_e32 v92, v92
	s_nop 0
	v_add_f32_e32 v92, 1.0, v92
	v_div_scale_f32 v93, s[24:25], v92, v92, 1.0
	v_rcp_f32_e32 v94, v93
	s_nop 0
	v_fma_f32 v95, -v93, v94, 1.0
	v_fmac_f32_e32 v94, v95, v94
	v_div_scale_f32 v95, vcc, 1.0, v92, 1.0
	v_mul_f32_e32 v96, v95, v94
	v_fma_f32 v97, -v93, v96, v95
	v_fmac_f32_e32 v96, v97, v94
	v_fma_f32 v93, -v93, v96, v95
	v_div_fmas_f32 v93, v93, v94, v96
	v_div_fixup_f32 v53, v93, v92, 1.0
	v_mul_f32_e32 v53, 0xbf1b4598, v53
	v_mul_f32_e32 v53, 0x3fb8aa3b, v53
	v_exp_f32_e32 v53, v53
	v_mul_f32_e32 v92, 0xbfb8aa3b, v57
	v_exp_f32_e32 v92, v92
	s_nop 0
	v_add_f32_e32 v92, 1.0, v92
	v_div_scale_f32 v93, s[24:25], v92, v92, 1.0
	v_rcp_f32_e32 v94, v93
	s_nop 0
	v_fma_f32 v95, -v93, v94, 1.0
	v_fmac_f32_e32 v94, v95, v94
	v_div_scale_f32 v95, vcc, 1.0, v92, 1.0
	v_mul_f32_e32 v96, v95, v94
	v_fma_f32 v97, -v93, v96, v95
	v_fmac_f32_e32 v96, v97, v94
	v_fma_f32 v93, -v93, v96, v95
	v_div_fmas_f32 v93, v93, v94, v96
	v_div_fixup_f32 v57, v93, v92, 1.0
	v_mul_f32_e32 v92, 0xbfb8aa3b, v54
	v_exp_f32_e32 v92, v92
	s_nop 0
	v_add_f32_e32 v92, 1.0, v92
	v_div_scale_f32 v93, s[24:25], v92, v92, 1.0
	v_rcp_f32_e32 v94, v93
	s_nop 0
	v_fma_f32 v95, -v93, v94, 1.0
	v_fmac_f32_e32 v94, v95, v94
	v_div_scale_f32 v95, vcc, 1.0, v92, 1.0
	v_mul_f32_e32 v96, v95, v94
	v_fma_f32 v97, -v93, v96, v95
	v_fmac_f32_e32 v96, v97, v94
	v_fma_f32 v93, -v93, v96, v95
	v_div_fmas_f32 v93, v93, v94, v96
	v_div_fixup_f32 v54, v93, v92, 1.0
	v_mul_f32_e32 v54, 0xbf1b4598, v54
	v_mul_f32_e32 v54, 0x3fb8aa3b, v54
	v_exp_f32_e32 v54, v54
	v_mul_f32_e32 v92, 0xbfb8aa3b, v58
	v_exp_f32_e32 v92, v92
	s_nop 0
	v_add_f32_e32 v92, 1.0, v92
	v_div_scale_f32 v93, s[24:25], v92, v92, 1.0
	v_rcp_f32_e32 v94, v93
	s_nop 0
	v_fma_f32 v95, -v93, v94, 1.0
	v_fmac_f32_e32 v94, v95, v94
	v_div_scale_f32 v95, vcc, 1.0, v92, 1.0
	v_mul_f32_e32 v96, v95, v94
	v_fma_f32 v97, -v93, v96, v95
	v_fmac_f32_e32 v96, v97, v94
	v_fma_f32 v93, -v93, v96, v95
	v_div_fmas_f32 v93, v93, v94, v96
	v_div_fixup_f32 v58, v93, v92, 1.0
	v_mul_f32_e32 v92, 0xbfb8aa3b, v55
	v_exp_f32_e32 v92, v92
	s_nop 0
	v_add_f32_e32 v92, 1.0, v92
	v_div_scale_f32 v93, s[24:25], v92, v92, 1.0
	v_rcp_f32_e32 v94, v93
	s_nop 0
	v_fma_f32 v95, -v93, v94, 1.0
	v_fmac_f32_e32 v94, v95, v94
	v_div_scale_f32 v95, vcc, 1.0, v92, 1.0
	v_mul_f32_e32 v96, v95, v94
	v_fma_f32 v97, -v93, v96, v95
	v_fmac_f32_e32 v96, v97, v94
	v_fma_f32 v93, -v93, v96, v95
	v_div_fmas_f32 v93, v93, v94, v96
	v_div_fixup_f32 v55, v93, v92, 1.0
	v_mul_f32_e32 v55, 0xbf1b4598, v55
	v_mul_f32_e32 v55, 0x3fb8aa3b, v55
	v_exp_f32_e32 v55, v55
	v_mul_f32_e32 v92, 0xbfb8aa3b, v59
	v_exp_f32_e32 v92, v92
	s_nop 0
	v_add_f32_e32 v92, 1.0, v92
	v_div_scale_f32 v93, s[24:25], v92, v92, 1.0
	v_rcp_f32_e32 v94, v93
	s_nop 0
	v_fma_f32 v95, -v93, v94, 1.0
	v_fmac_f32_e32 v94, v95, v94
	v_div_scale_f32 v95, vcc, 1.0, v92, 1.0
	v_mul_f32_e32 v96, v95, v94
	v_fma_f32 v97, -v93, v96, v95
	v_fmac_f32_e32 v96, v97, v94
	v_fma_f32 v93, -v93, v96, v95
	v_div_fmas_f32 v93, v93, v94, v96
	v_div_fixup_f32 v59, v93, v92, 1.0
	s_mul_i32 s7, s6, 0x1400
	s_add_u32 s8, s82, s7
	s_addc_u32 s9, s83, 0
	global_store_dwordx4 v232, v[52:55], s[8:9] offset:1024
	global_store_dwordx4 v232, v[56:59], s[8:9] offset:2048
	global_store_dwordx4 v232, v[0:3], s[8:9]
	s_add_u32 s6, s13, 1
	s_cmp_ge_u32 s6, 0x2800
	s_cbranch_scc1 .Lgprep_sk0
	v_mul_f32_e32 v92, 0xbfb8aa3b, v60
	v_exp_f32_e32 v92, v92
	s_nop 0
	v_add_f32_e32 v92, 1.0, v92
	v_div_scale_f32 v93, s[24:25], v92, v92, 1.0
	v_rcp_f32_e32 v94, v93
	s_nop 0
	v_fma_f32 v95, -v93, v94, 1.0
	v_fmac_f32_e32 v94, v95, v94
	v_div_scale_f32 v95, vcc, 1.0, v92, 1.0
	v_mul_f32_e32 v96, v95, v94
	v_fma_f32 v97, -v93, v96, v95
	v_fmac_f32_e32 v96, v97, v94
	v_fma_f32 v93, -v93, v96, v95
	v_div_fmas_f32 v93, v93, v94, v96
	v_div_fixup_f32 v60, v93, v92, 1.0
	v_mul_f32_e32 v60, 0xbf1b4598, v60
	v_mul_f32_e32 v60, 0x3fb8aa3b, v60
	v_exp_f32_e32 v60, v60
	v_mul_f32_e32 v92, 0xbfb8aa3b, v64
	v_exp_f32_e32 v92, v92
	s_nop 0
	v_add_f32_e32 v92, 1.0, v92
	v_div_scale_f32 v93, s[24:25], v92, v92, 1.0
	v_rcp_f32_e32 v94, v93
	s_nop 0
	v_fma_f32 v95, -v93, v94, 1.0
	v_fmac_f32_e32 v94, v95, v94
	v_div_scale_f32 v95, vcc, 1.0, v92, 1.0
	v_mul_f32_e32 v96, v95, v94
	v_fma_f32 v97, -v93, v96, v95
	v_fmac_f32_e32 v96, v97, v94
	v_fma_f32 v93, -v93, v96, v95
	v_div_fmas_f32 v93, v93, v94, v96
	v_div_fixup_f32 v64, v93, v92, 1.0
	v_mul_f32_e32 v92, 0xbfb8aa3b, v61
	v_exp_f32_e32 v92, v92
	s_nop 0
	v_add_f32_e32 v92, 1.0, v92
	v_div_scale_f32 v93, s[24:25], v92, v92, 1.0
	v_rcp_f32_e32 v94, v93
	s_nop 0
	v_fma_f32 v95, -v93, v94, 1.0
	v_fmac_f32_e32 v94, v95, v94
	v_div_scale_f32 v95, vcc, 1.0, v92, 1.0
	v_mul_f32_e32 v96, v95, v94
	v_fma_f32 v97, -v93, v96, v95
	v_fmac_f32_e32 v96, v97, v94
	v_fma_f32 v93, -v93, v96, v95
	v_div_fmas_f32 v93, v93, v94, v96
	v_div_fixup_f32 v61, v93, v92, 1.0
	v_mul_f32_e32 v61, 0xbf1b4598, v61
	v_mul_f32_e32 v61, 0x3fb8aa3b, v61
	v_exp_f32_e32 v61, v61
	v_mul_f32_e32 v92, 0xbfb8aa3b, v65
	v_exp_f32_e32 v92, v92
	s_nop 0
	v_add_f32_e32 v92, 1.0, v92
	v_div_scale_f32 v93, s[24:25], v92, v92, 1.0
	v_rcp_f32_e32 v94, v93
	s_nop 0
	v_fma_f32 v95, -v93, v94, 1.0
	v_fmac_f32_e32 v94, v95, v94
	v_div_scale_f32 v95, vcc, 1.0, v92, 1.0
	v_mul_f32_e32 v96, v95, v94
	v_fma_f32 v97, -v93, v96, v95
	v_fmac_f32_e32 v96, v97, v94
	v_fma_f32 v93, -v93, v96, v95
	v_div_fmas_f32 v93, v93, v94, v96
	v_div_fixup_f32 v65, v93, v92, 1.0
	v_mul_f32_e32 v92, 0xbfb8aa3b, v62
	v_exp_f32_e32 v92, v92
	s_nop 0
	v_add_f32_e32 v92, 1.0, v92
	v_div_scale_f32 v93, s[24:25], v92, v92, 1.0
	v_rcp_f32_e32 v94, v93
	s_nop 0
	v_fma_f32 v95, -v93, v94, 1.0
	v_fmac_f32_e32 v94, v95, v94
	v_div_scale_f32 v95, vcc, 1.0, v92, 1.0
	v_mul_f32_e32 v96, v95, v94
	v_fma_f32 v97, -v93, v96, v95
	v_fmac_f32_e32 v96, v97, v94
	v_fma_f32 v93, -v93, v96, v95
	v_div_fmas_f32 v93, v93, v94, v96
	v_div_fixup_f32 v62, v93, v92, 1.0
	v_mul_f32_e32 v62, 0xbf1b4598, v62
	v_mul_f32_e32 v62, 0x3fb8aa3b, v62
	v_exp_f32_e32 v62, v62
	v_mul_f32_e32 v92, 0xbfb8aa3b, v66
	v_exp_f32_e32 v92, v92
	s_nop 0
	v_add_f32_e32 v92, 1.0, v92
	v_div_scale_f32 v93, s[24:25], v92, v92, 1.0
	v_rcp_f32_e32 v94, v93
	s_nop 0
	v_fma_f32 v95, -v93, v94, 1.0
	v_fmac_f32_e32 v94, v95, v94
	v_div_scale_f32 v95, vcc, 1.0, v92, 1.0
	v_mul_f32_e32 v96, v95, v94
	v_fma_f32 v97, -v93, v96, v95
	v_fmac_f32_e32 v96, v97, v94
	v_fma_f32 v93, -v93, v96, v95
	v_div_fmas_f32 v93, v93, v94, v96
	v_div_fixup_f32 v66, v93, v92, 1.0
	v_mul_f32_e32 v92, 0xbfb8aa3b, v63
	v_exp_f32_e32 v92, v92
	s_nop 0
	v_add_f32_e32 v92, 1.0, v92
	v_div_scale_f32 v93, s[24:25], v92, v92, 1.0
	v_rcp_f32_e32 v94, v93
	s_nop 0
	v_fma_f32 v95, -v93, v94, 1.0
	v_fmac_f32_e32 v94, v95, v94
	v_div_scale_f32 v95, vcc, 1.0, v92, 1.0
	v_mul_f32_e32 v96, v95, v94
	v_fma_f32 v97, -v93, v96, v95
	v_fmac_f32_e32 v96, v97, v94
	v_fma_f32 v93, -v93, v96, v95
	v_div_fmas_f32 v93, v93, v94, v96
	v_div_fixup_f32 v63, v93, v92, 1.0
	v_mul_f32_e32 v63, 0xbf1b4598, v63
	v_mul_f32_e32 v63, 0x3fb8aa3b, v63
	v_exp_f32_e32 v63, v63
	v_mul_f32_e32 v92, 0xbfb8aa3b, v67
	v_exp_f32_e32 v92, v92
	s_nop 0
	v_add_f32_e32 v92, 1.0, v92
	v_div_scale_f32 v93, s[24:25], v92, v92, 1.0
	v_rcp_f32_e32 v94, v93
	s_nop 0
	v_fma_f32 v95, -v93, v94, 1.0
	v_fmac_f32_e32 v94, v95, v94
	v_div_scale_f32 v95, vcc, 1.0, v92, 1.0
	v_mul_f32_e32 v96, v95, v94
	v_fma_f32 v97, -v93, v96, v95
	v_fmac_f32_e32 v96, v97, v94
	v_fma_f32 v93, -v93, v96, v95
	v_div_fmas_f32 v93, v93, v94, v96
	v_div_fixup_f32 v67, v93, v92, 1.0
	s_mul_i32 s7, s6, 0x1400
	s_add_u32 s8, s82, s7
	s_addc_u32 s9, s83, 0
	global_store_dwordx4 v232, v[60:63], s[8:9] offset:1024
	global_store_dwordx4 v232, v[64:67], s[8:9] offset:2048
	global_store_dwordx4 v232, v[4:7], s[8:9]
	s_add_u32 s6, s13, 2
	s_cmp_ge_u32 s6, 0x2800
	s_cbranch_scc1 .Lgprep_sk0
	v_mul_f32_e32 v92, 0xbfb8aa3b, v68
	v_exp_f32_e32 v92, v92
	s_nop 0
	v_add_f32_e32 v92, 1.0, v92
	v_div_scale_f32 v93, s[24:25], v92, v92, 1.0
	v_rcp_f32_e32 v94, v93
	s_nop 0
	v_fma_f32 v95, -v93, v94, 1.0
	v_fmac_f32_e32 v94, v95, v94
	v_div_scale_f32 v95, vcc, 1.0, v92, 1.0
	v_mul_f32_e32 v96, v95, v94
	v_fma_f32 v97, -v93, v96, v95
	v_fmac_f32_e32 v96, v97, v94
	v_fma_f32 v93, -v93, v96, v95
	v_div_fmas_f32 v93, v93, v94, v96
	v_div_fixup_f32 v68, v93, v92, 1.0
	v_mul_f32_e32 v68, 0xbf1b4598, v68
	v_mul_f32_e32 v68, 0x3fb8aa3b, v68
	v_exp_f32_e32 v68, v68
	v_mul_f32_e32 v92, 0xbfb8aa3b, v72
	v_exp_f32_e32 v92, v92
	s_nop 0
	v_add_f32_e32 v92, 1.0, v92
	v_div_scale_f32 v93, s[24:25], v92, v92, 1.0
	v_rcp_f32_e32 v94, v93
	s_nop 0
	v_fma_f32 v95, -v93, v94, 1.0
	v_fmac_f32_e32 v94, v95, v94
	v_div_scale_f32 v95, vcc, 1.0, v92, 1.0
	v_mul_f32_e32 v96, v95, v94
	v_fma_f32 v97, -v93, v96, v95
	v_fmac_f32_e32 v96, v97, v94
	v_fma_f32 v93, -v93, v96, v95
	v_div_fmas_f32 v93, v93, v94, v96
	v_div_fixup_f32 v72, v93, v92, 1.0
	v_mul_f32_e32 v92, 0xbfb8aa3b, v69
	v_exp_f32_e32 v92, v92
	s_nop 0
	v_add_f32_e32 v92, 1.0, v92
	v_div_scale_f32 v93, s[24:25], v92, v92, 1.0
	v_rcp_f32_e32 v94, v93
	s_nop 0
	v_fma_f32 v95, -v93, v94, 1.0
	v_fmac_f32_e32 v94, v95, v94
	v_div_scale_f32 v95, vcc, 1.0, v92, 1.0
	v_mul_f32_e32 v96, v95, v94
	v_fma_f32 v97, -v93, v96, v95
	v_fmac_f32_e32 v96, v97, v94
	v_fma_f32 v93, -v93, v96, v95
	v_div_fmas_f32 v93, v93, v94, v96
	v_div_fixup_f32 v69, v93, v92, 1.0
	v_mul_f32_e32 v69, 0xbf1b4598, v69
	v_mul_f32_e32 v69, 0x3fb8aa3b, v69
	v_exp_f32_e32 v69, v69
	v_mul_f32_e32 v92, 0xbfb8aa3b, v73
	v_exp_f32_e32 v92, v92
	s_nop 0
	v_add_f32_e32 v92, 1.0, v92
	v_div_scale_f32 v93, s[24:25], v92, v92, 1.0
	v_rcp_f32_e32 v94, v93
	s_nop 0
	v_fma_f32 v95, -v93, v94, 1.0
	v_fmac_f32_e32 v94, v95, v94
	v_div_scale_f32 v95, vcc, 1.0, v92, 1.0
	v_mul_f32_e32 v96, v95, v94
	v_fma_f32 v97, -v93, v96, v95
	v_fmac_f32_e32 v96, v97, v94
	v_fma_f32 v93, -v93, v96, v95
	v_div_fmas_f32 v93, v93, v94, v96
	v_div_fixup_f32 v73, v93, v92, 1.0
	v_mul_f32_e32 v92, 0xbfb8aa3b, v70
	v_exp_f32_e32 v92, v92
	s_nop 0
	v_add_f32_e32 v92, 1.0, v92
	v_div_scale_f32 v93, s[24:25], v92, v92, 1.0
	v_rcp_f32_e32 v94, v93
	s_nop 0
	v_fma_f32 v95, -v93, v94, 1.0
	v_fmac_f32_e32 v94, v95, v94
	v_div_scale_f32 v95, vcc, 1.0, v92, 1.0
	v_mul_f32_e32 v96, v95, v94
	v_fma_f32 v97, -v93, v96, v95
	v_fmac_f32_e32 v96, v97, v94
	v_fma_f32 v93, -v93, v96, v95
	v_div_fmas_f32 v93, v93, v94, v96
	v_div_fixup_f32 v70, v93, v92, 1.0
	v_mul_f32_e32 v70, 0xbf1b4598, v70
	v_mul_f32_e32 v70, 0x3fb8aa3b, v70
	v_exp_f32_e32 v70, v70
	v_mul_f32_e32 v92, 0xbfb8aa3b, v74
	v_exp_f32_e32 v92, v92
	s_nop 0
	v_add_f32_e32 v92, 1.0, v92
	v_div_scale_f32 v93, s[24:25], v92, v92, 1.0
	v_rcp_f32_e32 v94, v93
	s_nop 0
	v_fma_f32 v95, -v93, v94, 1.0
	v_fmac_f32_e32 v94, v95, v94
	v_div_scale_f32 v95, vcc, 1.0, v92, 1.0
	v_mul_f32_e32 v96, v95, v94
	v_fma_f32 v97, -v93, v96, v95
	v_fmac_f32_e32 v96, v97, v94
	v_fma_f32 v93, -v93, v96, v95
	v_div_fmas_f32 v93, v93, v94, v96
	v_div_fixup_f32 v74, v93, v92, 1.0
	v_mul_f32_e32 v92, 0xbfb8aa3b, v71
	v_exp_f32_e32 v92, v92
	s_nop 0
	v_add_f32_e32 v92, 1.0, v92
	v_div_scale_f32 v93, s[24:25], v92, v92, 1.0
	v_rcp_f32_e32 v94, v93
	s_nop 0
	v_fma_f32 v95, -v93, v94, 1.0
	v_fmac_f32_e32 v94, v95, v94
	v_div_scale_f32 v95, vcc, 1.0, v92, 1.0
	v_mul_f32_e32 v96, v95, v94
	v_fma_f32 v97, -v93, v96, v95
	v_fmac_f32_e32 v96, v97, v94
	v_fma_f32 v93, -v93, v96, v95
	v_div_fmas_f32 v93, v93, v94, v96
	v_div_fixup_f32 v71, v93, v92, 1.0
	v_mul_f32_e32 v71, 0xbf1b4598, v71
	v_mul_f32_e32 v71, 0x3fb8aa3b, v71
	v_exp_f32_e32 v71, v71
	v_mul_f32_e32 v92, 0xbfb8aa3b, v75
	v_exp_f32_e32 v92, v92
	s_nop 0
	v_add_f32_e32 v92, 1.0, v92
	v_div_scale_f32 v93, s[24:25], v92, v92, 1.0
	v_rcp_f32_e32 v94, v93
	s_nop 0
	v_fma_f32 v95, -v93, v94, 1.0
	v_fmac_f32_e32 v94, v95, v94
	v_div_scale_f32 v95, vcc, 1.0, v92, 1.0
	v_mul_f32_e32 v96, v95, v94
	v_fma_f32 v97, -v93, v96, v95
	v_fmac_f32_e32 v96, v97, v94
	v_fma_f32 v93, -v93, v96, v95
	v_div_fmas_f32 v93, v93, v94, v96
	v_div_fixup_f32 v75, v93, v92, 1.0
	s_mul_i32 s7, s6, 0x1400
	s_add_u32 s8, s82, s7
	s_addc_u32 s9, s83, 0
	global_store_dwordx4 v232, v[68:71], s[8:9] offset:1024
	global_store_dwordx4 v232, v[72:75], s[8:9] offset:2048
	global_store_dwordx4 v232, v[8:11], s[8:9]
	s_add_u32 s6, s13, 3
	s_cmp_ge_u32 s6, 0x2800
	s_cbranch_scc1 .Lgprep_sk0
	v_mul_f32_e32 v92, 0xbfb8aa3b, v76
	v_exp_f32_e32 v92, v92
	s_nop 0
	v_add_f32_e32 v92, 1.0, v92
	v_div_scale_f32 v93, s[24:25], v92, v92, 1.0
	v_rcp_f32_e32 v94, v93
	s_nop 0
	v_fma_f32 v95, -v93, v94, 1.0
	v_fmac_f32_e32 v94, v95, v94
	v_div_scale_f32 v95, vcc, 1.0, v92, 1.0
	v_mul_f32_e32 v96, v95, v94
	v_fma_f32 v97, -v93, v96, v95
	v_fmac_f32_e32 v96, v97, v94
	v_fma_f32 v93, -v93, v96, v95
	v_div_fmas_f32 v93, v93, v94, v96
	v_div_fixup_f32 v76, v93, v92, 1.0
	v_mul_f32_e32 v76, 0xbf1b4598, v76
	v_mul_f32_e32 v76, 0x3fb8aa3b, v76
	v_exp_f32_e32 v76, v76
	v_mul_f32_e32 v92, 0xbfb8aa3b, v80
	v_exp_f32_e32 v92, v92
	s_nop 0
	v_add_f32_e32 v92, 1.0, v92
	v_div_scale_f32 v93, s[24:25], v92, v92, 1.0
	v_rcp_f32_e32 v94, v93
	s_nop 0
	v_fma_f32 v95, -v93, v94, 1.0
	v_fmac_f32_e32 v94, v95, v94
	v_div_scale_f32 v95, vcc, 1.0, v92, 1.0
	v_mul_f32_e32 v96, v95, v94
	v_fma_f32 v97, -v93, v96, v95
	v_fmac_f32_e32 v96, v97, v94
	v_fma_f32 v93, -v93, v96, v95
	v_div_fmas_f32 v93, v93, v94, v96
	v_div_fixup_f32 v80, v93, v92, 1.0
	v_mul_f32_e32 v92, 0xbfb8aa3b, v77
	v_exp_f32_e32 v92, v92
	s_nop 0
	v_add_f32_e32 v92, 1.0, v92
	v_div_scale_f32 v93, s[24:25], v92, v92, 1.0
	v_rcp_f32_e32 v94, v93
	s_nop 0
	v_fma_f32 v95, -v93, v94, 1.0
	v_fmac_f32_e32 v94, v95, v94
	v_div_scale_f32 v95, vcc, 1.0, v92, 1.0
	v_mul_f32_e32 v96, v95, v94
	v_fma_f32 v97, -v93, v96, v95
	v_fmac_f32_e32 v96, v97, v94
	v_fma_f32 v93, -v93, v96, v95
	v_div_fmas_f32 v93, v93, v94, v96
	v_div_fixup_f32 v77, v93, v92, 1.0
	v_mul_f32_e32 v77, 0xbf1b4598, v77
	v_mul_f32_e32 v77, 0x3fb8aa3b, v77
	v_exp_f32_e32 v77, v77
	v_mul_f32_e32 v92, 0xbfb8aa3b, v81
	v_exp_f32_e32 v92, v92
	s_nop 0
	v_add_f32_e32 v92, 1.0, v92
	v_div_scale_f32 v93, s[24:25], v92, v92, 1.0
	v_rcp_f32_e32 v94, v93
	s_nop 0
	v_fma_f32 v95, -v93, v94, 1.0
	v_fmac_f32_e32 v94, v95, v94
	v_div_scale_f32 v95, vcc, 1.0, v92, 1.0
	v_mul_f32_e32 v96, v95, v94
	v_fma_f32 v97, -v93, v96, v95
	v_fmac_f32_e32 v96, v97, v94
	v_fma_f32 v93, -v93, v96, v95
	v_div_fmas_f32 v93, v93, v94, v96
	v_div_fixup_f32 v81, v93, v92, 1.0
	v_mul_f32_e32 v92, 0xbfb8aa3b, v78
	v_exp_f32_e32 v92, v92
	s_nop 0
	v_add_f32_e32 v92, 1.0, v92
	v_div_scale_f32 v93, s[24:25], v92, v92, 1.0
	v_rcp_f32_e32 v94, v93
	s_nop 0
	v_fma_f32 v95, -v93, v94, 1.0
	v_fmac_f32_e32 v94, v95, v94
	v_div_scale_f32 v95, vcc, 1.0, v92, 1.0
	v_mul_f32_e32 v96, v95, v94
	v_fma_f32 v97, -v93, v96, v95
	v_fmac_f32_e32 v96, v97, v94
	v_fma_f32 v93, -v93, v96, v95
	v_div_fmas_f32 v93, v93, v94, v96
	v_div_fixup_f32 v78, v93, v92, 1.0
	v_mul_f32_e32 v78, 0xbf1b4598, v78
	v_mul_f32_e32 v78, 0x3fb8aa3b, v78
	v_exp_f32_e32 v78, v78
	v_mul_f32_e32 v92, 0xbfb8aa3b, v82
	v_exp_f32_e32 v92, v92
	s_nop 0
	v_add_f32_e32 v92, 1.0, v92
	v_div_scale_f32 v93, s[24:25], v92, v92, 1.0
	v_rcp_f32_e32 v94, v93
	s_nop 0
	v_fma_f32 v95, -v93, v94, 1.0
	v_fmac_f32_e32 v94, v95, v94
	v_div_scale_f32 v95, vcc, 1.0, v92, 1.0
	v_mul_f32_e32 v96, v95, v94
	v_fma_f32 v97, -v93, v96, v95
	v_fmac_f32_e32 v96, v97, v94
	v_fma_f32 v93, -v93, v96, v95
	v_div_fmas_f32 v93, v93, v94, v96
	v_div_fixup_f32 v82, v93, v92, 1.0
	v_mul_f32_e32 v92, 0xbfb8aa3b, v79
	v_exp_f32_e32 v92, v92
	s_nop 0
	v_add_f32_e32 v92, 1.0, v92
	v_div_scale_f32 v93, s[24:25], v92, v92, 1.0
	v_rcp_f32_e32 v94, v93
	s_nop 0
	v_fma_f32 v95, -v93, v94, 1.0
	v_fmac_f32_e32 v94, v95, v94
	v_div_scale_f32 v95, vcc, 1.0, v92, 1.0
	v_mul_f32_e32 v96, v95, v94
	v_fma_f32 v97, -v93, v96, v95
	v_fmac_f32_e32 v96, v97, v94
	v_fma_f32 v93, -v93, v96, v95
	v_div_fmas_f32 v93, v93, v94, v96
	v_div_fixup_f32 v79, v93, v92, 1.0
	v_mul_f32_e32 v79, 0xbf1b4598, v79
	v_mul_f32_e32 v79, 0x3fb8aa3b, v79
	v_exp_f32_e32 v79, v79
	v_mul_f32_e32 v92, 0xbfb8aa3b, v83
	v_exp_f32_e32 v92, v92
	s_nop 0
	v_add_f32_e32 v92, 1.0, v92
	v_div_scale_f32 v93, s[24:25], v92, v92, 1.0
	v_rcp_f32_e32 v94, v93
	s_nop 0
	v_fma_f32 v95, -v93, v94, 1.0
	v_fmac_f32_e32 v94, v95, v94
	v_div_scale_f32 v95, vcc, 1.0, v92, 1.0
	v_mul_f32_e32 v96, v95, v94
	v_fma_f32 v97, -v93, v96, v95
	v_fmac_f32_e32 v96, v97, v94
	v_fma_f32 v93, -v93, v96, v95
	v_div_fmas_f32 v93, v93, v94, v96
	v_div_fixup_f32 v83, v93, v92, 1.0
	s_mul_i32 s7, s6, 0x1400
	s_add_u32 s8, s82, s7
	s_addc_u32 s9, s83, 0
	global_store_dwordx4 v232, v[76:79], s[8:9] offset:1024
	global_store_dwordx4 v232, v[80:83], s[8:9] offset:2048
	global_store_dwordx4 v232, v[12:15], s[8:9]
	s_add_u32 s6, s13, 4
	s_cmp_ge_u32 s6, 0x2800
	s_cbranch_scc1 .Lgprep_sk0
	v_mul_f32_e32 v92, 0xbfb8aa3b, v84
	v_exp_f32_e32 v92, v92
	s_nop 0
	v_add_f32_e32 v92, 1.0, v92
	v_div_scale_f32 v93, s[24:25], v92, v92, 1.0
	v_rcp_f32_e32 v94, v93
	s_nop 0
	v_fma_f32 v95, -v93, v94, 1.0
	v_fmac_f32_e32 v94, v95, v94
	v_div_scale_f32 v95, vcc, 1.0, v92, 1.0
	v_mul_f32_e32 v96, v95, v94
	v_fma_f32 v97, -v93, v96, v95
	v_fmac_f32_e32 v96, v97, v94
	v_fma_f32 v93, -v93, v96, v95
	v_div_fmas_f32 v93, v93, v94, v96
	v_div_fixup_f32 v84, v93, v92, 1.0
	v_mul_f32_e32 v84, 0xbf1b4598, v84
	v_mul_f32_e32 v84, 0x3fb8aa3b, v84
	v_exp_f32_e32 v84, v84
	v_mul_f32_e32 v92, 0xbfb8aa3b, v88
	v_exp_f32_e32 v92, v92
	s_nop 0
	v_add_f32_e32 v92, 1.0, v92
	v_div_scale_f32 v93, s[24:25], v92, v92, 1.0
	v_rcp_f32_e32 v94, v93
	s_nop 0
	v_fma_f32 v95, -v93, v94, 1.0
	v_fmac_f32_e32 v94, v95, v94
	v_div_scale_f32 v95, vcc, 1.0, v92, 1.0
	v_mul_f32_e32 v96, v95, v94
	v_fma_f32 v97, -v93, v96, v95
	v_fmac_f32_e32 v96, v97, v94
	v_fma_f32 v93, -v93, v96, v95
	v_div_fmas_f32 v93, v93, v94, v96
	v_div_fixup_f32 v88, v93, v92, 1.0
	v_mul_f32_e32 v92, 0xbfb8aa3b, v85
	v_exp_f32_e32 v92, v92
	s_nop 0
	v_add_f32_e32 v92, 1.0, v92
	v_div_scale_f32 v93, s[24:25], v92, v92, 1.0
	v_rcp_f32_e32 v94, v93
	s_nop 0
	v_fma_f32 v95, -v93, v94, 1.0
	v_fmac_f32_e32 v94, v95, v94
	v_div_scale_f32 v95, vcc, 1.0, v92, 1.0
	v_mul_f32_e32 v96, v95, v94
	v_fma_f32 v97, -v93, v96, v95
	v_fmac_f32_e32 v96, v97, v94
	v_fma_f32 v93, -v93, v96, v95
	v_div_fmas_f32 v93, v93, v94, v96
	v_div_fixup_f32 v85, v93, v92, 1.0
	v_mul_f32_e32 v85, 0xbf1b4598, v85
	v_mul_f32_e32 v85, 0x3fb8aa3b, v85
	v_exp_f32_e32 v85, v85
	v_mul_f32_e32 v92, 0xbfb8aa3b, v89
	v_exp_f32_e32 v92, v92
	s_nop 0
	v_add_f32_e32 v92, 1.0, v92
	v_div_scale_f32 v93, s[24:25], v92, v92, 1.0
	v_rcp_f32_e32 v94, v93
	s_nop 0
	v_fma_f32 v95, -v93, v94, 1.0
	v_fmac_f32_e32 v94, v95, v94
	v_div_scale_f32 v95, vcc, 1.0, v92, 1.0
	v_mul_f32_e32 v96, v95, v94
	v_fma_f32 v97, -v93, v96, v95
	v_fmac_f32_e32 v96, v97, v94
	v_fma_f32 v93, -v93, v96, v95
	v_div_fmas_f32 v93, v93, v94, v96
	v_div_fixup_f32 v89, v93, v92, 1.0
	v_mul_f32_e32 v92, 0xbfb8aa3b, v86
	v_exp_f32_e32 v92, v92
	s_nop 0
	v_add_f32_e32 v92, 1.0, v92
	v_div_scale_f32 v93, s[24:25], v92, v92, 1.0
	v_rcp_f32_e32 v94, v93
	s_nop 0
	v_fma_f32 v95, -v93, v94, 1.0
	v_fmac_f32_e32 v94, v95, v94
	v_div_scale_f32 v95, vcc, 1.0, v92, 1.0
	v_mul_f32_e32 v96, v95, v94
	v_fma_f32 v97, -v93, v96, v95
	v_fmac_f32_e32 v96, v97, v94
	v_fma_f32 v93, -v93, v96, v95
	v_div_fmas_f32 v93, v93, v94, v96
	v_div_fixup_f32 v86, v93, v92, 1.0
	v_mul_f32_e32 v86, 0xbf1b4598, v86
	v_mul_f32_e32 v86, 0x3fb8aa3b, v86
	v_exp_f32_e32 v86, v86
	v_mul_f32_e32 v92, 0xbfb8aa3b, v90
	v_exp_f32_e32 v92, v92
	s_nop 0
	v_add_f32_e32 v92, 1.0, v92
	v_div_scale_f32 v93, s[24:25], v92, v92, 1.0
	v_rcp_f32_e32 v94, v93
	s_nop 0
	v_fma_f32 v95, -v93, v94, 1.0
	v_fmac_f32_e32 v94, v95, v94
	v_div_scale_f32 v95, vcc, 1.0, v92, 1.0
	v_mul_f32_e32 v96, v95, v94
	v_fma_f32 v97, -v93, v96, v95
	v_fmac_f32_e32 v96, v97, v94
	v_fma_f32 v93, -v93, v96, v95
	v_div_fmas_f32 v93, v93, v94, v96
	v_div_fixup_f32 v90, v93, v92, 1.0
	v_mul_f32_e32 v92, 0xbfb8aa3b, v87
	v_exp_f32_e32 v92, v92
	s_nop 0
	v_add_f32_e32 v92, 1.0, v92
	v_div_scale_f32 v93, s[24:25], v92, v92, 1.0
	v_rcp_f32_e32 v94, v93
	s_nop 0
	v_fma_f32 v95, -v93, v94, 1.0
	v_fmac_f32_e32 v94, v95, v94
	v_div_scale_f32 v95, vcc, 1.0, v92, 1.0
	v_mul_f32_e32 v96, v95, v94
	v_fma_f32 v97, -v93, v96, v95
	v_fmac_f32_e32 v96, v97, v94
	v_fma_f32 v93, -v93, v96, v95
	v_div_fmas_f32 v93, v93, v94, v96
	v_div_fixup_f32 v87, v93, v92, 1.0
	v_mul_f32_e32 v87, 0xbf1b4598, v87
	v_mul_f32_e32 v87, 0x3fb8aa3b, v87
	v_exp_f32_e32 v87, v87
	v_mul_f32_e32 v92, 0xbfb8aa3b, v91
	v_exp_f32_e32 v92, v92
	s_nop 0
	v_add_f32_e32 v92, 1.0, v92
	v_div_scale_f32 v93, s[24:25], v92, v92, 1.0
	v_rcp_f32_e32 v94, v93
	s_nop 0
	v_fma_f32 v95, -v93, v94, 1.0
	v_fmac_f32_e32 v94, v95, v94
	v_div_scale_f32 v95, vcc, 1.0, v92, 1.0
	v_mul_f32_e32 v96, v95, v94
	v_fma_f32 v97, -v93, v96, v95
	v_fmac_f32_e32 v96, v97, v94
	v_fma_f32 v93, -v93, v96, v95
	v_div_fmas_f32 v93, v93, v94, v96
	v_div_fixup_f32 v91, v93, v92, 1.0
	s_mul_i32 s7, s6, 0x1400
	s_add_u32 s8, s82, s7
	s_addc_u32 s9, s83, 0
	global_store_dwordx4 v232, v[84:87], s[8:9] offset:1024
	global_store_dwordx4 v232, v[88:91], s[8:9] offset:2048
	global_store_dwordx4 v232, v[16:19], s[8:9]
	s_branch .Lgprep_e0

.LBB0_807:
	s_or_b64 exec, exec, s[2:3]
	v_readlane_b32 s2, v162, 36
	v_readlane_b32 s20, v162, 12
	s_add_i32 s35, s2, 9
	v_readlane_b32 s21, v162, 13
	s_cmp_ge_i32 s35, s21
	v_readlane_b32 s22, v162, 14
	v_readlane_b32 s23, v162, 15
	s_cbranch_scc1 .LBB0_857
	s_waitcnt vmcnt(0)
	v_readlane_b32 s4, v163, 17
	v_readlane_b32 s5, v163, 18
	s_barrier
	v_readlane_b32 s21, v162, 62
	s_nop 1
	s_cmp_eq_u32 s21, 1
	s_cbranch_scc1 .Lxb6_noinv
	v_lshrrev_b32_e32 v0, 6, v128
	v_readfirstlane_b32 s20, v0
	s_cmp_lg_u32 s20, 1
	s_cbranch_scc1 .Lxb6_ninv
	buffer_inv sc1

.LBB0_877:
	v_readlane_b32 s2, v162, 36
	v_readlane_b32 s20, v162, 12
	s_add_i32 s35, s2, 10
	v_readlane_b32 s21, v162, 13
	s_cmp_ge_i32 s35, s21
	v_readlane_b32 s22, v162, 14
	v_readlane_b32 s23, v162, 15
	s_cbranch_scc1 .LBB0_927
	s_waitcnt vmcnt(0)
	v_readlane_b32 s4, v163, 17
	v_readlane_b32 s5, v163, 18
	s_barrier
	v_readlane_b32 s21, v162, 62
	s_nop 1
	s_cmp_eq_u32 s21, 1
	s_cbranch_scc1 .Lxb7_noinv
	v_lshrrev_b32_e32 v0, 6, v128
	v_readfirstlane_b32 s20, v0
	s_cmp_lg_u32 s20, 1
	s_cbranch_scc1 .Lxb7_ninv
	buffer_inv sc1

.LBB0_933:
	s_or_b64 exec, exec, s[2:3]
	v_readlane_b32 s2, v162, 36
	v_readlane_b32 s20, v162, 12
	s_add_i32 s35, s2, 11
	v_readlane_b32 s21, v162, 13
	s_cmp_ge_i32 s35, s21
	v_readlane_b32 s22, v162, 14
	v_readlane_b32 s23, v162, 15
	s_cbranch_scc1 .LBB0_983
	s_waitcnt vmcnt(0)
	v_readlane_b32 s4, v163, 17
	v_readlane_b32 s5, v163, 18
	s_barrier
	v_readlane_b32 s21, v162, 62
	s_nop 1
	s_cmp_eq_u32 s21, 1
	s_cbranch_scc1 .Lxb8_noinv
	v_lshrrev_b32_e32 v0, 6, v128
	v_readfirstlane_b32 s20, v0
	s_cmp_lg_u32 s20, 1
	s_cbranch_scc1 .Lxb8_ninv
	buffer_inv sc1

.LBB0_991:
	v_readlane_b32 s2, v162, 36
	v_readlane_b32 s20, v162, 12
	s_add_i32 s35, s2, 12
	v_readlane_b32 s21, v162, 13
	s_cmp_ge_i32 s35, s21
	v_readlane_b32 s22, v162, 14
	v_readlane_b32 s23, v162, 15
	s_cbranch_scc1 .LBB0_1041
	s_waitcnt vmcnt(0)
	v_readlane_b32 s4, v163, 17
	v_readlane_b32 s5, v163, 18
	s_barrier
	v_readlane_b32 s21, v162, 62
	s_nop 1
	s_cmp_eq_u32 s21, 1
	s_cbranch_scc1 .Lxb9_noinv
	v_lshrrev_b32_e32 v0, 6, v128
	v_readfirstlane_b32 s20, v0
	s_cmp_lg_u32 s20, 1
	s_cbranch_scc1 .Lxb9_ninv
	buffer_inv sc1

.LBB0_1061:
	v_readlane_b32 s2, v162, 36
	v_readlane_b32 s20, v162, 12
	s_add_i32 s35, s2, 13
	v_readlane_b32 s21, v162, 13
	s_cmp_ge_i32 s35, s21
	v_readlane_b32 s22, v162, 14
	v_readlane_b32 s23, v162, 15
	s_cbranch_scc1 .LBB0_1111
	s_waitcnt vmcnt(0)
	v_readlane_b32 s4, v163, 17
	v_readlane_b32 s5, v163, 18
	s_barrier
	v_readlane_b32 s21, v162, 62
	s_nop 1
	s_cmp_eq_u32 s21, 1
	s_cbranch_scc1 .Lxb10_noinv
	v_lshrrev_b32_e32 v0, 6, v128
	v_readfirstlane_b32 s20, v0
	s_cmp_lg_u32 s20, 1
	s_cbranch_scc1 .Lxb10_ninv
	buffer_inv sc1

.Lgro11_batch:
	s_mov_b32 s20, s13
	s_min_u32 s21, s20, 0x27ff
	s_lshl_b32 s21, s21, 11
	s_add_u32 s22, s86, s21
	s_addc_u32 s23, s87, 0
	global_load_dwordx4 v[168:171], v82, s[22:23] sc1
	global_load_dwordx4 v[172:175], v82, s[22:23] offset:1024 sc1
	s_add_u32 s22, s78, s21
	s_addc_u32 s23, s79, 0
	global_load_dwordx4 v[176:179], v82, s[22:23] sc1
	global_load_dwordx4 v[180:183], v82, s[22:23] offset:1024 sc1
	s_add_u32 s20, s20, s14
	s_min_u32 s21, s20, 0x27ff
	s_lshl_b32 s21, s21, 11
	s_add_u32 s22, s86, s21
	s_addc_u32 s23, s87, 0
	global_load_dwordx4 v[184:187], v82, s[22:23] sc1
	global_load_dwordx4 v[188:191], v82, s[22:23] offset:1024 sc1
	s_add_u32 s22, s78, s21
	s_addc_u32 s23, s79, 0
	global_load_dwordx4 v[192:195], v82, s[22:23] sc1
	global_load_dwordx4 v[196:199], v82, s[22:23] offset:1024 sc1
	s_add_u32 s20, s20, s14
	s_min_u32 s21, s20, 0x27ff
	s_lshl_b32 s21, s21, 11
	s_add_u32 s22, s86, s21
	s_addc_u32 s23, s87, 0
	global_load_dwordx4 v[200:203], v82, s[22:23] sc1
	global_load_dwordx4 v[204:207], v82, s[22:23] offset:1024 sc1
	s_add_u32 s22, s78, s21
	s_addc_u32 s23, s79, 0
	global_load_dwordx4 v[208:211], v82, s[22:23] sc1
	global_load_dwordx4 v[212:215], v82, s[22:23] offset:1024 sc1
	s_add_u32 s20, s20, s14
	s_min_u32 s21, s20, 0x27ff
	s_lshl_b32 s21, s21, 11
	s_add_u32 s22, s86, s21
	s_addc_u32 s23, s87, 0
	global_load_dwordx4 v[216:219], v82, s[22:23] sc1
	global_load_dwordx4 v[220:223], v82, s[22:23] offset:1024 sc1
	s_add_u32 s22, s78, s21
	s_addc_u32 s23, s79, 0
	global_load_dwordx4 v[224:227], v82, s[22:23] sc1
	global_load_dwordx4 v[228:231], v82, s[22:23] offset:1024 sc1
	s_add_u32 s20, s20, s14
	s_min_u32 s21, s20, 0x27ff
	s_lshl_b32 s21, s21, 11
	s_add_u32 s22, s86, s21
	s_addc_u32 s23, s87, 0
	global_load_dwordx4 v[232:235], v82, s[22:23] sc1
	global_load_dwordx4 v[236:239], v82, s[22:23] offset:1024 sc1
	s_add_u32 s22, s78, s21
	s_addc_u32 s23, s79, 0
	global_load_dwordx4 v[240:243], v82, s[22:23] sc1
	global_load_dwordx4 v[244:247], v82, s[22:23] offset:1024 sc1
	s_mov_b32 s15, -1
	s_mov_b32 s20, s13
	s_cmp_ge_u32 s20, 0x2800
	s_cbranch_scc1 .Lgro11_bend
	s_sub_u32 s4, s20, 0x2000
	s_lshr_b32 s4, s4, 10
	s_add_u32 s4, s4, 1
	s_cmp_lt_u32 s20, 0x2000
	s_cselect_b32 s4, 0, s4
	s_cmp_eq_u32 s4, s15
	s_cbranch_scc1 .Lgro11_r0_same
	s_mov_b32 s15, s4
	s_mul_i32 s4, s4, 0x9000
	s_add_u32 s32, s4, s6
	s_add_u32 s22, s16, s32
	s_addc_u32 s23, s17, 0
	global_load_dwordx4 v[0:3], v83, s[22:23]
	global_load_dwordx4 v[4:7], v83, s[22:23] offset:16
	global_load_dwordx4 v[8:11], v83, s[22:23] offset:2048
	global_load_dwordx4 v[12:15], v83, s[22:23] offset:2064
	s_cmp_lg_u32 s34, 0
	s_cbranch_scc1 .Lgro11_r0_novec
	s_add_u32 s32, s4, s7
	s_add_u32 s22, s16, s32
	s_addc_u32 s23, s17, 0
	global_load_dwordx4 v[16:19], v83, s[22:23]
	global_load_dwordx4 v[20:23], v83, s[22:23] offset:16
	global_load_dwordx4 v[24:27], v83, s[22:23] offset:2048
	global_load_dwordx4 v[28:31], v83, s[22:23] offset:2064
	s_add_u32 s22, s22, 0x1000
	s_addc_u32 s23, s23, 0
	global_load_dwordx4 v[32:35], v83, s[22:23]
	global_load_dwordx4 v[36:39], v83, s[22:23] offset:16
	global_load_dwordx4 v[40:43], v83, s[22:23] offset:2048
	global_load_dwordx4 v[44:47], v83, s[22:23] offset:2064

.LBB0_1122:
	s_waitcnt vmcnt(0)
	v_readlane_b32 s4, v163, 17
	v_readlane_b32 s5, v163, 18
	s_barrier
	v_readlane_b32 s21, v162, 62
	s_nop 1
	s_cmp_eq_u32 s21, 1
	s_cbranch_scc1 .Lxb11_noinv
	v_lshrrev_b32_e32 v0, 6, v128
	v_readfirstlane_b32 s20, v0
	s_cmp_lg_u32 s20, 1
	s_cbranch_scc1 .Lxb11_ninv
	buffer_inv sc1

.Lxb11_noinv:
	s_and_saveexec_b64 s[2:3], s[4:5]
	s_cbranch_execnz .LBB0_1123
